# K-loop MMA blocks: the two K-steps of each accumulator issued back-to-back (accumulate chain with D-to-C forwarding) instead of eight MFMAs apart
# speedup vs baseline: 1.0092x; 1.0092x over previous
.LBB0_322:
	s_ashr_i32 s43, s42, 31
	s_lshl_b64 s[46:47], s[42:43], 19
	s_add_u32 s46, s12, s46
	s_addc_u32 s47, s13, s47
	s_and_b64 s[48:49], s[4:5], exec
	s_cselect_b32 s18, s47, s7
	s_cselect_b32 s43, s46, s6
	s_ashr_i32 s45, s44, 31
	s_lshl_b64 s[48:49], s[44:45], 19
	s_add_u32 s48, s59, s48
	s_addc_u32 s49, s60, s49
	s_and_b64 s[50:51], s[4:5], exec
	s_cselect_b32 s45, s49, s9
	s_cselect_b32 s55, s48, s8
	s_add_u32 s6, s6, 0x40080
	s_addc_u32 s7, s7, 0
	s_add_u32 s56, s8, 0x100
	s_addc_u32 s57, s9, 0
	s_mov_b32 s78, -2
	ds_read_b128 v[96:99], v209
	ds_read_b128 v[100:103], v209 offset:1024
	ds_read_b128 v[120:123], v209 offset:2048
	ds_read_b128 v[124:127], v209 offset:3072
	ds_read_b128 v[144:147], v210
	ds_read_b128 v[148:151], v210 offset:1024
	ds_read_b128 v[152:155], v210 offset:2048
	ds_read_b128 v[156:159], v210 offset:3072
	s_add_u32 s8, s6, 0xfffc0080
	s_addc_u32 s9, s7, -1
	s_cmp_eq_u32 s78, 12
	s_cselect_b32 s51, s18, s9
	s_cselect_b32 s50, s43, s8
	s_cselect_b32 s9, s45, s57
	s_cselect_b32 s8, s55, s56
	v_lshl_add_u64 v[206:207], s[6:7], 0, v[170:171]
	s_add_i32 m0, s17, 0xc000
	ds_read_b128 v[178:181], v211
	ds_read_b128 v[182:185], v211 offset:1024
	ds_read_b128 v[186:189], v211 offset:2048
	ds_read_b128 v[190:193], v211 offset:3072
	ds_read_b128 v[194:197], v211 offset:4096
	ds_read_b128 v[198:201], v211 offset:5120
	ds_read_b128 v[202:205], v211 offset:6144
	ds_read_b128 v[218:221], v211 offset:7168
	global_load_lds_dwordx4 v[206:207], off
	s_add_i32 m0, s17, 0xe000
	v_lshl_add_u64 v[206:207], s[6:7], 0, v[172:173]
	global_load_lds_dwordx4 v[206:207], off
	s_waitcnt vmcnt(8) lgkmcnt(0)
	s_barrier
	s_setprio 1
	v_mfma_f32_16x16x32_bf16 v[140:143], v[96:99], v[178:181], 0
	v_mfma_f32_16x16x32_bf16 v[140:143], v[100:103], v[182:185], v[140:143]
	v_mfma_f32_16x16x32_bf16 v[136:139], v[120:123], v[178:181], 0
	v_mfma_f32_16x16x32_bf16 v[136:139], v[124:127], v[182:185], v[136:139]
	v_mfma_f32_16x16x32_bf16 v[116:119], v[96:99], v[186:189], 0
	v_mfma_f32_16x16x32_bf16 v[116:119], v[100:103], v[190:193], v[116:119]
	v_mfma_f32_16x16x32_bf16 v[112:115], v[120:123], v[186:189], 0
	v_mfma_f32_16x16x32_bf16 v[112:115], v[124:127], v[190:193], v[112:115]
	v_mfma_f32_16x16x32_bf16 v[92:95], v[96:99], v[194:197], 0
	v_mfma_f32_16x16x32_bf16 v[92:95], v[100:103], v[198:201], v[92:95]
	v_mfma_f32_16x16x32_bf16 v[88:91], v[120:123], v[194:197], 0
	v_mfma_f32_16x16x32_bf16 v[88:91], v[124:127], v[198:201], v[88:91]
	v_mfma_f32_16x16x32_bf16 v[76:79], v[96:99], v[202:205], 0
	v_mfma_f32_16x16x32_bf16 v[76:79], v[100:103], v[218:221], v[76:79]
	v_mfma_f32_16x16x32_bf16 v[72:75], v[120:123], v[202:205], 0
	v_mfma_f32_16x16x32_bf16 v[72:75], v[124:127], v[218:221], v[72:75]
	v_mfma_f32_16x16x32_bf16 v[132:135], v[144:147], v[178:181], 0
	v_mfma_f32_16x16x32_bf16 v[132:135], v[148:151], v[182:185], v[132:135]
	v_mfma_f32_16x16x32_bf16 v[128:131], v[152:155], v[178:181], 0
	v_mfma_f32_16x16x32_bf16 v[128:131], v[156:159], v[182:185], v[128:131]
	v_mfma_f32_16x16x32_bf16 v[108:111], v[144:147], v[186:189], 0
	v_mfma_f32_16x16x32_bf16 v[108:111], v[148:151], v[190:193], v[108:111]
	v_mfma_f32_16x16x32_bf16 v[104:107], v[152:155], v[186:189], 0
	v_mfma_f32_16x16x32_bf16 v[104:107], v[156:159], v[190:193], v[104:107]
	v_mfma_f32_16x16x32_bf16 v[84:87], v[144:147], v[194:197], 0
	v_mfma_f32_16x16x32_bf16 v[84:87], v[148:151], v[198:201], v[84:87]
	v_mfma_f32_16x16x32_bf16 v[80:83], v[152:155], v[194:197], 0
	v_mfma_f32_16x16x32_bf16 v[80:83], v[156:159], v[198:201], v[80:83]
	s_setprio 2
	s_barrier
	v_mfma_f32_16x16x32_bf16 v[68:71], v[144:147], v[202:205], 0
	v_mfma_f32_16x16x32_bf16 v[68:71], v[148:151], v[218:221], v[68:71]
	v_mfma_f32_16x16x32_bf16 v[64:67], v[152:155], v[202:205], 0
	v_mfma_f32_16x16x32_bf16 v[64:67], v[156:159], v[218:221], v[64:67]
	s_setprio 2
	s_add_i32 s79, s73, s61
	v_lshl_add_u64 v[206:207], s[8:9], 0, v[162:163]
	s_mov_b32 m0, s79
	ds_read_b128 v[178:181], v211 offset:16384
	ds_read_b128 v[182:185], v211 offset:17408
	ds_read_b128 v[186:189], v211 offset:18432
	ds_read_b128 v[190:193], v211 offset:19456
	ds_read_b128 v[194:197], v211 offset:20480
	ds_read_b128 v[198:201], v211 offset:21504
	ds_read_b128 v[202:205], v211 offset:22528
	ds_read_b128 v[218:221], v211 offset:23552
	global_load_lds_dwordx4 v[206:207], off
	s_add_i32 m0, s79, 0x2000
	s_add_u32 s80, s8, 0x40000
	v_lshl_add_u64 v[222:223], s[8:9], 0, v[166:167]
	s_addc_u32 s81, s9, 0
	s_add_i32 s79, s74, s61
	global_load_lds_dwordx4 v[222:223], off
	v_lshl_add_u64 v[224:225], s[80:81], 0, v[162:163]
	s_mov_b32 m0, s79
	v_lshl_add_u64 v[226:227], s[50:51], 0, v[164:165]
	global_load_lds_dwordx4 v[224:225], off
	s_add_i32 m0, s79, 0x2000
	v_lshl_add_u64 v[224:225], s[80:81], 0, v[166:167]
	global_load_lds_dwordx4 v[224:225], off
	s_mov_b32 m0, s17
	v_lshl_add_u64 v[224:225], s[50:51], 0, v[160:161]
	global_load_lds_dwordx4 v[224:225], off
	s_mov_b32 m0, s62
	s_nop 0
	global_load_lds_dwordx4 v[226:227], off
	s_waitcnt vmcnt(8) lgkmcnt(0)
	s_barrier
	s_setprio 1
	v_mfma_f32_16x16x32_bf16 v[60:63], v[96:99], v[178:181], 0
	v_mfma_f32_16x16x32_bf16 v[60:63], v[100:103], v[182:185], v[60:63]
	v_mfma_f32_16x16x32_bf16 v[56:59], v[120:123], v[178:181], 0
	v_mfma_f32_16x16x32_bf16 v[56:59], v[124:127], v[182:185], v[56:59]
	v_mfma_f32_16x16x32_bf16 v[44:47], v[96:99], v[186:189], 0
	v_mfma_f32_16x16x32_bf16 v[44:47], v[100:103], v[190:193], v[44:47]
	v_mfma_f32_16x16x32_bf16 v[40:43], v[120:123], v[186:189], 0
	v_mfma_f32_16x16x32_bf16 v[40:43], v[124:127], v[190:193], v[40:43]
	v_mfma_f32_16x16x32_bf16 v[28:31], v[96:99], v[194:197], 0
	v_mfma_f32_16x16x32_bf16 v[28:31], v[100:103], v[198:201], v[28:31]
	v_mfma_f32_16x16x32_bf16 v[24:27], v[120:123], v[194:197], 0
	v_mfma_f32_16x16x32_bf16 v[24:27], v[124:127], v[198:201], v[24:27]
	v_mfma_f32_16x16x32_bf16 v[12:15], v[96:99], v[202:205], 0
	v_mfma_f32_16x16x32_bf16 v[12:15], v[100:103], v[218:221], v[12:15]
	v_mfma_f32_16x16x32_bf16 v[8:11], v[120:123], v[202:205], 0
	v_mfma_f32_16x16x32_bf16 v[8:11], v[124:127], v[218:221], v[8:11]
	v_mfma_f32_16x16x32_bf16 v[52:55], v[144:147], v[178:181], 0
	v_mfma_f32_16x16x32_bf16 v[52:55], v[148:151], v[182:185], v[52:55]
	v_mfma_f32_16x16x32_bf16 v[48:51], v[152:155], v[178:181], 0
	v_mfma_f32_16x16x32_bf16 v[48:51], v[156:159], v[182:185], v[48:51]
	v_mfma_f32_16x16x32_bf16 v[36:39], v[144:147], v[186:189], 0
	v_mfma_f32_16x16x32_bf16 v[36:39], v[148:151], v[190:193], v[36:39]
	v_mfma_f32_16x16x32_bf16 v[32:35], v[152:155], v[186:189], 0
	v_mfma_f32_16x16x32_bf16 v[32:35], v[156:159], v[190:193], v[32:35]
	v_mfma_f32_16x16x32_bf16 v[20:23], v[144:147], v[194:197], 0
	v_mfma_f32_16x16x32_bf16 v[20:23], v[148:151], v[198:201], v[20:23]
	v_mfma_f32_16x16x32_bf16 v[16:19], v[152:155], v[194:197], 0
	v_mfma_f32_16x16x32_bf16 v[16:19], v[156:159], v[198:201], v[16:19]
	s_setprio 2
	s_barrier
	v_mfma_f32_16x16x32_bf16 v[4:7], v[144:147], v[202:205], 0
	v_mfma_f32_16x16x32_bf16 v[4:7], v[148:151], v[218:221], v[4:7]
	v_mfma_f32_16x16x32_bf16 v[0:3], v[152:155], v[202:205], 0
	v_mfma_f32_16x16x32_bf16 v[0:3], v[156:159], v[218:221], v[0:3]
	s_setprio 0
	s_add_i32 s79, 0, 0x18000
	s_add_i32 s80, 0, 0x1c000
	v_add_u32_e32 v124, s79, v208
	v_add_u32_e32 v156, s80, v208
	ds_read_b128 v[96:99], v124
	ds_read_b128 v[100:103], v124 offset:1024
	ds_read_b128 v[120:123], v124 offset:2048
	ds_read_b128 v[124:127], v124 offset:3072
	ds_read_b128 v[144:147], v156
	ds_read_b128 v[148:151], v156 offset:1024
	ds_read_b128 v[152:155], v156 offset:2048
	ds_read_b128 v[156:159], v156 offset:3072
	s_add_u32 s50, s50, 0x40000
	s_addc_u32 s51, s51, 0
	s_mov_b32 m0, s63
	v_lshl_add_u64 v[228:229], s[50:51], 0, v[160:161]
	ds_read_b128 v[178:181], v211 offset:32768
	ds_read_b128 v[182:185], v211 offset:33792
	ds_read_b128 v[186:189], v211 offset:34816
	ds_read_b128 v[190:193], v211 offset:35840
	ds_read_b128 v[194:197], v211 offset:36864
	ds_read_b128 v[198:201], v211 offset:37888
	ds_read_b128 v[202:205], v211 offset:38912
	ds_read_b128 v[218:221], v211 offset:39936
	global_load_lds_dwordx4 v[228:229], off
	s_mov_b32 m0, s64
	v_lshl_add_u64 v[228:229], s[50:51], 0, v[164:165]
	global_load_lds_dwordx4 v[228:229], off
	s_waitcnt vmcnt(8) lgkmcnt(0)
	s_barrier
	s_setprio 1
	v_mfma_f32_16x16x32_bf16 v[140:143], v[96:99], v[178:181], v[140:143]
	v_mfma_f32_16x16x32_bf16 v[140:143], v[100:103], v[182:185], v[140:143]
	v_mfma_f32_16x16x32_bf16 v[136:139], v[120:123], v[178:181], v[136:139]
	v_mfma_f32_16x16x32_bf16 v[136:139], v[124:127], v[182:185], v[136:139]
	v_mfma_f32_16x16x32_bf16 v[116:119], v[96:99], v[186:189], v[116:119]
	v_mfma_f32_16x16x32_bf16 v[116:119], v[100:103], v[190:193], v[116:119]
	v_mfma_f32_16x16x32_bf16 v[112:115], v[120:123], v[186:189], v[112:115]
	v_mfma_f32_16x16x32_bf16 v[112:115], v[124:127], v[190:193], v[112:115]
	v_mfma_f32_16x16x32_bf16 v[92:95], v[96:99], v[194:197], v[92:95]
	v_mfma_f32_16x16x32_bf16 v[92:95], v[100:103], v[198:201], v[92:95]
	v_mfma_f32_16x16x32_bf16 v[88:91], v[120:123], v[194:197], v[88:91]
	v_mfma_f32_16x16x32_bf16 v[88:91], v[124:127], v[198:201], v[88:91]
	v_mfma_f32_16x16x32_bf16 v[76:79], v[96:99], v[202:205], v[76:79]
	v_mfma_f32_16x16x32_bf16 v[76:79], v[100:103], v[218:221], v[76:79]
	v_mfma_f32_16x16x32_bf16 v[72:75], v[120:123], v[202:205], v[72:75]
	v_mfma_f32_16x16x32_bf16 v[72:75], v[124:127], v[218:221], v[72:75]
	v_mfma_f32_16x16x32_bf16 v[132:135], v[144:147], v[178:181], v[132:135]
	v_mfma_f32_16x16x32_bf16 v[132:135], v[148:151], v[182:185], v[132:135]
	v_mfma_f32_16x16x32_bf16 v[128:131], v[152:155], v[178:181], v[128:131]
	v_mfma_f32_16x16x32_bf16 v[128:131], v[156:159], v[182:185], v[128:131]
	v_mfma_f32_16x16x32_bf16 v[108:111], v[144:147], v[186:189], v[108:111]
	v_mfma_f32_16x16x32_bf16 v[108:111], v[148:151], v[190:193], v[108:111]
	v_mfma_f32_16x16x32_bf16 v[104:107], v[152:155], v[186:189], v[104:107]
	v_mfma_f32_16x16x32_bf16 v[104:107], v[156:159], v[190:193], v[104:107]
	v_mfma_f32_16x16x32_bf16 v[84:87], v[144:147], v[194:197], v[84:87]
	v_mfma_f32_16x16x32_bf16 v[84:87], v[148:151], v[198:201], v[84:87]
	v_mfma_f32_16x16x32_bf16 v[80:83], v[152:155], v[194:197], v[80:83]
	v_mfma_f32_16x16x32_bf16 v[80:83], v[156:159], v[198:201], v[80:83]
	s_setprio 2
	s_barrier
	v_mfma_f32_16x16x32_bf16 v[68:71], v[144:147], v[202:205], v[68:71]
	v_mfma_f32_16x16x32_bf16 v[68:71], v[148:151], v[218:221], v[68:71]
	v_mfma_f32_16x16x32_bf16 v[64:67], v[152:155], v[202:205], v[64:67]
	v_mfma_f32_16x16x32_bf16 v[64:67], v[156:159], v[218:221], v[64:67]
	s_setprio 2
	s_add_i32 s50, s79, s61
	v_lshl_add_u64 v[206:207], v[206:207], 0, s[36:37]
	s_mov_b32 m0, s50
	ds_read_b128 v[178:181], v211 offset:49152
	ds_read_b128 v[182:185], v211 offset:50176
	ds_read_b128 v[186:189], v211 offset:51200
	ds_read_b128 v[190:193], v211 offset:52224
	ds_read_b128 v[194:197], v211 offset:53248
	ds_read_b128 v[198:201], v211 offset:54272
	ds_read_b128 v[202:205], v211 offset:55296
	ds_read_b128 v[218:221], v211 offset:56320
	global_load_lds_dwordx4 v[206:207], off
	s_add_i32 m0, s50, 0x2000
	s_add_u32 s8, s8, 0x40080
	v_lshl_add_u64 v[206:207], v[222:223], 0, s[36:37]
	s_addc_u32 s9, s9, 0
	s_add_i32 s50, s80, s61
	global_load_lds_dwordx4 v[206:207], off
	s_mov_b32 m0, s50
	v_lshl_add_u64 v[206:207], s[8:9], 0, v[162:163]
	global_load_lds_dwordx4 v[206:207], off
	s_add_i32 m0, s50, 0x2000
	v_lshl_add_u64 v[206:207], s[8:9], 0, v[166:167]
	global_load_lds_dwordx4 v[206:207], off
	s_mov_b32 m0, s68
	v_lshl_add_u64 v[206:207], v[224:225], 0, s[36:37]
	global_load_lds_dwordx4 v[206:207], off
	s_mov_b32 m0, s69
	v_lshl_add_u64 v[206:207], v[226:227], 0, s[36:37]
	global_load_lds_dwordx4 v[206:207], off
	s_waitcnt vmcnt(8) lgkmcnt(0)
	s_barrier
	s_setprio 1
	v_mfma_f32_16x16x32_bf16 v[60:63], v[96:99], v[178:181], v[60:63]
	v_mfma_f32_16x16x32_bf16 v[60:63], v[100:103], v[182:185], v[60:63]
	v_mfma_f32_16x16x32_bf16 v[56:59], v[120:123], v[178:181], v[56:59]
	v_mfma_f32_16x16x32_bf16 v[56:59], v[124:127], v[182:185], v[56:59]
	v_mfma_f32_16x16x32_bf16 v[44:47], v[96:99], v[186:189], v[44:47]
	v_mfma_f32_16x16x32_bf16 v[44:47], v[100:103], v[190:193], v[44:47]
	v_mfma_f32_16x16x32_bf16 v[40:43], v[120:123], v[186:189], v[40:43]
	v_mfma_f32_16x16x32_bf16 v[40:43], v[124:127], v[190:193], v[40:43]
	v_mfma_f32_16x16x32_bf16 v[28:31], v[96:99], v[194:197], v[28:31]
	v_mfma_f32_16x16x32_bf16 v[28:31], v[100:103], v[198:201], v[28:31]
	v_mfma_f32_16x16x32_bf16 v[24:27], v[120:123], v[194:197], v[24:27]
	v_mfma_f32_16x16x32_bf16 v[24:27], v[124:127], v[198:201], v[24:27]
	v_mfma_f32_16x16x32_bf16 v[12:15], v[96:99], v[202:205], v[12:15]
	v_mfma_f32_16x16x32_bf16 v[12:15], v[100:103], v[218:221], v[12:15]
	v_mfma_f32_16x16x32_bf16 v[8:11], v[120:123], v[202:205], v[8:11]
	v_mfma_f32_16x16x32_bf16 v[8:11], v[124:127], v[218:221], v[8:11]
	v_mfma_f32_16x16x32_bf16 v[52:55], v[144:147], v[178:181], v[52:55]
	v_mfma_f32_16x16x32_bf16 v[52:55], v[148:151], v[182:185], v[52:55]
	v_mfma_f32_16x16x32_bf16 v[48:51], v[152:155], v[178:181], v[48:51]
	v_mfma_f32_16x16x32_bf16 v[48:51], v[156:159], v[182:185], v[48:51]
	v_mfma_f32_16x16x32_bf16 v[36:39], v[144:147], v[186:189], v[36:39]
	v_mfma_f32_16x16x32_bf16 v[36:39], v[148:151], v[190:193], v[36:39]
	v_mfma_f32_16x16x32_bf16 v[32:35], v[152:155], v[186:189], v[32:35]
	v_mfma_f32_16x16x32_bf16 v[32:35], v[156:159], v[190:193], v[32:35]
	v_mfma_f32_16x16x32_bf16 v[20:23], v[144:147], v[194:197], v[20:23]
	v_mfma_f32_16x16x32_bf16 v[20:23], v[148:151], v[198:201], v[20:23]
	v_mfma_f32_16x16x32_bf16 v[16:19], v[152:155], v[194:197], v[16:19]
	v_mfma_f32_16x16x32_bf16 v[16:19], v[156:159], v[198:201], v[16:19]
	s_setprio 2
	s_barrier
	v_mfma_f32_16x16x32_bf16 v[4:7], v[144:147], v[202:205], v[4:7]
	v_mfma_f32_16x16x32_bf16 v[4:7], v[148:151], v[218:221], v[4:7]
	v_mfma_f32_16x16x32_bf16 v[0:3], v[152:155], v[202:205], v[0:3]
	v_mfma_f32_16x16x32_bf16 v[0:3], v[156:159], v[218:221], v[0:3]
	s_setprio 0
	s_add_i32 s78, s78, 2
	s_add_u32 s6, s6, 0x100
	s_addc_u32 s7, s7, 0
	s_add_u32 s56, s56, 0x100
	s_addc_u32 s57, s57, 0
	s_cmp_gt_u32 s78, 13
.LBB0_323:
	ds_read_b128 v[96:99], v209
	ds_read_b128 v[100:103], v209 offset:1024
	ds_read_b128 v[120:123], v209 offset:2048
	ds_read_b128 v[124:127], v209 offset:3072
	ds_read_b128 v[144:147], v210
	ds_read_b128 v[148:151], v210 offset:1024
	ds_read_b128 v[152:155], v210 offset:2048
	ds_read_b128 v[156:159], v210 offset:3072
	s_add_u32 s8, s6, 0xfffc0080
	s_addc_u32 s9, s7, -1
	s_cmp_eq_u32 s78, 12
	s_cselect_b32 s51, s18, s9
	s_cselect_b32 s50, s43, s8
	s_cselect_b32 s9, s45, s57
	s_cselect_b32 s8, s55, s56
	v_lshl_add_u64 v[206:207], s[6:7], 0, v[170:171]
	s_add_i32 m0, s17, 0xc000
	ds_read_b128 v[178:181], v211
	ds_read_b128 v[182:185], v211 offset:1024
	ds_read_b128 v[186:189], v211 offset:2048
	ds_read_b128 v[190:193], v211 offset:3072
	ds_read_b128 v[194:197], v211 offset:4096
	ds_read_b128 v[198:201], v211 offset:5120
	ds_read_b128 v[202:205], v211 offset:6144
	ds_read_b128 v[218:221], v211 offset:7168
	global_load_lds_dwordx4 v[206:207], off
	s_add_i32 m0, s17, 0xe000
	v_lshl_add_u64 v[206:207], s[6:7], 0, v[172:173]
	global_load_lds_dwordx4 v[206:207], off
	s_waitcnt vmcnt(8) lgkmcnt(0)
	s_barrier
	s_setprio 1
	v_mfma_f32_16x16x32_bf16 v[140:143], v[96:99], v[178:181], v[140:143]
	v_mfma_f32_16x16x32_bf16 v[140:143], v[100:103], v[182:185], v[140:143]
	v_mfma_f32_16x16x32_bf16 v[136:139], v[120:123], v[178:181], v[136:139]
	v_mfma_f32_16x16x32_bf16 v[136:139], v[124:127], v[182:185], v[136:139]
	v_mfma_f32_16x16x32_bf16 v[116:119], v[96:99], v[186:189], v[116:119]
	v_mfma_f32_16x16x32_bf16 v[116:119], v[100:103], v[190:193], v[116:119]
	v_mfma_f32_16x16x32_bf16 v[112:115], v[120:123], v[186:189], v[112:115]
	v_mfma_f32_16x16x32_bf16 v[112:115], v[124:127], v[190:193], v[112:115]
	v_mfma_f32_16x16x32_bf16 v[92:95], v[96:99], v[194:197], v[92:95]
	v_mfma_f32_16x16x32_bf16 v[92:95], v[100:103], v[198:201], v[92:95]
	v_mfma_f32_16x16x32_bf16 v[88:91], v[120:123], v[194:197], v[88:91]
	v_mfma_f32_16x16x32_bf16 v[88:91], v[124:127], v[198:201], v[88:91]
	v_mfma_f32_16x16x32_bf16 v[76:79], v[96:99], v[202:205], v[76:79]
	v_mfma_f32_16x16x32_bf16 v[76:79], v[100:103], v[218:221], v[76:79]
	v_mfma_f32_16x16x32_bf16 v[72:75], v[120:123], v[202:205], v[72:75]
	v_mfma_f32_16x16x32_bf16 v[72:75], v[124:127], v[218:221], v[72:75]
	v_mfma_f32_16x16x32_bf16 v[132:135], v[144:147], v[178:181], v[132:135]
	v_mfma_f32_16x16x32_bf16 v[132:135], v[148:151], v[182:185], v[132:135]
	v_mfma_f32_16x16x32_bf16 v[128:131], v[152:155], v[178:181], v[128:131]
	v_mfma_f32_16x16x32_bf16 v[128:131], v[156:159], v[182:185], v[128:131]
	v_mfma_f32_16x16x32_bf16 v[108:111], v[144:147], v[186:189], v[108:111]
	v_mfma_f32_16x16x32_bf16 v[108:111], v[148:151], v[190:193], v[108:111]
	v_mfma_f32_16x16x32_bf16 v[104:107], v[152:155], v[186:189], v[104:107]
	v_mfma_f32_16x16x32_bf16 v[104:107], v[156:159], v[190:193], v[104:107]
	v_mfma_f32_16x16x32_bf16 v[84:87], v[144:147], v[194:197], v[84:87]
	v_mfma_f32_16x16x32_bf16 v[84:87], v[148:151], v[198:201], v[84:87]
	v_mfma_f32_16x16x32_bf16 v[80:83], v[152:155], v[194:197], v[80:83]
	v_mfma_f32_16x16x32_bf16 v[80:83], v[156:159], v[198:201], v[80:83]
	s_setprio 2
	s_barrier
	v_mfma_f32_16x16x32_bf16 v[68:71], v[144:147], v[202:205], v[68:71]
	v_mfma_f32_16x16x32_bf16 v[68:71], v[148:151], v[218:221], v[68:71]
	v_mfma_f32_16x16x32_bf16 v[64:67], v[152:155], v[202:205], v[64:67]
	v_mfma_f32_16x16x32_bf16 v[64:67], v[156:159], v[218:221], v[64:67]
	s_setprio 2
	s_add_i32 s79, s73, s61
	v_lshl_add_u64 v[206:207], s[8:9], 0, v[162:163]
	s_mov_b32 m0, s79
	ds_read_b128 v[178:181], v211 offset:16384
	ds_read_b128 v[182:185], v211 offset:17408
	ds_read_b128 v[186:189], v211 offset:18432
	ds_read_b128 v[190:193], v211 offset:19456
	ds_read_b128 v[194:197], v211 offset:20480
	ds_read_b128 v[198:201], v211 offset:21504
	ds_read_b128 v[202:205], v211 offset:22528
	ds_read_b128 v[218:221], v211 offset:23552
	global_load_lds_dwordx4 v[206:207], off
	s_add_i32 m0, s79, 0x2000
	s_add_u32 s80, s8, 0x40000
	v_lshl_add_u64 v[222:223], s[8:9], 0, v[166:167]
	s_addc_u32 s81, s9, 0
	s_add_i32 s79, s74, s61
	global_load_lds_dwordx4 v[222:223], off
	v_lshl_add_u64 v[224:225], s[80:81], 0, v[162:163]
	s_mov_b32 m0, s79
	v_lshl_add_u64 v[226:227], s[50:51], 0, v[164:165]
	global_load_lds_dwordx4 v[224:225], off
	s_add_i32 m0, s79, 0x2000
	v_lshl_add_u64 v[224:225], s[80:81], 0, v[166:167]
	global_load_lds_dwordx4 v[224:225], off
	s_mov_b32 m0, s17
	v_lshl_add_u64 v[224:225], s[50:51], 0, v[160:161]
	global_load_lds_dwordx4 v[224:225], off
	s_mov_b32 m0, s62
	s_nop 0
	global_load_lds_dwordx4 v[226:227], off
	s_waitcnt vmcnt(8) lgkmcnt(0)
	s_barrier
	s_setprio 1
	v_mfma_f32_16x16x32_bf16 v[60:63], v[96:99], v[178:181], v[60:63]
	v_mfma_f32_16x16x32_bf16 v[60:63], v[100:103], v[182:185], v[60:63]
	v_mfma_f32_16x16x32_bf16 v[56:59], v[120:123], v[178:181], v[56:59]
	v_mfma_f32_16x16x32_bf16 v[56:59], v[124:127], v[182:185], v[56:59]
	v_mfma_f32_16x16x32_bf16 v[44:47], v[96:99], v[186:189], v[44:47]
	v_mfma_f32_16x16x32_bf16 v[44:47], v[100:103], v[190:193], v[44:47]
	v_mfma_f32_16x16x32_bf16 v[40:43], v[120:123], v[186:189], v[40:43]
	v_mfma_f32_16x16x32_bf16 v[40:43], v[124:127], v[190:193], v[40:43]
	v_mfma_f32_16x16x32_bf16 v[28:31], v[96:99], v[194:197], v[28:31]
	v_mfma_f32_16x16x32_bf16 v[28:31], v[100:103], v[198:201], v[28:31]
	v_mfma_f32_16x16x32_bf16 v[24:27], v[120:123], v[194:197], v[24:27]
	v_mfma_f32_16x16x32_bf16 v[24:27], v[124:127], v[198:201], v[24:27]
	v_mfma_f32_16x16x32_bf16 v[12:15], v[96:99], v[202:205], v[12:15]
	v_mfma_f32_16x16x32_bf16 v[12:15], v[100:103], v[218:221], v[12:15]
	v_mfma_f32_16x16x32_bf16 v[8:11], v[120:123], v[202:205], v[8:11]
	v_mfma_f32_16x16x32_bf16 v[8:11], v[124:127], v[218:221], v[8:11]
	v_mfma_f32_16x16x32_bf16 v[52:55], v[144:147], v[178:181], v[52:55]
	v_mfma_f32_16x16x32_bf16 v[52:55], v[148:151], v[182:185], v[52:55]
	v_mfma_f32_16x16x32_bf16 v[48:51], v[152:155], v[178:181], v[48:51]
	v_mfma_f32_16x16x32_bf16 v[48:51], v[156:159], v[182:185], v[48:51]
	v_mfma_f32_16x16x32_bf16 v[36:39], v[144:147], v[186:189], v[36:39]
	v_mfma_f32_16x16x32_bf16 v[36:39], v[148:151], v[190:193], v[36:39]
	v_mfma_f32_16x16x32_bf16 v[32:35], v[152:155], v[186:189], v[32:35]
	v_mfma_f32_16x16x32_bf16 v[32:35], v[156:159], v[190:193], v[32:35]
	v_mfma_f32_16x16x32_bf16 v[20:23], v[144:147], v[194:197], v[20:23]
	v_mfma_f32_16x16x32_bf16 v[20:23], v[148:151], v[198:201], v[20:23]
	v_mfma_f32_16x16x32_bf16 v[16:19], v[152:155], v[194:197], v[16:19]
	v_mfma_f32_16x16x32_bf16 v[16:19], v[156:159], v[198:201], v[16:19]
	s_setprio 2
	s_barrier
	v_mfma_f32_16x16x32_bf16 v[4:7], v[144:147], v[202:205], v[4:7]
	v_mfma_f32_16x16x32_bf16 v[4:7], v[148:151], v[218:221], v[4:7]
	v_mfma_f32_16x16x32_bf16 v[0:3], v[152:155], v[202:205], v[0:3]
	v_mfma_f32_16x16x32_bf16 v[0:3], v[156:159], v[218:221], v[0:3]
	s_setprio 0
	s_add_i32 s79, 0, 0x18000
	s_add_i32 s80, 0, 0x1c000
	v_add_u32_e32 v124, s79, v208
	v_add_u32_e32 v156, s80, v208
	ds_read_b128 v[96:99], v124
	ds_read_b128 v[100:103], v124 offset:1024
	ds_read_b128 v[120:123], v124 offset:2048
	ds_read_b128 v[124:127], v124 offset:3072
	ds_read_b128 v[144:147], v156
	ds_read_b128 v[148:151], v156 offset:1024
	ds_read_b128 v[152:155], v156 offset:2048
	ds_read_b128 v[156:159], v156 offset:3072
	s_add_u32 s50, s50, 0x40000
	s_addc_u32 s51, s51, 0
	s_mov_b32 m0, s63
	v_lshl_add_u64 v[228:229], s[50:51], 0, v[160:161]
	ds_read_b128 v[178:181], v211 offset:32768
	ds_read_b128 v[182:185], v211 offset:33792
	ds_read_b128 v[186:189], v211 offset:34816
	ds_read_b128 v[190:193], v211 offset:35840
	ds_read_b128 v[194:197], v211 offset:36864
	ds_read_b128 v[198:201], v211 offset:37888
	ds_read_b128 v[202:205], v211 offset:38912
	ds_read_b128 v[218:221], v211 offset:39936
	global_load_lds_dwordx4 v[228:229], off
	s_mov_b32 m0, s64
	v_lshl_add_u64 v[228:229], s[50:51], 0, v[164:165]
	global_load_lds_dwordx4 v[228:229], off
	s_waitcnt vmcnt(8) lgkmcnt(0)
	s_barrier
	s_setprio 1
	v_mfma_f32_16x16x32_bf16 v[140:143], v[96:99], v[178:181], v[140:143]
	v_mfma_f32_16x16x32_bf16 v[140:143], v[100:103], v[182:185], v[140:143]
	v_mfma_f32_16x16x32_bf16 v[136:139], v[120:123], v[178:181], v[136:139]
	v_mfma_f32_16x16x32_bf16 v[136:139], v[124:127], v[182:185], v[136:139]
	v_mfma_f32_16x16x32_bf16 v[116:119], v[96:99], v[186:189], v[116:119]
	v_mfma_f32_16x16x32_bf16 v[116:119], v[100:103], v[190:193], v[116:119]
	v_mfma_f32_16x16x32_bf16 v[112:115], v[120:123], v[186:189], v[112:115]
	v_mfma_f32_16x16x32_bf16 v[112:115], v[124:127], v[190:193], v[112:115]
	v_mfma_f32_16x16x32_bf16 v[92:95], v[96:99], v[194:197], v[92:95]
	v_mfma_f32_16x16x32_bf16 v[92:95], v[100:103], v[198:201], v[92:95]
	v_mfma_f32_16x16x32_bf16 v[88:91], v[120:123], v[194:197], v[88:91]
	v_mfma_f32_16x16x32_bf16 v[88:91], v[124:127], v[198:201], v[88:91]
	v_mfma_f32_16x16x32_bf16 v[76:79], v[96:99], v[202:205], v[76:79]
	v_mfma_f32_16x16x32_bf16 v[76:79], v[100:103], v[218:221], v[76:79]
	v_mfma_f32_16x16x32_bf16 v[72:75], v[120:123], v[202:205], v[72:75]
	v_mfma_f32_16x16x32_bf16 v[72:75], v[124:127], v[218:221], v[72:75]
	v_mfma_f32_16x16x32_bf16 v[132:135], v[144:147], v[178:181], v[132:135]
	v_mfma_f32_16x16x32_bf16 v[132:135], v[148:151], v[182:185], v[132:135]
	v_mfma_f32_16x16x32_bf16 v[128:131], v[152:155], v[178:181], v[128:131]
	v_mfma_f32_16x16x32_bf16 v[128:131], v[156:159], v[182:185], v[128:131]
	v_mfma_f32_16x16x32_bf16 v[108:111], v[144:147], v[186:189], v[108:111]
	v_mfma_f32_16x16x32_bf16 v[108:111], v[148:151], v[190:193], v[108:111]
	v_mfma_f32_16x16x32_bf16 v[104:107], v[152:155], v[186:189], v[104:107]
	v_mfma_f32_16x16x32_bf16 v[104:107], v[156:159], v[190:193], v[104:107]
	v_mfma_f32_16x16x32_bf16 v[84:87], v[144:147], v[194:197], v[84:87]
	v_mfma_f32_16x16x32_bf16 v[84:87], v[148:151], v[198:201], v[84:87]
	v_mfma_f32_16x16x32_bf16 v[80:83], v[152:155], v[194:197], v[80:83]
	v_mfma_f32_16x16x32_bf16 v[80:83], v[156:159], v[198:201], v[80:83]
	s_setprio 2
	s_barrier
	v_mfma_f32_16x16x32_bf16 v[68:71], v[144:147], v[202:205], v[68:71]
	v_mfma_f32_16x16x32_bf16 v[68:71], v[148:151], v[218:221], v[68:71]
	v_mfma_f32_16x16x32_bf16 v[64:67], v[152:155], v[202:205], v[64:67]
	v_mfma_f32_16x16x32_bf16 v[64:67], v[156:159], v[218:221], v[64:67]
	s_setprio 2
	s_add_i32 s50, s79, s61
	v_lshl_add_u64 v[206:207], v[206:207], 0, s[36:37]
	s_mov_b32 m0, s50
	ds_read_b128 v[178:181], v211 offset:49152
	ds_read_b128 v[182:185], v211 offset:50176
	ds_read_b128 v[186:189], v211 offset:51200
	ds_read_b128 v[190:193], v211 offset:52224
	ds_read_b128 v[194:197], v211 offset:53248
	ds_read_b128 v[198:201], v211 offset:54272
	ds_read_b128 v[202:205], v211 offset:55296
	ds_read_b128 v[218:221], v211 offset:56320
	global_load_lds_dwordx4 v[206:207], off
	s_add_i32 m0, s50, 0x2000
	s_add_u32 s8, s8, 0x40080
	v_lshl_add_u64 v[206:207], v[222:223], 0, s[36:37]
	s_addc_u32 s9, s9, 0
	s_add_i32 s50, s80, s61
	global_load_lds_dwordx4 v[206:207], off
	s_mov_b32 m0, s50
	v_lshl_add_u64 v[206:207], s[8:9], 0, v[162:163]
	global_load_lds_dwordx4 v[206:207], off
	s_add_i32 m0, s50, 0x2000
	v_lshl_add_u64 v[206:207], s[8:9], 0, v[166:167]
	global_load_lds_dwordx4 v[206:207], off
	s_mov_b32 m0, s68
	v_lshl_add_u64 v[206:207], v[224:225], 0, s[36:37]
	global_load_lds_dwordx4 v[206:207], off
	s_mov_b32 m0, s69
	v_lshl_add_u64 v[206:207], v[226:227], 0, s[36:37]
	global_load_lds_dwordx4 v[206:207], off
	s_waitcnt vmcnt(8) lgkmcnt(0)
	s_barrier
	s_setprio 1
	v_mfma_f32_16x16x32_bf16 v[60:63], v[96:99], v[178:181], v[60:63]
	v_mfma_f32_16x16x32_bf16 v[60:63], v[100:103], v[182:185], v[60:63]
	v_mfma_f32_16x16x32_bf16 v[56:59], v[120:123], v[178:181], v[56:59]
	v_mfma_f32_16x16x32_bf16 v[56:59], v[124:127], v[182:185], v[56:59]
	v_mfma_f32_16x16x32_bf16 v[44:47], v[96:99], v[186:189], v[44:47]
	v_mfma_f32_16x16x32_bf16 v[44:47], v[100:103], v[190:193], v[44:47]
	v_mfma_f32_16x16x32_bf16 v[40:43], v[120:123], v[186:189], v[40:43]
	v_mfma_f32_16x16x32_bf16 v[40:43], v[124:127], v[190:193], v[40:43]
	v_mfma_f32_16x16x32_bf16 v[28:31], v[96:99], v[194:197], v[28:31]
	v_mfma_f32_16x16x32_bf16 v[28:31], v[100:103], v[198:201], v[28:31]
	v_mfma_f32_16x16x32_bf16 v[24:27], v[120:123], v[194:197], v[24:27]
	v_mfma_f32_16x16x32_bf16 v[24:27], v[124:127], v[198:201], v[24:27]
	v_mfma_f32_16x16x32_bf16 v[12:15], v[96:99], v[202:205], v[12:15]
	v_mfma_f32_16x16x32_bf16 v[12:15], v[100:103], v[218:221], v[12:15]
	v_mfma_f32_16x16x32_bf16 v[8:11], v[120:123], v[202:205], v[8:11]
	v_mfma_f32_16x16x32_bf16 v[8:11], v[124:127], v[218:221], v[8:11]
	v_mfma_f32_16x16x32_bf16 v[52:55], v[144:147], v[178:181], v[52:55]
	v_mfma_f32_16x16x32_bf16 v[52:55], v[148:151], v[182:185], v[52:55]
	v_mfma_f32_16x16x32_bf16 v[48:51], v[152:155], v[178:181], v[48:51]
	v_mfma_f32_16x16x32_bf16 v[48:51], v[156:159], v[182:185], v[48:51]
	v_mfma_f32_16x16x32_bf16 v[36:39], v[144:147], v[186:189], v[36:39]
	v_mfma_f32_16x16x32_bf16 v[36:39], v[148:151], v[190:193], v[36:39]
	v_mfma_f32_16x16x32_bf16 v[32:35], v[152:155], v[186:189], v[32:35]
	v_mfma_f32_16x16x32_bf16 v[32:35], v[156:159], v[190:193], v[32:35]
	v_mfma_f32_16x16x32_bf16 v[20:23], v[144:147], v[194:197], v[20:23]
	v_mfma_f32_16x16x32_bf16 v[20:23], v[148:151], v[198:201], v[20:23]
	v_mfma_f32_16x16x32_bf16 v[16:19], v[152:155], v[194:197], v[16:19]
	v_mfma_f32_16x16x32_bf16 v[16:19], v[156:159], v[198:201], v[16:19]
	s_setprio 2
	s_barrier
	v_mfma_f32_16x16x32_bf16 v[4:7], v[144:147], v[202:205], v[4:7]
	v_mfma_f32_16x16x32_bf16 v[4:7], v[148:151], v[218:221], v[4:7]
	v_mfma_f32_16x16x32_bf16 v[0:3], v[152:155], v[202:205], v[0:3]
	v_mfma_f32_16x16x32_bf16 v[0:3], v[156:159], v[218:221], v[0:3]
	s_setprio 0
	s_add_i32 s78, s78, 2
	s_add_u32 s6, s6, 0x100
	s_addc_u32 s7, s7, 0
	s_add_u32 s56, s56, 0x100
	s_addc_u32 s57, s57, 0
	s_cmp_gt_u32 s78, 13
	s_cbranch_scc0 .LBB0_323

.LBB0_700:
	ds_read_b128 v[130:133], v203
	ds_read_b128 v[134:137], v203 offset:1024
	ds_read_b128 v[138:141], v203 offset:2048
	ds_read_b128 v[142:145], v203 offset:3072
	ds_read_b128 v[146:149], v195
	ds_read_b128 v[150:153], v195 offset:1024
	ds_read_b128 v[154:157], v195 offset:2048
	ds_read_b128 v[158:161], v195 offset:3072
	s_add_u32 s47, s44, 0xfff80080
	s_addc_u32 s48, s45, -1
	s_cmp_eq_u32 s46, 28
	s_cselect_b32 s49, s29, s48
	s_cselect_b32 s48, s71, s47
	s_cselect_b32 s47, s31, s84
	s_cselect_b32 s46, s72, s83
	s_mov_b32 m0, s73
	v_lshl_add_u64 v[174:175], s[44:45], 0, v[180:181]
	ds_read_b128 v[162:165], v211
	ds_read_b128 v[166:169], v211 offset:1024
	ds_read_b128 v[170:173], v211 offset:2048
	ds_read_b128 v[184:187], v211 offset:3072
	ds_read_b128 v[190:193], v211 offset:4096
	ds_read_b128 v[196:199], v211 offset:5120
	ds_read_b128 v[204:207], v211 offset:6144
	ds_read_b128 v[212:215], v211 offset:7168
	global_load_lds_dwordx4 v[174:175], off
	s_mov_b32 m0, s74
	v_lshl_add_u64 v[174:175], s[44:45], 0, v[182:183]
	global_load_lds_dwordx4 v[174:175], off
	s_waitcnt vmcnt(8) lgkmcnt(0)
	s_barrier
	s_setprio 1
	v_mfma_f32_16x16x32_bf16 v[124:127], v[130:133], v[162:165], v[124:127]
	v_mfma_f32_16x16x32_bf16 v[124:127], v[134:137], v[166:169], v[124:127]
	v_mfma_f32_16x16x32_bf16 v[120:123], v[138:141], v[162:165], v[120:123]
	v_mfma_f32_16x16x32_bf16 v[120:123], v[142:145], v[166:169], v[120:123]
	v_mfma_f32_16x16x32_bf16 v[108:111], v[130:133], v[170:173], v[108:111]
	v_mfma_f32_16x16x32_bf16 v[108:111], v[134:137], v[184:187], v[108:111]
	v_mfma_f32_16x16x32_bf16 v[104:107], v[138:141], v[170:173], v[104:107]
	v_mfma_f32_16x16x32_bf16 v[104:107], v[142:145], v[184:187], v[104:107]
	v_mfma_f32_16x16x32_bf16 v[92:95], v[130:133], v[190:193], v[92:95]
	v_mfma_f32_16x16x32_bf16 v[92:95], v[134:137], v[196:199], v[92:95]
	v_mfma_f32_16x16x32_bf16 v[88:91], v[138:141], v[190:193], v[88:91]
	v_mfma_f32_16x16x32_bf16 v[88:91], v[142:145], v[196:199], v[88:91]
	v_mfma_f32_16x16x32_bf16 v[76:79], v[130:133], v[204:207], v[76:79]
	v_mfma_f32_16x16x32_bf16 v[76:79], v[134:137], v[212:215], v[76:79]
	v_mfma_f32_16x16x32_bf16 v[72:75], v[138:141], v[204:207], v[72:75]
	v_mfma_f32_16x16x32_bf16 v[72:75], v[142:145], v[212:215], v[72:75]
	v_mfma_f32_16x16x32_bf16 v[116:119], v[146:149], v[162:165], v[116:119]
	v_mfma_f32_16x16x32_bf16 v[116:119], v[150:153], v[166:169], v[116:119]
	v_mfma_f32_16x16x32_bf16 v[112:115], v[154:157], v[162:165], v[112:115]
	v_mfma_f32_16x16x32_bf16 v[112:115], v[158:161], v[166:169], v[112:115]
	v_mfma_f32_16x16x32_bf16 v[100:103], v[146:149], v[170:173], v[100:103]
	v_mfma_f32_16x16x32_bf16 v[100:103], v[150:153], v[184:187], v[100:103]
	v_mfma_f32_16x16x32_bf16 v[96:99], v[154:157], v[170:173], v[96:99]
	v_mfma_f32_16x16x32_bf16 v[96:99], v[158:161], v[184:187], v[96:99]
	v_mfma_f32_16x16x32_bf16 v[84:87], v[146:149], v[190:193], v[84:87]
	v_mfma_f32_16x16x32_bf16 v[84:87], v[150:153], v[196:199], v[84:87]
	v_mfma_f32_16x16x32_bf16 v[80:83], v[154:157], v[190:193], v[80:83]
	v_mfma_f32_16x16x32_bf16 v[80:83], v[158:161], v[196:199], v[80:83]
	s_setprio 2
	s_barrier
	v_mfma_f32_16x16x32_bf16 v[68:71], v[146:149], v[204:207], v[68:71]
	v_mfma_f32_16x16x32_bf16 v[68:71], v[150:153], v[212:215], v[68:71]
	v_mfma_f32_16x16x32_bf16 v[64:67], v[154:157], v[204:207], v[64:67]
	v_mfma_f32_16x16x32_bf16 v[64:67], v[158:161], v[212:215], v[64:67]
	s_setprio 2
	s_mov_b32 m0, s75
	v_lshl_add_u64 v[174:175], s[46:47], 0, v[176:177]
	s_add_u32 s86, s46, 0x80000
	ds_read_b128 v[162:165], v211 offset:16384
	ds_read_b128 v[166:169], v211 offset:17408
	ds_read_b128 v[170:173], v211 offset:18432
	ds_read_b128 v[184:187], v211 offset:19456
	ds_read_b128 v[190:193], v211 offset:20480
	ds_read_b128 v[196:199], v211 offset:21504
	ds_read_b128 v[204:207], v211 offset:22528
	ds_read_b128 v[212:215], v211 offset:23552
	global_load_lds_dwordx4 v[174:175], off
	v_lshl_add_u64 v[200:201], s[46:47], 0, v[178:179]
	s_mov_b32 m0, s76
	s_addc_u32 s87, s47, 0
	global_load_lds_dwordx4 v[200:201], off
	v_lshl_add_u64 v[208:209], s[86:87], 0, v[176:177]
	s_mov_b32 m0, s77
	v_lshl_add_u64 v[216:217], s[48:49], 0, v[178:179]
	global_load_lds_dwordx4 v[208:209], off
	s_mov_b32 m0, s78
	v_lshl_add_u64 v[208:209], s[86:87], 0, v[178:179]
	global_load_lds_dwordx4 v[208:209], off
	s_mov_b32 m0, s56
	v_lshl_add_u64 v[208:209], s[48:49], 0, v[176:177]
	global_load_lds_dwordx4 v[208:209], off
	s_mov_b32 m0, s57
	s_nop 0
	global_load_lds_dwordx4 v[216:217], off
	s_waitcnt vmcnt(8) lgkmcnt(0)
	s_barrier
	s_setprio 1
	v_mfma_f32_16x16x32_bf16 v[60:63], v[130:133], v[162:165], v[60:63]
	v_mfma_f32_16x16x32_bf16 v[60:63], v[134:137], v[166:169], v[60:63]
	v_mfma_f32_16x16x32_bf16 v[56:59], v[138:141], v[162:165], v[56:59]
	v_mfma_f32_16x16x32_bf16 v[56:59], v[142:145], v[166:169], v[56:59]
	v_mfma_f32_16x16x32_bf16 v[44:47], v[130:133], v[170:173], v[44:47]
	v_mfma_f32_16x16x32_bf16 v[44:47], v[134:137], v[184:187], v[44:47]
	v_mfma_f32_16x16x32_bf16 v[40:43], v[138:141], v[170:173], v[40:43]
	v_mfma_f32_16x16x32_bf16 v[40:43], v[142:145], v[184:187], v[40:43]
	v_mfma_f32_16x16x32_bf16 v[28:31], v[130:133], v[190:193], v[28:31]
	v_mfma_f32_16x16x32_bf16 v[28:31], v[134:137], v[196:199], v[28:31]
	v_mfma_f32_16x16x32_bf16 v[24:27], v[138:141], v[190:193], v[24:27]
	v_mfma_f32_16x16x32_bf16 v[24:27], v[142:145], v[196:199], v[24:27]
	v_mfma_f32_16x16x32_bf16 v[12:15], v[130:133], v[204:207], v[12:15]
	v_mfma_f32_16x16x32_bf16 v[12:15], v[134:137], v[212:215], v[12:15]
	v_mfma_f32_16x16x32_bf16 v[8:11], v[138:141], v[204:207], v[8:11]
	v_mfma_f32_16x16x32_bf16 v[8:11], v[142:145], v[212:215], v[8:11]
	v_mfma_f32_16x16x32_bf16 v[52:55], v[146:149], v[162:165], v[52:55]
	v_mfma_f32_16x16x32_bf16 v[52:55], v[150:153], v[166:169], v[52:55]
	v_mfma_f32_16x16x32_bf16 v[48:51], v[154:157], v[162:165], v[48:51]
	v_mfma_f32_16x16x32_bf16 v[48:51], v[158:161], v[166:169], v[48:51]
	v_mfma_f32_16x16x32_bf16 v[36:39], v[146:149], v[170:173], v[36:39]
	v_mfma_f32_16x16x32_bf16 v[36:39], v[150:153], v[184:187], v[36:39]
	v_mfma_f32_16x16x32_bf16 v[32:35], v[154:157], v[170:173], v[32:35]
	v_mfma_f32_16x16x32_bf16 v[32:35], v[158:161], v[184:187], v[32:35]
	v_mfma_f32_16x16x32_bf16 v[20:23], v[146:149], v[190:193], v[20:23]
	v_mfma_f32_16x16x32_bf16 v[20:23], v[150:153], v[196:199], v[20:23]
	v_mfma_f32_16x16x32_bf16 v[16:19], v[154:157], v[190:193], v[16:19]
	v_mfma_f32_16x16x32_bf16 v[16:19], v[158:161], v[196:199], v[16:19]
	s_setprio 2
	s_barrier
	v_mfma_f32_16x16x32_bf16 v[4:7], v[146:149], v[204:207], v[4:7]
	v_mfma_f32_16x16x32_bf16 v[4:7], v[150:153], v[212:215], v[4:7]
	v_mfma_f32_16x16x32_bf16 v[0:3], v[154:157], v[204:207], v[0:3]
	v_mfma_f32_16x16x32_bf16 v[0:3], v[158:161], v[212:215], v[0:3]
	s_setprio 0
	ds_read_b128 v[130:133], v128
	ds_read_b128 v[134:137], v128 offset:1024
	ds_read_b128 v[138:141], v128 offset:2048
	ds_read_b128 v[142:145], v128 offset:3072
	ds_read_b128 v[146:149], v129
	ds_read_b128 v[150:153], v129 offset:1024
	ds_read_b128 v[154:157], v129 offset:2048
	ds_read_b128 v[158:161], v129 offset:3072
	s_add_u32 s48, s48, 0x80000
	s_addc_u32 s49, s49, 0
	s_mov_b32 m0, s58
	v_lshl_add_u64 v[218:219], s[48:49], 0, v[176:177]
	ds_read_b128 v[162:165], v211 offset:32768
	ds_read_b128 v[166:169], v211 offset:33792
	ds_read_b128 v[170:173], v211 offset:34816
	ds_read_b128 v[184:187], v211 offset:35840
	ds_read_b128 v[190:193], v211 offset:36864
	ds_read_b128 v[196:199], v211 offset:37888
	ds_read_b128 v[204:207], v211 offset:38912
	ds_read_b128 v[212:215], v211 offset:39936
	global_load_lds_dwordx4 v[218:219], off
	s_mov_b32 m0, s59
	v_lshl_add_u64 v[218:219], s[48:49], 0, v[178:179]
	global_load_lds_dwordx4 v[218:219], off
	s_waitcnt vmcnt(8) lgkmcnt(0)
	s_barrier
	s_setprio 1
	v_mfma_f32_16x16x32_bf16 v[124:127], v[130:133], v[162:165], v[124:127]
	v_mfma_f32_16x16x32_bf16 v[124:127], v[134:137], v[166:169], v[124:127]
	v_mfma_f32_16x16x32_bf16 v[120:123], v[138:141], v[162:165], v[120:123]
	v_mfma_f32_16x16x32_bf16 v[120:123], v[142:145], v[166:169], v[120:123]
	v_mfma_f32_16x16x32_bf16 v[108:111], v[130:133], v[170:173], v[108:111]
	v_mfma_f32_16x16x32_bf16 v[108:111], v[134:137], v[184:187], v[108:111]
	v_mfma_f32_16x16x32_bf16 v[104:107], v[138:141], v[170:173], v[104:107]
	v_mfma_f32_16x16x32_bf16 v[104:107], v[142:145], v[184:187], v[104:107]
	v_mfma_f32_16x16x32_bf16 v[92:95], v[130:133], v[190:193], v[92:95]
	v_mfma_f32_16x16x32_bf16 v[92:95], v[134:137], v[196:199], v[92:95]
	v_mfma_f32_16x16x32_bf16 v[88:91], v[138:141], v[190:193], v[88:91]
	v_mfma_f32_16x16x32_bf16 v[88:91], v[142:145], v[196:199], v[88:91]
	v_mfma_f32_16x16x32_bf16 v[76:79], v[130:133], v[204:207], v[76:79]
	v_mfma_f32_16x16x32_bf16 v[76:79], v[134:137], v[212:215], v[76:79]
	v_mfma_f32_16x16x32_bf16 v[72:75], v[138:141], v[204:207], v[72:75]
	v_mfma_f32_16x16x32_bf16 v[72:75], v[142:145], v[212:215], v[72:75]
	v_mfma_f32_16x16x32_bf16 v[116:119], v[146:149], v[162:165], v[116:119]
	v_mfma_f32_16x16x32_bf16 v[116:119], v[150:153], v[166:169], v[116:119]
	v_mfma_f32_16x16x32_bf16 v[112:115], v[154:157], v[162:165], v[112:115]
	v_mfma_f32_16x16x32_bf16 v[112:115], v[158:161], v[166:169], v[112:115]
	v_mfma_f32_16x16x32_bf16 v[100:103], v[146:149], v[170:173], v[100:103]
	v_mfma_f32_16x16x32_bf16 v[100:103], v[150:153], v[184:187], v[100:103]
	v_mfma_f32_16x16x32_bf16 v[96:99], v[154:157], v[170:173], v[96:99]
	v_mfma_f32_16x16x32_bf16 v[96:99], v[158:161], v[184:187], v[96:99]
	v_mfma_f32_16x16x32_bf16 v[84:87], v[146:149], v[190:193], v[84:87]
	v_mfma_f32_16x16x32_bf16 v[84:87], v[150:153], v[196:199], v[84:87]
	v_mfma_f32_16x16x32_bf16 v[80:83], v[154:157], v[190:193], v[80:83]
	v_mfma_f32_16x16x32_bf16 v[80:83], v[158:161], v[196:199], v[80:83]
	s_setprio 2
	s_barrier
	v_mfma_f32_16x16x32_bf16 v[68:71], v[146:149], v[204:207], v[68:71]
	v_mfma_f32_16x16x32_bf16 v[68:71], v[150:153], v[212:215], v[68:71]
	v_mfma_f32_16x16x32_bf16 v[64:67], v[154:157], v[204:207], v[64:67]
	v_mfma_f32_16x16x32_bf16 v[64:67], v[158:161], v[212:215], v[64:67]
	s_setprio 2
	s_mov_b32 m0, s79
	v_lshl_add_u64 v[174:175], v[174:175], 0, s[20:21]
	s_add_u32 s46, s46, 0x80080
	ds_read_b128 v[162:165], v211 offset:49152
	ds_read_b128 v[166:169], v211 offset:50176
	ds_read_b128 v[170:173], v211 offset:51200
	ds_read_b128 v[184:187], v211 offset:52224
	ds_read_b128 v[190:193], v211 offset:53248
	ds_read_b128 v[196:199], v211 offset:54272
	ds_read_b128 v[204:207], v211 offset:55296
	ds_read_b128 v[212:215], v211 offset:56320
	global_load_lds_dwordx4 v[174:175], off
	v_lshl_add_u64 v[174:175], v[200:201], 0, s[20:21]
	s_mov_b32 m0, s80
	s_addc_u32 s47, s47, 0
	global_load_lds_dwordx4 v[174:175], off
	s_mov_b32 m0, s81
	v_lshl_add_u64 v[174:175], s[46:47], 0, v[176:177]
	global_load_lds_dwordx4 v[174:175], off
	s_mov_b32 m0, s82
	v_lshl_add_u64 v[174:175], s[46:47], 0, v[178:179]
	global_load_lds_dwordx4 v[174:175], off
	s_mov_b32 m0, s61
	v_lshl_add_u64 v[174:175], v[208:209], 0, s[20:21]
	global_load_lds_dwordx4 v[174:175], off
	s_mov_b32 m0, s62
	v_lshl_add_u64 v[174:175], v[216:217], 0, s[20:21]
	global_load_lds_dwordx4 v[174:175], off
	s_waitcnt vmcnt(8) lgkmcnt(0)
	s_barrier
	s_setprio 1
	v_mfma_f32_16x16x32_bf16 v[60:63], v[130:133], v[162:165], v[60:63]
	v_mfma_f32_16x16x32_bf16 v[60:63], v[134:137], v[166:169], v[60:63]
	v_mfma_f32_16x16x32_bf16 v[56:59], v[138:141], v[162:165], v[56:59]
	v_mfma_f32_16x16x32_bf16 v[56:59], v[142:145], v[166:169], v[56:59]
	v_mfma_f32_16x16x32_bf16 v[44:47], v[130:133], v[170:173], v[44:47]
	v_mfma_f32_16x16x32_bf16 v[44:47], v[134:137], v[184:187], v[44:47]
	v_mfma_f32_16x16x32_bf16 v[40:43], v[138:141], v[170:173], v[40:43]
	v_mfma_f32_16x16x32_bf16 v[40:43], v[142:145], v[184:187], v[40:43]
	v_mfma_f32_16x16x32_bf16 v[28:31], v[130:133], v[190:193], v[28:31]
	v_mfma_f32_16x16x32_bf16 v[28:31], v[134:137], v[196:199], v[28:31]
	v_mfma_f32_16x16x32_bf16 v[24:27], v[138:141], v[190:193], v[24:27]
	v_mfma_f32_16x16x32_bf16 v[24:27], v[142:145], v[196:199], v[24:27]
	v_mfma_f32_16x16x32_bf16 v[12:15], v[130:133], v[204:207], v[12:15]
	v_mfma_f32_16x16x32_bf16 v[12:15], v[134:137], v[212:215], v[12:15]
	v_mfma_f32_16x16x32_bf16 v[8:11], v[138:141], v[204:207], v[8:11]
	v_mfma_f32_16x16x32_bf16 v[8:11], v[142:145], v[212:215], v[8:11]
	v_mfma_f32_16x16x32_bf16 v[52:55], v[146:149], v[162:165], v[52:55]
	v_mfma_f32_16x16x32_bf16 v[52:55], v[150:153], v[166:169], v[52:55]
	v_mfma_f32_16x16x32_bf16 v[48:51], v[154:157], v[162:165], v[48:51]
	v_mfma_f32_16x16x32_bf16 v[48:51], v[158:161], v[166:169], v[48:51]
	v_mfma_f32_16x16x32_bf16 v[36:39], v[146:149], v[170:173], v[36:39]
	v_mfma_f32_16x16x32_bf16 v[36:39], v[150:153], v[184:187], v[36:39]
	v_mfma_f32_16x16x32_bf16 v[32:35], v[154:157], v[170:173], v[32:35]
	v_mfma_f32_16x16x32_bf16 v[32:35], v[158:161], v[184:187], v[32:35]
	v_mfma_f32_16x16x32_bf16 v[20:23], v[146:149], v[190:193], v[20:23]
	v_mfma_f32_16x16x32_bf16 v[20:23], v[150:153], v[196:199], v[20:23]
	v_mfma_f32_16x16x32_bf16 v[16:19], v[154:157], v[190:193], v[16:19]
	v_mfma_f32_16x16x32_bf16 v[16:19], v[158:161], v[196:199], v[16:19]
	s_setprio 2
	s_barrier
	v_mfma_f32_16x16x32_bf16 v[4:7], v[146:149], v[204:207], v[4:7]
	v_mfma_f32_16x16x32_bf16 v[4:7], v[150:153], v[212:215], v[4:7]
	v_mfma_f32_16x16x32_bf16 v[0:3], v[154:157], v[204:207], v[0:3]
	v_mfma_f32_16x16x32_bf16 v[0:3], v[158:161], v[212:215], v[0:3]
	s_setprio 0
	s_add_i32 s70, s70, 1
	s_add_u32 s44, s44, 0x100
	s_addc_u32 s45, s45, 0
	s_add_u32 s83, s83, 0x100
	s_addc_u32 s84, s84, 0
	s_cmp_gt_u32 s85, 29
	s_cbranch_scc0 .LBB0_698
	s_lshl_b32 s29, s41, 12
	s_and_b32 s29, s29, 0x1000
	s_add_i32 s29, s29, 0
	v_mbcnt_lo_u32_b32 v128, -1, 0
	v_mbcnt_hi_u32_b32 v128, -1, v128
	s_add_i32 s29, s29, s63
	v_lshlrev_b32_e32 v128, 4, v128
	s_add_i32 s29, s29, 0x20400
	v_and_b32_e32 v128, 0xf0, v128
	v_add_u32_e32 v128, s29, v128
	ds_read2_b32 v[214:215], v128 offset0:3 offset1:67
	ds_read2_b32 v[206:207], v128 offset0:131 offset1:195
	v_add_u32_e32 v128, 12, v128
	ds_read2st64_b32 v[196:197], v128 offset0:8 offset1:9
	ds_read2st64_b32 v[190:191], v128 offset0:10 offset1:11
	s_and_b64 vcc, exec, s[22:23]
	s_waitcnt lgkmcnt(0)
	v_mov_b32_e32 v210, v215
	v_mov_b32_e32 v202, v207
	v_mov_b32_e32 v194, v197
	v_mov_b32_e32 v188, v191
	s_cbranch_vccz .LBB0_703
	s_barrier

.LBB0_783:
	s_ashr_i32 s23, s22, 31
	s_lshl_b64 s[26:27], s[22:23], 19
	s_add_u32 s26, s43, s26
	s_addc_u32 s27, s44, s27
	s_and_b64 s[28:29], s[4:5], exec
	s_cselect_b32 s23, s27, s37
	s_cselect_b32 s31, s26, s36
	s_ashr_i32 s25, s24, 31
	s_lshl_b64 s[28:29], s[24:25], 19
	s_add_u32 s28, s45, s28
	s_addc_u32 s29, s46, s29
	s_and_b64 s[40:41], s[4:5], exec
	s_cselect_b32 s25, s29, s39
	s_cselect_b32 s62, s28, s38
	s_add_u32 s36, s36, 0x40080
	s_addc_u32 s37, s37, 0
	s_add_u32 s63, s38, 0x100
	s_addc_u32 s64, s39, 0
	s_mov_b32 s65, -2
	ds_read_b128 v[144:147], v163
	ds_read_b128 v[148:151], v163 offset:1024
	ds_read_b128 v[152:155], v163 offset:2048
	ds_read_b128 v[156:159], v163 offset:3072
	ds_read_b128 v[168:171], v164
	ds_read_b128 v[172:175], v164 offset:1024
	ds_read_b128 v[176:179], v164 offset:2048
	ds_read_b128 v[180:183], v164 offset:3072
	s_add_u32 s38, s36, 0xfffc0080
	s_addc_u32 s39, s37, -1
	s_cmp_eq_u32 s65, 12
	s_cselect_b32 s41, s23, s39
	s_cselect_b32 s40, s31, s38
	s_cselect_b32 s39, s25, s64
	s_cselect_b32 s38, s62, s63
	v_lshl_add_u64 v[160:161], s[36:37], 0, v[136:137]
	s_add_i32 m0, s50, 0xc000
	ds_read_b128 v[184:187], v165
	ds_read_b128 v[188:191], v165 offset:1024
	ds_read_b128 v[192:195], v165 offset:2048
	ds_read_b128 v[196:199], v165 offset:3072
	ds_read_b128 v[200:203], v165 offset:4096
	ds_read_b128 v[204:207], v165 offset:5120
	ds_read_b128 v[208:211], v165 offset:6144
	ds_read_b128 v[212:215], v165 offset:7168
	global_load_lds_dwordx4 v[160:161], off
	s_add_i32 m0, s50, 0xe000
	v_lshl_add_u64 v[160:161], s[36:37], 0, v[138:139]
	global_load_lds_dwordx4 v[160:161], off
	s_waitcnt vmcnt(8) lgkmcnt(0)
	s_barrier
	s_setprio 1
	v_mfma_f32_16x16x32_bf16 v[124:127], v[144:147], v[184:187], 0
	v_mfma_f32_16x16x32_bf16 v[124:127], v[148:151], v[188:191], v[124:127]
	v_mfma_f32_16x16x32_bf16 v[120:123], v[152:155], v[184:187], 0
	v_mfma_f32_16x16x32_bf16 v[120:123], v[156:159], v[188:191], v[120:123]
	v_mfma_f32_16x16x32_bf16 v[108:111], v[144:147], v[192:195], 0
	v_mfma_f32_16x16x32_bf16 v[108:111], v[148:151], v[196:199], v[108:111]
	v_mfma_f32_16x16x32_bf16 v[104:107], v[152:155], v[192:195], 0
	v_mfma_f32_16x16x32_bf16 v[104:107], v[156:159], v[196:199], v[104:107]
	v_mfma_f32_16x16x32_bf16 v[92:95], v[144:147], v[200:203], 0
	v_mfma_f32_16x16x32_bf16 v[92:95], v[148:151], v[204:207], v[92:95]
	v_mfma_f32_16x16x32_bf16 v[88:91], v[152:155], v[200:203], 0
	v_mfma_f32_16x16x32_bf16 v[88:91], v[156:159], v[204:207], v[88:91]
	v_mfma_f32_16x16x32_bf16 v[76:79], v[144:147], v[208:211], 0
	v_mfma_f32_16x16x32_bf16 v[76:79], v[148:151], v[212:215], v[76:79]
	v_mfma_f32_16x16x32_bf16 v[72:75], v[152:155], v[208:211], 0
	v_mfma_f32_16x16x32_bf16 v[72:75], v[156:159], v[212:215], v[72:75]
	v_mfma_f32_16x16x32_bf16 v[116:119], v[168:171], v[184:187], 0
	v_mfma_f32_16x16x32_bf16 v[116:119], v[172:175], v[188:191], v[116:119]
	v_mfma_f32_16x16x32_bf16 v[112:115], v[176:179], v[184:187], 0
	v_mfma_f32_16x16x32_bf16 v[112:115], v[180:183], v[188:191], v[112:115]
	v_mfma_f32_16x16x32_bf16 v[100:103], v[168:171], v[192:195], 0
	v_mfma_f32_16x16x32_bf16 v[100:103], v[172:175], v[196:199], v[100:103]
	v_mfma_f32_16x16x32_bf16 v[96:99], v[176:179], v[192:195], 0
	v_mfma_f32_16x16x32_bf16 v[96:99], v[180:183], v[196:199], v[96:99]
	v_mfma_f32_16x16x32_bf16 v[84:87], v[168:171], v[200:203], 0
	v_mfma_f32_16x16x32_bf16 v[84:87], v[172:175], v[204:207], v[84:87]
	v_mfma_f32_16x16x32_bf16 v[80:83], v[176:179], v[200:203], 0
	v_mfma_f32_16x16x32_bf16 v[80:83], v[180:183], v[204:207], v[80:83]
	s_setprio 2
	s_barrier
	v_mfma_f32_16x16x32_bf16 v[68:71], v[168:171], v[208:211], 0
	v_mfma_f32_16x16x32_bf16 v[68:71], v[172:175], v[212:215], v[68:71]
	v_mfma_f32_16x16x32_bf16 v[64:67], v[176:179], v[208:211], 0
	v_mfma_f32_16x16x32_bf16 v[64:67], v[180:183], v[212:215], v[64:67]
	s_setprio 2
	s_add_i32 s66, s59, s47
	v_lshl_add_u64 v[160:161], s[38:39], 0, v[132:133]
	s_mov_b32 m0, s66
	ds_read_b128 v[184:187], v165 offset:16384
	ds_read_b128 v[188:191], v165 offset:17408
	ds_read_b128 v[192:195], v165 offset:18432
	ds_read_b128 v[196:199], v165 offset:19456
	ds_read_b128 v[200:203], v165 offset:20480
	ds_read_b128 v[204:207], v165 offset:21504
	ds_read_b128 v[208:211], v165 offset:22528
	ds_read_b128 v[212:215], v165 offset:23552
	global_load_lds_dwordx4 v[160:161], off
	s_add_i32 m0, s66, 0x2000
	s_add_u32 s66, s38, 0x40000
	v_lshl_add_u64 v[216:217], s[38:39], 0, v[128:129]
	s_addc_u32 s67, s39, 0
	s_add_i32 s68, s60, s47
	global_load_lds_dwordx4 v[216:217], off
	v_lshl_add_u64 v[218:219], s[66:67], 0, v[132:133]
	s_mov_b32 m0, s68
	v_lshl_add_u64 v[220:221], s[40:41], 0, v[130:131]
	global_load_lds_dwordx4 v[218:219], off
	s_add_i32 m0, s68, 0x2000
	v_lshl_add_u64 v[218:219], s[66:67], 0, v[128:129]
	global_load_lds_dwordx4 v[218:219], off
	s_mov_b32 m0, s50
	v_lshl_add_u64 v[218:219], s[40:41], 0, v[134:135]
	global_load_lds_dwordx4 v[218:219], off
	s_mov_b32 m0, s51
	s_nop 0
	global_load_lds_dwordx4 v[220:221], off
	s_waitcnt vmcnt(8) lgkmcnt(0)
	s_barrier
	s_setprio 1
	v_mfma_f32_16x16x32_bf16 v[60:63], v[144:147], v[184:187], 0
	v_mfma_f32_16x16x32_bf16 v[60:63], v[148:151], v[188:191], v[60:63]
	v_mfma_f32_16x16x32_bf16 v[56:59], v[152:155], v[184:187], 0
	v_mfma_f32_16x16x32_bf16 v[56:59], v[156:159], v[188:191], v[56:59]
	v_mfma_f32_16x16x32_bf16 v[44:47], v[144:147], v[192:195], 0
	v_mfma_f32_16x16x32_bf16 v[44:47], v[148:151], v[196:199], v[44:47]
	v_mfma_f32_16x16x32_bf16 v[40:43], v[152:155], v[192:195], 0
	v_mfma_f32_16x16x32_bf16 v[40:43], v[156:159], v[196:199], v[40:43]
	v_mfma_f32_16x16x32_bf16 v[28:31], v[144:147], v[200:203], 0
	v_mfma_f32_16x16x32_bf16 v[28:31], v[148:151], v[204:207], v[28:31]
	v_mfma_f32_16x16x32_bf16 v[24:27], v[152:155], v[200:203], 0
	v_mfma_f32_16x16x32_bf16 v[24:27], v[156:159], v[204:207], v[24:27]
	v_mfma_f32_16x16x32_bf16 v[12:15], v[144:147], v[208:211], 0
	v_mfma_f32_16x16x32_bf16 v[12:15], v[148:151], v[212:215], v[12:15]
	v_mfma_f32_16x16x32_bf16 v[8:11], v[152:155], v[208:211], 0
	v_mfma_f32_16x16x32_bf16 v[8:11], v[156:159], v[212:215], v[8:11]
	v_mfma_f32_16x16x32_bf16 v[52:55], v[168:171], v[184:187], 0
	v_mfma_f32_16x16x32_bf16 v[52:55], v[172:175], v[188:191], v[52:55]
	v_mfma_f32_16x16x32_bf16 v[48:51], v[176:179], v[184:187], 0
	v_mfma_f32_16x16x32_bf16 v[48:51], v[180:183], v[188:191], v[48:51]
	v_mfma_f32_16x16x32_bf16 v[36:39], v[168:171], v[192:195], 0
	v_mfma_f32_16x16x32_bf16 v[36:39], v[172:175], v[196:199], v[36:39]
	v_mfma_f32_16x16x32_bf16 v[32:35], v[176:179], v[192:195], 0
	v_mfma_f32_16x16x32_bf16 v[32:35], v[180:183], v[196:199], v[32:35]
	v_mfma_f32_16x16x32_bf16 v[20:23], v[168:171], v[200:203], 0
	v_mfma_f32_16x16x32_bf16 v[20:23], v[172:175], v[204:207], v[20:23]
	v_mfma_f32_16x16x32_bf16 v[16:19], v[176:179], v[200:203], 0
	v_mfma_f32_16x16x32_bf16 v[16:19], v[180:183], v[204:207], v[16:19]
	s_setprio 2
	s_barrier
	v_mfma_f32_16x16x32_bf16 v[4:7], v[168:171], v[208:211], 0
	v_mfma_f32_16x16x32_bf16 v[4:7], v[172:175], v[212:215], v[4:7]
	v_mfma_f32_16x16x32_bf16 v[0:3], v[176:179], v[208:211], 0
	v_mfma_f32_16x16x32_bf16 v[0:3], v[180:183], v[212:215], v[0:3]
	s_setprio 0
	s_add_i32 s66, 0, 0x18000
	s_add_i32 s67, 0, 0x1c000
	v_add_u32_e32 v156, s66, v162
	v_add_u32_e32 v167, s67, v162
	ds_read_b128 v[144:147], v156
	ds_read_b128 v[148:151], v156 offset:1024
	ds_read_b128 v[152:155], v156 offset:2048
	ds_read_b128 v[156:159], v156 offset:3072
	ds_read_b128 v[168:171], v167
	ds_read_b128 v[172:175], v167 offset:1024
	ds_read_b128 v[176:179], v167 offset:2048
	ds_read_b128 v[180:183], v167 offset:3072
	s_add_u32 s40, s40, 0x40000
	s_addc_u32 s41, s41, 0
	s_mov_b32 m0, s54
	v_lshl_add_u64 v[222:223], s[40:41], 0, v[134:135]
	ds_read_b128 v[184:187], v165 offset:32768
	ds_read_b128 v[188:191], v165 offset:33792
	ds_read_b128 v[192:195], v165 offset:34816
	ds_read_b128 v[196:199], v165 offset:35840
	ds_read_b128 v[200:203], v165 offset:36864
	ds_read_b128 v[204:207], v165 offset:37888
	ds_read_b128 v[208:211], v165 offset:38912
	ds_read_b128 v[212:215], v165 offset:39936
	global_load_lds_dwordx4 v[222:223], off
	s_mov_b32 m0, s55
	v_lshl_add_u64 v[222:223], s[40:41], 0, v[130:131]
	global_load_lds_dwordx4 v[222:223], off
	s_waitcnt vmcnt(8) lgkmcnt(0)
	s_barrier
	s_setprio 1
	v_mfma_f32_16x16x32_bf16 v[124:127], v[144:147], v[184:187], v[124:127]
	v_mfma_f32_16x16x32_bf16 v[124:127], v[148:151], v[188:191], v[124:127]
	v_mfma_f32_16x16x32_bf16 v[120:123], v[152:155], v[184:187], v[120:123]
	v_mfma_f32_16x16x32_bf16 v[120:123], v[156:159], v[188:191], v[120:123]
	v_mfma_f32_16x16x32_bf16 v[108:111], v[144:147], v[192:195], v[108:111]
	v_mfma_f32_16x16x32_bf16 v[108:111], v[148:151], v[196:199], v[108:111]
	v_mfma_f32_16x16x32_bf16 v[104:107], v[152:155], v[192:195], v[104:107]
	v_mfma_f32_16x16x32_bf16 v[104:107], v[156:159], v[196:199], v[104:107]
	v_mfma_f32_16x16x32_bf16 v[92:95], v[144:147], v[200:203], v[92:95]
	v_mfma_f32_16x16x32_bf16 v[92:95], v[148:151], v[204:207], v[92:95]
	v_mfma_f32_16x16x32_bf16 v[88:91], v[152:155], v[200:203], v[88:91]
	v_mfma_f32_16x16x32_bf16 v[88:91], v[156:159], v[204:207], v[88:91]
	v_mfma_f32_16x16x32_bf16 v[76:79], v[144:147], v[208:211], v[76:79]
	v_mfma_f32_16x16x32_bf16 v[76:79], v[148:151], v[212:215], v[76:79]
	v_mfma_f32_16x16x32_bf16 v[72:75], v[152:155], v[208:211], v[72:75]
	v_mfma_f32_16x16x32_bf16 v[72:75], v[156:159], v[212:215], v[72:75]
	v_mfma_f32_16x16x32_bf16 v[116:119], v[168:171], v[184:187], v[116:119]
	v_mfma_f32_16x16x32_bf16 v[116:119], v[172:175], v[188:191], v[116:119]
	v_mfma_f32_16x16x32_bf16 v[112:115], v[176:179], v[184:187], v[112:115]
	v_mfma_f32_16x16x32_bf16 v[112:115], v[180:183], v[188:191], v[112:115]
	v_mfma_f32_16x16x32_bf16 v[100:103], v[168:171], v[192:195], v[100:103]
	v_mfma_f32_16x16x32_bf16 v[100:103], v[172:175], v[196:199], v[100:103]
	v_mfma_f32_16x16x32_bf16 v[96:99], v[176:179], v[192:195], v[96:99]
	v_mfma_f32_16x16x32_bf16 v[96:99], v[180:183], v[196:199], v[96:99]
	v_mfma_f32_16x16x32_bf16 v[84:87], v[168:171], v[200:203], v[84:87]
	v_mfma_f32_16x16x32_bf16 v[84:87], v[172:175], v[204:207], v[84:87]
	v_mfma_f32_16x16x32_bf16 v[80:83], v[176:179], v[200:203], v[80:83]
	v_mfma_f32_16x16x32_bf16 v[80:83], v[180:183], v[204:207], v[80:83]
	s_setprio 2
	s_barrier
	v_mfma_f32_16x16x32_bf16 v[68:71], v[168:171], v[208:211], v[68:71]
	v_mfma_f32_16x16x32_bf16 v[68:71], v[172:175], v[212:215], v[68:71]
	v_mfma_f32_16x16x32_bf16 v[64:67], v[176:179], v[208:211], v[64:67]
	v_mfma_f32_16x16x32_bf16 v[64:67], v[180:183], v[212:215], v[64:67]
	s_setprio 2
	s_add_i32 s40, s66, s47
	v_lshl_add_u64 v[160:161], v[160:161], 0, s[16:17]
	s_mov_b32 m0, s40
	ds_read_b128 v[184:187], v165 offset:49152
	ds_read_b128 v[188:191], v165 offset:50176
	ds_read_b128 v[192:195], v165 offset:51200
	ds_read_b128 v[196:199], v165 offset:52224
	ds_read_b128 v[200:203], v165 offset:53248
	ds_read_b128 v[204:207], v165 offset:54272
	ds_read_b128 v[208:211], v165 offset:55296
	ds_read_b128 v[212:215], v165 offset:56320
	global_load_lds_dwordx4 v[160:161], off
	s_add_i32 m0, s40, 0x2000
	s_add_u32 s38, s38, 0x40080
	v_lshl_add_u64 v[160:161], v[216:217], 0, s[16:17]
	s_addc_u32 s39, s39, 0
	s_add_i32 s40, s67, s47
	global_load_lds_dwordx4 v[160:161], off
	s_mov_b32 m0, s40
	v_lshl_add_u64 v[160:161], s[38:39], 0, v[132:133]
	global_load_lds_dwordx4 v[160:161], off
	s_add_i32 m0, s40, 0x2000
	v_lshl_add_u64 v[160:161], s[38:39], 0, v[128:129]
	global_load_lds_dwordx4 v[160:161], off
	s_mov_b32 m0, s57
	v_lshl_add_u64 v[160:161], v[218:219], 0, s[16:17]
	global_load_lds_dwordx4 v[160:161], off
	s_mov_b32 m0, s58
	v_lshl_add_u64 v[160:161], v[220:221], 0, s[16:17]
	global_load_lds_dwordx4 v[160:161], off
	s_waitcnt vmcnt(8) lgkmcnt(0)
	s_barrier
	s_setprio 1
	v_mfma_f32_16x16x32_bf16 v[60:63], v[144:147], v[184:187], v[60:63]
	v_mfma_f32_16x16x32_bf16 v[60:63], v[148:151], v[188:191], v[60:63]
	v_mfma_f32_16x16x32_bf16 v[56:59], v[152:155], v[184:187], v[56:59]
	v_mfma_f32_16x16x32_bf16 v[56:59], v[156:159], v[188:191], v[56:59]
	v_mfma_f32_16x16x32_bf16 v[44:47], v[144:147], v[192:195], v[44:47]
	v_mfma_f32_16x16x32_bf16 v[44:47], v[148:151], v[196:199], v[44:47]
	v_mfma_f32_16x16x32_bf16 v[40:43], v[152:155], v[192:195], v[40:43]
	v_mfma_f32_16x16x32_bf16 v[40:43], v[156:159], v[196:199], v[40:43]
	v_mfma_f32_16x16x32_bf16 v[28:31], v[144:147], v[200:203], v[28:31]
	v_mfma_f32_16x16x32_bf16 v[28:31], v[148:151], v[204:207], v[28:31]
	v_mfma_f32_16x16x32_bf16 v[24:27], v[152:155], v[200:203], v[24:27]
	v_mfma_f32_16x16x32_bf16 v[24:27], v[156:159], v[204:207], v[24:27]
	v_mfma_f32_16x16x32_bf16 v[12:15], v[144:147], v[208:211], v[12:15]
	v_mfma_f32_16x16x32_bf16 v[12:15], v[148:151], v[212:215], v[12:15]
	v_mfma_f32_16x16x32_bf16 v[8:11], v[152:155], v[208:211], v[8:11]
	v_mfma_f32_16x16x32_bf16 v[8:11], v[156:159], v[212:215], v[8:11]
	v_mfma_f32_16x16x32_bf16 v[52:55], v[168:171], v[184:187], v[52:55]
	v_mfma_f32_16x16x32_bf16 v[52:55], v[172:175], v[188:191], v[52:55]
	v_mfma_f32_16x16x32_bf16 v[48:51], v[176:179], v[184:187], v[48:51]
	v_mfma_f32_16x16x32_bf16 v[48:51], v[180:183], v[188:191], v[48:51]
	v_mfma_f32_16x16x32_bf16 v[36:39], v[168:171], v[192:195], v[36:39]
	v_mfma_f32_16x16x32_bf16 v[36:39], v[172:175], v[196:199], v[36:39]
	v_mfma_f32_16x16x32_bf16 v[32:35], v[176:179], v[192:195], v[32:35]
	v_mfma_f32_16x16x32_bf16 v[32:35], v[180:183], v[196:199], v[32:35]
	v_mfma_f32_16x16x32_bf16 v[20:23], v[168:171], v[200:203], v[20:23]
	v_mfma_f32_16x16x32_bf16 v[20:23], v[172:175], v[204:207], v[20:23]
	v_mfma_f32_16x16x32_bf16 v[16:19], v[176:179], v[200:203], v[16:19]
	v_mfma_f32_16x16x32_bf16 v[16:19], v[180:183], v[204:207], v[16:19]
	s_setprio 2
	s_barrier
	v_mfma_f32_16x16x32_bf16 v[4:7], v[168:171], v[208:211], v[4:7]
	v_mfma_f32_16x16x32_bf16 v[4:7], v[172:175], v[212:215], v[4:7]
	v_mfma_f32_16x16x32_bf16 v[0:3], v[176:179], v[208:211], v[0:3]
	v_mfma_f32_16x16x32_bf16 v[0:3], v[180:183], v[212:215], v[0:3]
	s_setprio 0
	s_add_i32 s65, s65, 2
	s_add_u32 s36, s36, 0x100
	s_addc_u32 s37, s37, 0
	s_add_u32 s63, s63, 0x100
	s_addc_u32 s64, s64, 0
	s_cmp_gt_u32 s65, 13
.LBB0_784:
	ds_read_b128 v[144:147], v163
	ds_read_b128 v[148:151], v163 offset:1024
	ds_read_b128 v[152:155], v163 offset:2048
	ds_read_b128 v[156:159], v163 offset:3072
	ds_read_b128 v[168:171], v164
	ds_read_b128 v[172:175], v164 offset:1024
	ds_read_b128 v[176:179], v164 offset:2048
	ds_read_b128 v[180:183], v164 offset:3072
	s_add_u32 s38, s36, 0xfffc0080
	s_addc_u32 s39, s37, -1
	s_cmp_eq_u32 s65, 12
	s_cselect_b32 s41, s23, s39
	s_cselect_b32 s40, s31, s38
	s_cselect_b32 s39, s25, s64
	s_cselect_b32 s38, s62, s63
	v_lshl_add_u64 v[160:161], s[36:37], 0, v[136:137]
	s_add_i32 m0, s50, 0xc000
	ds_read_b128 v[184:187], v165
	ds_read_b128 v[188:191], v165 offset:1024
	ds_read_b128 v[192:195], v165 offset:2048
	ds_read_b128 v[196:199], v165 offset:3072
	ds_read_b128 v[200:203], v165 offset:4096
	ds_read_b128 v[204:207], v165 offset:5120
	ds_read_b128 v[208:211], v165 offset:6144
	ds_read_b128 v[212:215], v165 offset:7168
	global_load_lds_dwordx4 v[160:161], off
	s_add_i32 m0, s50, 0xe000
	v_lshl_add_u64 v[160:161], s[36:37], 0, v[138:139]
	global_load_lds_dwordx4 v[160:161], off
	s_waitcnt vmcnt(8) lgkmcnt(0)
	s_barrier
	s_setprio 1
	v_mfma_f32_16x16x32_bf16 v[124:127], v[144:147], v[184:187], v[124:127]
	v_mfma_f32_16x16x32_bf16 v[124:127], v[148:151], v[188:191], v[124:127]
	v_mfma_f32_16x16x32_bf16 v[120:123], v[152:155], v[184:187], v[120:123]
	v_mfma_f32_16x16x32_bf16 v[120:123], v[156:159], v[188:191], v[120:123]
	v_mfma_f32_16x16x32_bf16 v[108:111], v[144:147], v[192:195], v[108:111]
	v_mfma_f32_16x16x32_bf16 v[108:111], v[148:151], v[196:199], v[108:111]
	v_mfma_f32_16x16x32_bf16 v[104:107], v[152:155], v[192:195], v[104:107]
	v_mfma_f32_16x16x32_bf16 v[104:107], v[156:159], v[196:199], v[104:107]
	v_mfma_f32_16x16x32_bf16 v[92:95], v[144:147], v[200:203], v[92:95]
	v_mfma_f32_16x16x32_bf16 v[92:95], v[148:151], v[204:207], v[92:95]
	v_mfma_f32_16x16x32_bf16 v[88:91], v[152:155], v[200:203], v[88:91]
	v_mfma_f32_16x16x32_bf16 v[88:91], v[156:159], v[204:207], v[88:91]
	v_mfma_f32_16x16x32_bf16 v[76:79], v[144:147], v[208:211], v[76:79]
	v_mfma_f32_16x16x32_bf16 v[76:79], v[148:151], v[212:215], v[76:79]
	v_mfma_f32_16x16x32_bf16 v[72:75], v[152:155], v[208:211], v[72:75]
	v_mfma_f32_16x16x32_bf16 v[72:75], v[156:159], v[212:215], v[72:75]
	v_mfma_f32_16x16x32_bf16 v[116:119], v[168:171], v[184:187], v[116:119]
	v_mfma_f32_16x16x32_bf16 v[116:119], v[172:175], v[188:191], v[116:119]
	v_mfma_f32_16x16x32_bf16 v[112:115], v[176:179], v[184:187], v[112:115]
	v_mfma_f32_16x16x32_bf16 v[112:115], v[180:183], v[188:191], v[112:115]
	v_mfma_f32_16x16x32_bf16 v[100:103], v[168:171], v[192:195], v[100:103]
	v_mfma_f32_16x16x32_bf16 v[100:103], v[172:175], v[196:199], v[100:103]
	v_mfma_f32_16x16x32_bf16 v[96:99], v[176:179], v[192:195], v[96:99]
	v_mfma_f32_16x16x32_bf16 v[96:99], v[180:183], v[196:199], v[96:99]
	v_mfma_f32_16x16x32_bf16 v[84:87], v[168:171], v[200:203], v[84:87]
	v_mfma_f32_16x16x32_bf16 v[84:87], v[172:175], v[204:207], v[84:87]
	v_mfma_f32_16x16x32_bf16 v[80:83], v[176:179], v[200:203], v[80:83]
	v_mfma_f32_16x16x32_bf16 v[80:83], v[180:183], v[204:207], v[80:83]
	s_setprio 2
	s_barrier
	v_mfma_f32_16x16x32_bf16 v[68:71], v[168:171], v[208:211], v[68:71]
	v_mfma_f32_16x16x32_bf16 v[68:71], v[172:175], v[212:215], v[68:71]
	v_mfma_f32_16x16x32_bf16 v[64:67], v[176:179], v[208:211], v[64:67]
	v_mfma_f32_16x16x32_bf16 v[64:67], v[180:183], v[212:215], v[64:67]
	s_setprio 2
	s_add_i32 s66, s59, s47
	v_lshl_add_u64 v[160:161], s[38:39], 0, v[132:133]
	s_mov_b32 m0, s66
	ds_read_b128 v[184:187], v165 offset:16384
	ds_read_b128 v[188:191], v165 offset:17408
	ds_read_b128 v[192:195], v165 offset:18432
	ds_read_b128 v[196:199], v165 offset:19456
	ds_read_b128 v[200:203], v165 offset:20480
	ds_read_b128 v[204:207], v165 offset:21504
	ds_read_b128 v[208:211], v165 offset:22528
	ds_read_b128 v[212:215], v165 offset:23552
	global_load_lds_dwordx4 v[160:161], off
	s_add_i32 m0, s66, 0x2000
	s_add_u32 s66, s38, 0x40000
	v_lshl_add_u64 v[216:217], s[38:39], 0, v[128:129]
	s_addc_u32 s67, s39, 0
	s_add_i32 s68, s60, s47
	global_load_lds_dwordx4 v[216:217], off
	v_lshl_add_u64 v[218:219], s[66:67], 0, v[132:133]
	s_mov_b32 m0, s68
	v_lshl_add_u64 v[220:221], s[40:41], 0, v[130:131]
	global_load_lds_dwordx4 v[218:219], off
	s_add_i32 m0, s68, 0x2000
	v_lshl_add_u64 v[218:219], s[66:67], 0, v[128:129]
	global_load_lds_dwordx4 v[218:219], off
	s_mov_b32 m0, s50
	v_lshl_add_u64 v[218:219], s[40:41], 0, v[134:135]
	global_load_lds_dwordx4 v[218:219], off
	s_mov_b32 m0, s51
	s_nop 0
	global_load_lds_dwordx4 v[220:221], off
	s_waitcnt vmcnt(8) lgkmcnt(0)
	s_barrier
	s_setprio 1
	v_mfma_f32_16x16x32_bf16 v[60:63], v[144:147], v[184:187], v[60:63]
	v_mfma_f32_16x16x32_bf16 v[60:63], v[148:151], v[188:191], v[60:63]
	v_mfma_f32_16x16x32_bf16 v[56:59], v[152:155], v[184:187], v[56:59]
	v_mfma_f32_16x16x32_bf16 v[56:59], v[156:159], v[188:191], v[56:59]
	v_mfma_f32_16x16x32_bf16 v[44:47], v[144:147], v[192:195], v[44:47]
	v_mfma_f32_16x16x32_bf16 v[44:47], v[148:151], v[196:199], v[44:47]
	v_mfma_f32_16x16x32_bf16 v[40:43], v[152:155], v[192:195], v[40:43]
	v_mfma_f32_16x16x32_bf16 v[40:43], v[156:159], v[196:199], v[40:43]
	v_mfma_f32_16x16x32_bf16 v[28:31], v[144:147], v[200:203], v[28:31]
	v_mfma_f32_16x16x32_bf16 v[28:31], v[148:151], v[204:207], v[28:31]
	v_mfma_f32_16x16x32_bf16 v[24:27], v[152:155], v[200:203], v[24:27]
	v_mfma_f32_16x16x32_bf16 v[24:27], v[156:159], v[204:207], v[24:27]
	v_mfma_f32_16x16x32_bf16 v[12:15], v[144:147], v[208:211], v[12:15]
	v_mfma_f32_16x16x32_bf16 v[12:15], v[148:151], v[212:215], v[12:15]
	v_mfma_f32_16x16x32_bf16 v[8:11], v[152:155], v[208:211], v[8:11]
	v_mfma_f32_16x16x32_bf16 v[8:11], v[156:159], v[212:215], v[8:11]
	v_mfma_f32_16x16x32_bf16 v[52:55], v[168:171], v[184:187], v[52:55]
	v_mfma_f32_16x16x32_bf16 v[52:55], v[172:175], v[188:191], v[52:55]
	v_mfma_f32_16x16x32_bf16 v[48:51], v[176:179], v[184:187], v[48:51]
	v_mfma_f32_16x16x32_bf16 v[48:51], v[180:183], v[188:191], v[48:51]
	v_mfma_f32_16x16x32_bf16 v[36:39], v[168:171], v[192:195], v[36:39]
	v_mfma_f32_16x16x32_bf16 v[36:39], v[172:175], v[196:199], v[36:39]
	v_mfma_f32_16x16x32_bf16 v[32:35], v[176:179], v[192:195], v[32:35]
	v_mfma_f32_16x16x32_bf16 v[32:35], v[180:183], v[196:199], v[32:35]
	v_mfma_f32_16x16x32_bf16 v[20:23], v[168:171], v[200:203], v[20:23]
	v_mfma_f32_16x16x32_bf16 v[20:23], v[172:175], v[204:207], v[20:23]
	v_mfma_f32_16x16x32_bf16 v[16:19], v[176:179], v[200:203], v[16:19]
	v_mfma_f32_16x16x32_bf16 v[16:19], v[180:183], v[204:207], v[16:19]
	s_setprio 2
	s_barrier
	v_mfma_f32_16x16x32_bf16 v[4:7], v[168:171], v[208:211], v[4:7]
	v_mfma_f32_16x16x32_bf16 v[4:7], v[172:175], v[212:215], v[4:7]
	v_mfma_f32_16x16x32_bf16 v[0:3], v[176:179], v[208:211], v[0:3]
	v_mfma_f32_16x16x32_bf16 v[0:3], v[180:183], v[212:215], v[0:3]
	s_setprio 0
	s_add_i32 s66, 0, 0x18000
	s_add_i32 s67, 0, 0x1c000
	v_add_u32_e32 v156, s66, v162
	v_add_u32_e32 v167, s67, v162
	ds_read_b128 v[144:147], v156
	ds_read_b128 v[148:151], v156 offset:1024
	ds_read_b128 v[152:155], v156 offset:2048
	ds_read_b128 v[156:159], v156 offset:3072
	ds_read_b128 v[168:171], v167
	ds_read_b128 v[172:175], v167 offset:1024
	ds_read_b128 v[176:179], v167 offset:2048
	ds_read_b128 v[180:183], v167 offset:3072
	s_add_u32 s40, s40, 0x40000
	s_addc_u32 s41, s41, 0
	s_mov_b32 m0, s54
	v_lshl_add_u64 v[222:223], s[40:41], 0, v[134:135]
	ds_read_b128 v[184:187], v165 offset:32768
	ds_read_b128 v[188:191], v165 offset:33792
	ds_read_b128 v[192:195], v165 offset:34816
	ds_read_b128 v[196:199], v165 offset:35840
	ds_read_b128 v[200:203], v165 offset:36864
	ds_read_b128 v[204:207], v165 offset:37888
	ds_read_b128 v[208:211], v165 offset:38912
	ds_read_b128 v[212:215], v165 offset:39936
	global_load_lds_dwordx4 v[222:223], off
	s_mov_b32 m0, s55
	v_lshl_add_u64 v[222:223], s[40:41], 0, v[130:131]
	global_load_lds_dwordx4 v[222:223], off
	s_waitcnt vmcnt(8) lgkmcnt(0)
	s_barrier
	s_setprio 1
	v_mfma_f32_16x16x32_bf16 v[124:127], v[144:147], v[184:187], v[124:127]
	v_mfma_f32_16x16x32_bf16 v[124:127], v[148:151], v[188:191], v[124:127]
	v_mfma_f32_16x16x32_bf16 v[120:123], v[152:155], v[184:187], v[120:123]
	v_mfma_f32_16x16x32_bf16 v[120:123], v[156:159], v[188:191], v[120:123]
	v_mfma_f32_16x16x32_bf16 v[108:111], v[144:147], v[192:195], v[108:111]
	v_mfma_f32_16x16x32_bf16 v[108:111], v[148:151], v[196:199], v[108:111]
	v_mfma_f32_16x16x32_bf16 v[104:107], v[152:155], v[192:195], v[104:107]
	v_mfma_f32_16x16x32_bf16 v[104:107], v[156:159], v[196:199], v[104:107]
	v_mfma_f32_16x16x32_bf16 v[92:95], v[144:147], v[200:203], v[92:95]
	v_mfma_f32_16x16x32_bf16 v[92:95], v[148:151], v[204:207], v[92:95]
	v_mfma_f32_16x16x32_bf16 v[88:91], v[152:155], v[200:203], v[88:91]
	v_mfma_f32_16x16x32_bf16 v[88:91], v[156:159], v[204:207], v[88:91]
	v_mfma_f32_16x16x32_bf16 v[76:79], v[144:147], v[208:211], v[76:79]
	v_mfma_f32_16x16x32_bf16 v[76:79], v[148:151], v[212:215], v[76:79]
	v_mfma_f32_16x16x32_bf16 v[72:75], v[152:155], v[208:211], v[72:75]
	v_mfma_f32_16x16x32_bf16 v[72:75], v[156:159], v[212:215], v[72:75]
	v_mfma_f32_16x16x32_bf16 v[116:119], v[168:171], v[184:187], v[116:119]
	v_mfma_f32_16x16x32_bf16 v[116:119], v[172:175], v[188:191], v[116:119]
	v_mfma_f32_16x16x32_bf16 v[112:115], v[176:179], v[184:187], v[112:115]
	v_mfma_f32_16x16x32_bf16 v[112:115], v[180:183], v[188:191], v[112:115]
	v_mfma_f32_16x16x32_bf16 v[100:103], v[168:171], v[192:195], v[100:103]
	v_mfma_f32_16x16x32_bf16 v[100:103], v[172:175], v[196:199], v[100:103]
	v_mfma_f32_16x16x32_bf16 v[96:99], v[176:179], v[192:195], v[96:99]
	v_mfma_f32_16x16x32_bf16 v[96:99], v[180:183], v[196:199], v[96:99]
	v_mfma_f32_16x16x32_bf16 v[84:87], v[168:171], v[200:203], v[84:87]
	v_mfma_f32_16x16x32_bf16 v[84:87], v[172:175], v[204:207], v[84:87]
	v_mfma_f32_16x16x32_bf16 v[80:83], v[176:179], v[200:203], v[80:83]
	v_mfma_f32_16x16x32_bf16 v[80:83], v[180:183], v[204:207], v[80:83]
	s_setprio 2
	s_barrier
	v_mfma_f32_16x16x32_bf16 v[68:71], v[168:171], v[208:211], v[68:71]
	v_mfma_f32_16x16x32_bf16 v[68:71], v[172:175], v[212:215], v[68:71]
	v_mfma_f32_16x16x32_bf16 v[64:67], v[176:179], v[208:211], v[64:67]
	v_mfma_f32_16x16x32_bf16 v[64:67], v[180:183], v[212:215], v[64:67]
	s_setprio 2
	s_add_i32 s40, s66, s47
	v_lshl_add_u64 v[160:161], v[160:161], 0, s[16:17]
	s_mov_b32 m0, s40
	ds_read_b128 v[184:187], v165 offset:49152
	ds_read_b128 v[188:191], v165 offset:50176
	ds_read_b128 v[192:195], v165 offset:51200
	ds_read_b128 v[196:199], v165 offset:52224
	ds_read_b128 v[200:203], v165 offset:53248
	ds_read_b128 v[204:207], v165 offset:54272
	ds_read_b128 v[208:211], v165 offset:55296
	ds_read_b128 v[212:215], v165 offset:56320
	global_load_lds_dwordx4 v[160:161], off
	s_add_i32 m0, s40, 0x2000
	s_add_u32 s38, s38, 0x40080
	v_lshl_add_u64 v[160:161], v[216:217], 0, s[16:17]
	s_addc_u32 s39, s39, 0
	s_add_i32 s40, s67, s47
	global_load_lds_dwordx4 v[160:161], off
	s_mov_b32 m0, s40
	v_lshl_add_u64 v[160:161], s[38:39], 0, v[132:133]
	global_load_lds_dwordx4 v[160:161], off
	s_add_i32 m0, s40, 0x2000
	v_lshl_add_u64 v[160:161], s[38:39], 0, v[128:129]
	global_load_lds_dwordx4 v[160:161], off
	s_mov_b32 m0, s57
	v_lshl_add_u64 v[160:161], v[218:219], 0, s[16:17]
	global_load_lds_dwordx4 v[160:161], off
	s_mov_b32 m0, s58
	v_lshl_add_u64 v[160:161], v[220:221], 0, s[16:17]
	global_load_lds_dwordx4 v[160:161], off
	s_waitcnt vmcnt(8) lgkmcnt(0)
	s_barrier
	s_setprio 1
	v_mfma_f32_16x16x32_bf16 v[60:63], v[144:147], v[184:187], v[60:63]
	v_mfma_f32_16x16x32_bf16 v[60:63], v[148:151], v[188:191], v[60:63]
	v_mfma_f32_16x16x32_bf16 v[56:59], v[152:155], v[184:187], v[56:59]
	v_mfma_f32_16x16x32_bf16 v[56:59], v[156:159], v[188:191], v[56:59]
	v_mfma_f32_16x16x32_bf16 v[44:47], v[144:147], v[192:195], v[44:47]
	v_mfma_f32_16x16x32_bf16 v[44:47], v[148:151], v[196:199], v[44:47]
	v_mfma_f32_16x16x32_bf16 v[40:43], v[152:155], v[192:195], v[40:43]
	v_mfma_f32_16x16x32_bf16 v[40:43], v[156:159], v[196:199], v[40:43]
	v_mfma_f32_16x16x32_bf16 v[28:31], v[144:147], v[200:203], v[28:31]
	v_mfma_f32_16x16x32_bf16 v[28:31], v[148:151], v[204:207], v[28:31]
	v_mfma_f32_16x16x32_bf16 v[24:27], v[152:155], v[200:203], v[24:27]
	v_mfma_f32_16x16x32_bf16 v[24:27], v[156:159], v[204:207], v[24:27]
	v_mfma_f32_16x16x32_bf16 v[12:15], v[144:147], v[208:211], v[12:15]
	v_mfma_f32_16x16x32_bf16 v[12:15], v[148:151], v[212:215], v[12:15]
	v_mfma_f32_16x16x32_bf16 v[8:11], v[152:155], v[208:211], v[8:11]
	v_mfma_f32_16x16x32_bf16 v[8:11], v[156:159], v[212:215], v[8:11]
	v_mfma_f32_16x16x32_bf16 v[52:55], v[168:171], v[184:187], v[52:55]
	v_mfma_f32_16x16x32_bf16 v[52:55], v[172:175], v[188:191], v[52:55]
	v_mfma_f32_16x16x32_bf16 v[48:51], v[176:179], v[184:187], v[48:51]
	v_mfma_f32_16x16x32_bf16 v[48:51], v[180:183], v[188:191], v[48:51]
	v_mfma_f32_16x16x32_bf16 v[36:39], v[168:171], v[192:195], v[36:39]
	v_mfma_f32_16x16x32_bf16 v[36:39], v[172:175], v[196:199], v[36:39]
	v_mfma_f32_16x16x32_bf16 v[32:35], v[176:179], v[192:195], v[32:35]
	v_mfma_f32_16x16x32_bf16 v[32:35], v[180:183], v[196:199], v[32:35]
	v_mfma_f32_16x16x32_bf16 v[20:23], v[168:171], v[200:203], v[20:23]
	v_mfma_f32_16x16x32_bf16 v[20:23], v[172:175], v[204:207], v[20:23]
	v_mfma_f32_16x16x32_bf16 v[16:19], v[176:179], v[200:203], v[16:19]
	v_mfma_f32_16x16x32_bf16 v[16:19], v[180:183], v[204:207], v[16:19]
	s_setprio 2
	s_barrier
	v_mfma_f32_16x16x32_bf16 v[4:7], v[168:171], v[208:211], v[4:7]
	v_mfma_f32_16x16x32_bf16 v[4:7], v[172:175], v[212:215], v[4:7]
	v_mfma_f32_16x16x32_bf16 v[0:3], v[176:179], v[208:211], v[0:3]
	v_mfma_f32_16x16x32_bf16 v[0:3], v[180:183], v[212:215], v[0:3]
	s_setprio 0
	s_add_i32 s65, s65, 2
	s_add_u32 s36, s36, 0x100
	s_addc_u32 s37, s37, 0
	s_add_u32 s63, s63, 0x100
	s_addc_u32 s64, s64, 0
	s_cmp_gt_u32 s65, 13
	s_cbranch_scc0 .LBB0_784

.LBB0_865:
	s_add_u32 s62, s28, 0x100
	s_addc_u32 s63, s29, 0
	s_mov_b32 s64, -2
	ds_read_b128 v[120:123], v233
	ds_read_b128 v[124:127], v233 offset:1024
	ds_read_b128 v[136:139], v233 offset:2048
	ds_read_b128 v[140:143], v233 offset:3072
	ds_read_b128 v[144:147], v234
	ds_read_b128 v[148:151], v234 offset:1024
	ds_read_b128 v[152:155], v234 offset:2048
	ds_read_b128 v[156:159], v234 offset:3072
	s_add_u32 s28, s26, 0x100
	s_addc_u32 s29, s27, 0
	s_cmp_eq_u32 s64, 40
	s_cselect_b32 s37, s7, s29
	s_cselect_b32 s36, s6, s28
	s_cselect_b32 s31, s25, s63
	s_cselect_b32 s30, s24, s62
	v_lshl_add_u64 v[208:209], s[26:27], 0, v[192:193]
	s_add_i32 m0, s44, 0xc000
	ds_read_b128 v[160:163], v235
	ds_read_b128 v[164:167], v235 offset:1024
	ds_read_b128 v[168:171], v235 offset:2048
	ds_read_b128 v[172:175], v235 offset:3072
	ds_read_b128 v[176:179], v235 offset:4096
	ds_read_b128 v[180:183], v235 offset:5120
	ds_read_b128 v[200:203], v235 offset:6144
	ds_read_b128 v[204:207], v235 offset:7168
	global_load_lds_dwordx4 v[208:209], off
	s_add_i32 m0, s44, 0xe000
	v_lshl_add_u64 v[208:209], s[26:27], 0, v[194:195]
	global_load_lds_dwordx4 v[208:209], off
	s_waitcnt vmcnt(8) lgkmcnt(0)
	s_barrier
	s_setprio 1
	v_mfma_f32_16x16x32_bf16 v[132:135], v[120:123], v[160:163], 0
	v_mfma_f32_16x16x32_bf16 v[132:135], v[124:127], v[164:167], v[132:135]
	v_mfma_f32_16x16x32_bf16 v[128:131], v[136:139], v[160:163], 0
	v_mfma_f32_16x16x32_bf16 v[128:131], v[140:143], v[164:167], v[128:131]
	v_mfma_f32_16x16x32_bf16 v[108:111], v[120:123], v[168:171], 0
	v_mfma_f32_16x16x32_bf16 v[108:111], v[124:127], v[172:175], v[108:111]
	v_mfma_f32_16x16x32_bf16 v[104:107], v[136:139], v[168:171], 0
	v_mfma_f32_16x16x32_bf16 v[104:107], v[140:143], v[172:175], v[104:107]
	v_mfma_f32_16x16x32_bf16 v[92:95], v[120:123], v[176:179], 0
	v_mfma_f32_16x16x32_bf16 v[92:95], v[124:127], v[180:183], v[92:95]
	v_mfma_f32_16x16x32_bf16 v[88:91], v[136:139], v[176:179], 0
	v_mfma_f32_16x16x32_bf16 v[88:91], v[140:143], v[180:183], v[88:91]
	v_mfma_f32_16x16x32_bf16 v[76:79], v[120:123], v[200:203], 0
	v_mfma_f32_16x16x32_bf16 v[76:79], v[124:127], v[204:207], v[76:79]
	v_mfma_f32_16x16x32_bf16 v[72:75], v[136:139], v[200:203], 0
	v_mfma_f32_16x16x32_bf16 v[72:75], v[140:143], v[204:207], v[72:75]
	v_mfma_f32_16x16x32_bf16 v[116:119], v[144:147], v[160:163], 0
	v_mfma_f32_16x16x32_bf16 v[116:119], v[148:151], v[164:167], v[116:119]
	v_mfma_f32_16x16x32_bf16 v[112:115], v[152:155], v[160:163], 0
	v_mfma_f32_16x16x32_bf16 v[112:115], v[156:159], v[164:167], v[112:115]
	v_mfma_f32_16x16x32_bf16 v[100:103], v[144:147], v[168:171], 0
	v_mfma_f32_16x16x32_bf16 v[100:103], v[148:151], v[172:175], v[100:103]
	v_mfma_f32_16x16x32_bf16 v[96:99], v[152:155], v[168:171], 0
	v_mfma_f32_16x16x32_bf16 v[96:99], v[156:159], v[172:175], v[96:99]
	v_mfma_f32_16x16x32_bf16 v[84:87], v[144:147], v[176:179], 0
	v_mfma_f32_16x16x32_bf16 v[84:87], v[148:151], v[180:183], v[84:87]
	v_mfma_f32_16x16x32_bf16 v[80:83], v[152:155], v[176:179], 0
	v_mfma_f32_16x16x32_bf16 v[80:83], v[156:159], v[180:183], v[80:83]
	s_setprio 2
	s_barrier
	v_mfma_f32_16x16x32_bf16 v[68:71], v[144:147], v[200:203], 0
	v_mfma_f32_16x16x32_bf16 v[68:71], v[148:151], v[204:207], v[68:71]
	v_mfma_f32_16x16x32_bf16 v[64:67], v[152:155], v[200:203], 0
	v_mfma_f32_16x16x32_bf16 v[64:67], v[156:159], v[204:207], v[64:67]
	s_setprio 2
	s_add_i32 s26, s56, s43
	v_lshl_add_u64 v[208:209], s[30:31], 0, v[186:187]
	s_mov_b32 m0, s26
	ds_read_b128 v[160:163], v235 offset:16384
	ds_read_b128 v[164:167], v235 offset:17408
	ds_read_b128 v[168:171], v235 offset:18432
	ds_read_b128 v[172:175], v235 offset:19456
	ds_read_b128 v[176:179], v235 offset:20480
	ds_read_b128 v[180:183], v235 offset:21504
	ds_read_b128 v[200:203], v235 offset:22528
	ds_read_b128 v[204:207], v235 offset:23552
	global_load_lds_dwordx4 v[208:209], off
	s_add_i32 m0, s26, 0x2000
	s_add_u32 s26, s30, 0xb0000
	v_lshl_add_u64 v[210:211], s[30:31], 0, v[190:191]
	s_addc_u32 s27, s31, 0
	s_add_i32 s65, s57, s43
	global_load_lds_dwordx4 v[210:211], off
	v_lshl_add_u64 v[212:213], s[26:27], 0, v[186:187]
	s_mov_b32 m0, s65
	v_lshl_add_u64 v[214:215], s[36:37], 0, v[188:189]
	global_load_lds_dwordx4 v[212:213], off
	s_add_i32 m0, s65, 0x2000
	v_lshl_add_u64 v[212:213], s[26:27], 0, v[190:191]
	global_load_lds_dwordx4 v[212:213], off
	s_mov_b32 m0, s44
	v_lshl_add_u64 v[212:213], s[36:37], 0, v[184:185]
	global_load_lds_dwordx4 v[212:213], off
	s_mov_b32 m0, s45
	s_nop 0
	global_load_lds_dwordx4 v[214:215], off
	s_waitcnt vmcnt(8) lgkmcnt(0)
	s_barrier
	s_setprio 1
	v_mfma_f32_16x16x32_bf16 v[60:63], v[120:123], v[160:163], 0
	v_mfma_f32_16x16x32_bf16 v[60:63], v[124:127], v[164:167], v[60:63]
	v_mfma_f32_16x16x32_bf16 v[56:59], v[136:139], v[160:163], 0
	v_mfma_f32_16x16x32_bf16 v[56:59], v[140:143], v[164:167], v[56:59]
	v_mfma_f32_16x16x32_bf16 v[44:47], v[120:123], v[168:171], 0
	v_mfma_f32_16x16x32_bf16 v[44:47], v[124:127], v[172:175], v[44:47]
	v_mfma_f32_16x16x32_bf16 v[40:43], v[136:139], v[168:171], 0
	v_mfma_f32_16x16x32_bf16 v[40:43], v[140:143], v[172:175], v[40:43]
	v_mfma_f32_16x16x32_bf16 v[28:31], v[120:123], v[176:179], 0
	v_mfma_f32_16x16x32_bf16 v[28:31], v[124:127], v[180:183], v[28:31]
	v_mfma_f32_16x16x32_bf16 v[24:27], v[136:139], v[176:179], 0
	v_mfma_f32_16x16x32_bf16 v[24:27], v[140:143], v[180:183], v[24:27]
	v_mfma_f32_16x16x32_bf16 v[12:15], v[120:123], v[200:203], 0
	v_mfma_f32_16x16x32_bf16 v[12:15], v[124:127], v[204:207], v[12:15]
	v_mfma_f32_16x16x32_bf16 v[8:11], v[136:139], v[200:203], 0
	v_mfma_f32_16x16x32_bf16 v[8:11], v[140:143], v[204:207], v[8:11]
	v_mfma_f32_16x16x32_bf16 v[52:55], v[144:147], v[160:163], 0
	v_mfma_f32_16x16x32_bf16 v[52:55], v[148:151], v[164:167], v[52:55]
	v_mfma_f32_16x16x32_bf16 v[48:51], v[152:155], v[160:163], 0
	v_mfma_f32_16x16x32_bf16 v[48:51], v[156:159], v[164:167], v[48:51]
	v_mfma_f32_16x16x32_bf16 v[36:39], v[144:147], v[168:171], 0
	v_mfma_f32_16x16x32_bf16 v[36:39], v[148:151], v[172:175], v[36:39]
	v_mfma_f32_16x16x32_bf16 v[32:35], v[152:155], v[168:171], 0
	v_mfma_f32_16x16x32_bf16 v[32:35], v[156:159], v[172:175], v[32:35]
	v_mfma_f32_16x16x32_bf16 v[20:23], v[144:147], v[176:179], 0
	v_mfma_f32_16x16x32_bf16 v[20:23], v[148:151], v[180:183], v[20:23]
	v_mfma_f32_16x16x32_bf16 v[16:19], v[152:155], v[176:179], 0
	v_mfma_f32_16x16x32_bf16 v[16:19], v[156:159], v[180:183], v[16:19]
	s_setprio 2
	s_barrier
	v_mfma_f32_16x16x32_bf16 v[4:7], v[144:147], v[200:203], 0
	v_mfma_f32_16x16x32_bf16 v[4:7], v[148:151], v[204:207], v[4:7]
	v_mfma_f32_16x16x32_bf16 v[0:3], v[152:155], v[200:203], 0
	v_mfma_f32_16x16x32_bf16 v[0:3], v[156:159], v[204:207], v[0:3]
	s_setprio 0
	s_add_i32 s65, 0, 0x18000
	s_add_i32 s66, 0, 0x1c000
	v_add_u32_e32 v140, s65, v232
	v_add_u32_e32 v156, s66, v232
	ds_read_b128 v[120:123], v140
	ds_read_b128 v[124:127], v140 offset:1024
	ds_read_b128 v[136:139], v140 offset:2048
	ds_read_b128 v[140:143], v140 offset:3072
	ds_read_b128 v[144:147], v156
	ds_read_b128 v[148:151], v156 offset:1024
	ds_read_b128 v[152:155], v156 offset:2048
	ds_read_b128 v[156:159], v156 offset:3072
	s_add_u32 s26, s36, 0xb0000
	s_addc_u32 s27, s37, 0
	s_mov_b32 m0, s46
	v_lshl_add_u64 v[216:217], s[26:27], 0, v[184:185]
	ds_read_b128 v[160:163], v235 offset:32768
	ds_read_b128 v[164:167], v235 offset:33792
	ds_read_b128 v[168:171], v235 offset:34816
	ds_read_b128 v[172:175], v235 offset:35840
	ds_read_b128 v[176:179], v235 offset:36864
	ds_read_b128 v[180:183], v235 offset:37888
	ds_read_b128 v[200:203], v235 offset:38912
	ds_read_b128 v[204:207], v235 offset:39936
	global_load_lds_dwordx4 v[216:217], off
	s_mov_b32 m0, s47
	v_lshl_add_u64 v[216:217], s[26:27], 0, v[188:189]
	global_load_lds_dwordx4 v[216:217], off
	s_waitcnt vmcnt(8) lgkmcnt(0)
	s_barrier
	s_setprio 1
	v_mfma_f32_16x16x32_bf16 v[132:135], v[120:123], v[160:163], v[132:135]
	v_mfma_f32_16x16x32_bf16 v[132:135], v[124:127], v[164:167], v[132:135]
	v_mfma_f32_16x16x32_bf16 v[128:131], v[136:139], v[160:163], v[128:131]
	v_mfma_f32_16x16x32_bf16 v[128:131], v[140:143], v[164:167], v[128:131]
	v_mfma_f32_16x16x32_bf16 v[108:111], v[120:123], v[168:171], v[108:111]
	v_mfma_f32_16x16x32_bf16 v[108:111], v[124:127], v[172:175], v[108:111]
	v_mfma_f32_16x16x32_bf16 v[104:107], v[136:139], v[168:171], v[104:107]
	v_mfma_f32_16x16x32_bf16 v[104:107], v[140:143], v[172:175], v[104:107]
	v_mfma_f32_16x16x32_bf16 v[92:95], v[120:123], v[176:179], v[92:95]
	v_mfma_f32_16x16x32_bf16 v[92:95], v[124:127], v[180:183], v[92:95]
	v_mfma_f32_16x16x32_bf16 v[88:91], v[136:139], v[176:179], v[88:91]
	v_mfma_f32_16x16x32_bf16 v[88:91], v[140:143], v[180:183], v[88:91]
	v_mfma_f32_16x16x32_bf16 v[76:79], v[120:123], v[200:203], v[76:79]
	v_mfma_f32_16x16x32_bf16 v[76:79], v[124:127], v[204:207], v[76:79]
	v_mfma_f32_16x16x32_bf16 v[72:75], v[136:139], v[200:203], v[72:75]
	v_mfma_f32_16x16x32_bf16 v[72:75], v[140:143], v[204:207], v[72:75]
	v_mfma_f32_16x16x32_bf16 v[116:119], v[144:147], v[160:163], v[116:119]
	v_mfma_f32_16x16x32_bf16 v[116:119], v[148:151], v[164:167], v[116:119]
	v_mfma_f32_16x16x32_bf16 v[112:115], v[152:155], v[160:163], v[112:115]
	v_mfma_f32_16x16x32_bf16 v[112:115], v[156:159], v[164:167], v[112:115]
	v_mfma_f32_16x16x32_bf16 v[100:103], v[144:147], v[168:171], v[100:103]
	v_mfma_f32_16x16x32_bf16 v[100:103], v[148:151], v[172:175], v[100:103]
	v_mfma_f32_16x16x32_bf16 v[96:99], v[152:155], v[168:171], v[96:99]
	v_mfma_f32_16x16x32_bf16 v[96:99], v[156:159], v[172:175], v[96:99]
	v_mfma_f32_16x16x32_bf16 v[84:87], v[144:147], v[176:179], v[84:87]
	v_mfma_f32_16x16x32_bf16 v[84:87], v[148:151], v[180:183], v[84:87]
	v_mfma_f32_16x16x32_bf16 v[80:83], v[152:155], v[176:179], v[80:83]
	v_mfma_f32_16x16x32_bf16 v[80:83], v[156:159], v[180:183], v[80:83]
	s_setprio 2
	s_barrier
	v_mfma_f32_16x16x32_bf16 v[68:71], v[144:147], v[200:203], v[68:71]
	v_mfma_f32_16x16x32_bf16 v[68:71], v[148:151], v[204:207], v[68:71]
	v_mfma_f32_16x16x32_bf16 v[64:67], v[152:155], v[200:203], v[64:67]
	v_mfma_f32_16x16x32_bf16 v[64:67], v[156:159], v[204:207], v[64:67]
	s_setprio 2
	s_add_i32 s26, s65, s43
	v_lshl_add_u64 v[208:209], v[208:209], 0, s[20:21]
	s_mov_b32 m0, s26
	ds_read_b128 v[160:163], v235 offset:49152
	ds_read_b128 v[164:167], v235 offset:50176
	ds_read_b128 v[168:171], v235 offset:51200
	ds_read_b128 v[172:175], v235 offset:52224
	ds_read_b128 v[176:179], v235 offset:53248
	ds_read_b128 v[180:183], v235 offset:54272
	ds_read_b128 v[200:203], v235 offset:55296
	ds_read_b128 v[204:207], v235 offset:56320
	global_load_lds_dwordx4 v[208:209], off
	s_add_i32 m0, s26, 0x2000
	s_add_u32 s26, s30, 0xb0080
	v_lshl_add_u64 v[208:209], v[210:211], 0, s[20:21]
	s_addc_u32 s27, s31, 0
	s_add_i32 s30, s66, s43
	global_load_lds_dwordx4 v[208:209], off
	s_mov_b32 m0, s30
	v_lshl_add_u64 v[208:209], s[26:27], 0, v[186:187]
	global_load_lds_dwordx4 v[208:209], off
	s_add_i32 m0, s30, 0x2000
	v_lshl_add_u64 v[208:209], s[26:27], 0, v[190:191]
	global_load_lds_dwordx4 v[208:209], off
	s_mov_b32 m0, s49
	v_lshl_add_u64 v[208:209], v[212:213], 0, s[20:21]
	global_load_lds_dwordx4 v[208:209], off
	s_mov_b32 m0, s50
	v_lshl_add_u64 v[208:209], v[214:215], 0, s[20:21]
	global_load_lds_dwordx4 v[208:209], off
	s_waitcnt vmcnt(8) lgkmcnt(0)
	s_barrier
	s_setprio 1
	v_mfma_f32_16x16x32_bf16 v[60:63], v[120:123], v[160:163], v[60:63]
	v_mfma_f32_16x16x32_bf16 v[60:63], v[124:127], v[164:167], v[60:63]
	v_mfma_f32_16x16x32_bf16 v[56:59], v[136:139], v[160:163], v[56:59]
	v_mfma_f32_16x16x32_bf16 v[56:59], v[140:143], v[164:167], v[56:59]
	v_mfma_f32_16x16x32_bf16 v[44:47], v[120:123], v[168:171], v[44:47]
	v_mfma_f32_16x16x32_bf16 v[44:47], v[124:127], v[172:175], v[44:47]
	v_mfma_f32_16x16x32_bf16 v[40:43], v[136:139], v[168:171], v[40:43]
	v_mfma_f32_16x16x32_bf16 v[40:43], v[140:143], v[172:175], v[40:43]
	v_mfma_f32_16x16x32_bf16 v[28:31], v[120:123], v[176:179], v[28:31]
	v_mfma_f32_16x16x32_bf16 v[28:31], v[124:127], v[180:183], v[28:31]
	v_mfma_f32_16x16x32_bf16 v[24:27], v[136:139], v[176:179], v[24:27]
	v_mfma_f32_16x16x32_bf16 v[24:27], v[140:143], v[180:183], v[24:27]
	v_mfma_f32_16x16x32_bf16 v[12:15], v[120:123], v[200:203], v[12:15]
	v_mfma_f32_16x16x32_bf16 v[12:15], v[124:127], v[204:207], v[12:15]
	v_mfma_f32_16x16x32_bf16 v[8:11], v[136:139], v[200:203], v[8:11]
	v_mfma_f32_16x16x32_bf16 v[8:11], v[140:143], v[204:207], v[8:11]
	v_mfma_f32_16x16x32_bf16 v[52:55], v[144:147], v[160:163], v[52:55]
	v_mfma_f32_16x16x32_bf16 v[52:55], v[148:151], v[164:167], v[52:55]
	v_mfma_f32_16x16x32_bf16 v[48:51], v[152:155], v[160:163], v[48:51]
	v_mfma_f32_16x16x32_bf16 v[48:51], v[156:159], v[164:167], v[48:51]
	v_mfma_f32_16x16x32_bf16 v[36:39], v[144:147], v[168:171], v[36:39]
	v_mfma_f32_16x16x32_bf16 v[36:39], v[148:151], v[172:175], v[36:39]
	v_mfma_f32_16x16x32_bf16 v[32:35], v[152:155], v[168:171], v[32:35]
	v_mfma_f32_16x16x32_bf16 v[32:35], v[156:159], v[172:175], v[32:35]
	v_mfma_f32_16x16x32_bf16 v[20:23], v[144:147], v[176:179], v[20:23]
	v_mfma_f32_16x16x32_bf16 v[20:23], v[148:151], v[180:183], v[20:23]
	v_mfma_f32_16x16x32_bf16 v[16:19], v[152:155], v[176:179], v[16:19]
	v_mfma_f32_16x16x32_bf16 v[16:19], v[156:159], v[180:183], v[16:19]
	s_setprio 2
	s_barrier
	v_mfma_f32_16x16x32_bf16 v[4:7], v[144:147], v[200:203], v[4:7]
	v_mfma_f32_16x16x32_bf16 v[4:7], v[148:151], v[204:207], v[4:7]
	v_mfma_f32_16x16x32_bf16 v[0:3], v[152:155], v[200:203], v[0:3]
	v_mfma_f32_16x16x32_bf16 v[0:3], v[156:159], v[204:207], v[0:3]
	s_setprio 0
	s_add_i32 s64, s64, 2
	s_add_u32 s62, s62, 0x100
	s_addc_u32 s63, s63, 0
	s_cmp_gt_u32 s64, 41
	s_mov_b64 s[26:27], s[28:29]
.LBB0_866:
	ds_read_b128 v[120:123], v233
	ds_read_b128 v[124:127], v233 offset:1024
	ds_read_b128 v[136:139], v233 offset:2048
	ds_read_b128 v[140:143], v233 offset:3072
	ds_read_b128 v[144:147], v234
	ds_read_b128 v[148:151], v234 offset:1024
	ds_read_b128 v[152:155], v234 offset:2048
	ds_read_b128 v[156:159], v234 offset:3072
	s_add_u32 s28, s26, 0x100
	s_addc_u32 s29, s27, 0
	s_cmp_eq_u32 s64, 40
	s_cselect_b32 s37, s7, s29
	s_cselect_b32 s36, s6, s28
	s_cselect_b32 s31, s25, s63
	s_cselect_b32 s30, s24, s62
	v_lshl_add_u64 v[208:209], s[26:27], 0, v[192:193]
	s_add_i32 m0, s44, 0xc000
	ds_read_b128 v[160:163], v235
	ds_read_b128 v[164:167], v235 offset:1024
	ds_read_b128 v[168:171], v235 offset:2048
	ds_read_b128 v[172:175], v235 offset:3072
	ds_read_b128 v[176:179], v235 offset:4096
	ds_read_b128 v[180:183], v235 offset:5120
	ds_read_b128 v[200:203], v235 offset:6144
	ds_read_b128 v[204:207], v235 offset:7168
	global_load_lds_dwordx4 v[208:209], off
	s_add_i32 m0, s44, 0xe000
	v_lshl_add_u64 v[208:209], s[26:27], 0, v[194:195]
	global_load_lds_dwordx4 v[208:209], off
	s_waitcnt vmcnt(8) lgkmcnt(0)
	s_barrier
	s_setprio 1
	v_mfma_f32_16x16x32_bf16 v[132:135], v[120:123], v[160:163], v[132:135]
	v_mfma_f32_16x16x32_bf16 v[132:135], v[124:127], v[164:167], v[132:135]
	v_mfma_f32_16x16x32_bf16 v[128:131], v[136:139], v[160:163], v[128:131]
	v_mfma_f32_16x16x32_bf16 v[128:131], v[140:143], v[164:167], v[128:131]
	v_mfma_f32_16x16x32_bf16 v[108:111], v[120:123], v[168:171], v[108:111]
	v_mfma_f32_16x16x32_bf16 v[108:111], v[124:127], v[172:175], v[108:111]
	v_mfma_f32_16x16x32_bf16 v[104:107], v[136:139], v[168:171], v[104:107]
	v_mfma_f32_16x16x32_bf16 v[104:107], v[140:143], v[172:175], v[104:107]
	v_mfma_f32_16x16x32_bf16 v[92:95], v[120:123], v[176:179], v[92:95]
	v_mfma_f32_16x16x32_bf16 v[92:95], v[124:127], v[180:183], v[92:95]
	v_mfma_f32_16x16x32_bf16 v[88:91], v[136:139], v[176:179], v[88:91]
	v_mfma_f32_16x16x32_bf16 v[88:91], v[140:143], v[180:183], v[88:91]
	v_mfma_f32_16x16x32_bf16 v[76:79], v[120:123], v[200:203], v[76:79]
	v_mfma_f32_16x16x32_bf16 v[76:79], v[124:127], v[204:207], v[76:79]
	v_mfma_f32_16x16x32_bf16 v[72:75], v[136:139], v[200:203], v[72:75]
	v_mfma_f32_16x16x32_bf16 v[72:75], v[140:143], v[204:207], v[72:75]
	v_mfma_f32_16x16x32_bf16 v[116:119], v[144:147], v[160:163], v[116:119]
	v_mfma_f32_16x16x32_bf16 v[116:119], v[148:151], v[164:167], v[116:119]
	v_mfma_f32_16x16x32_bf16 v[112:115], v[152:155], v[160:163], v[112:115]
	v_mfma_f32_16x16x32_bf16 v[112:115], v[156:159], v[164:167], v[112:115]
	v_mfma_f32_16x16x32_bf16 v[100:103], v[144:147], v[168:171], v[100:103]
	v_mfma_f32_16x16x32_bf16 v[100:103], v[148:151], v[172:175], v[100:103]
	v_mfma_f32_16x16x32_bf16 v[96:99], v[152:155], v[168:171], v[96:99]
	v_mfma_f32_16x16x32_bf16 v[96:99], v[156:159], v[172:175], v[96:99]
	v_mfma_f32_16x16x32_bf16 v[84:87], v[144:147], v[176:179], v[84:87]
	v_mfma_f32_16x16x32_bf16 v[84:87], v[148:151], v[180:183], v[84:87]
	v_mfma_f32_16x16x32_bf16 v[80:83], v[152:155], v[176:179], v[80:83]
	v_mfma_f32_16x16x32_bf16 v[80:83], v[156:159], v[180:183], v[80:83]
	s_setprio 2
	s_barrier
	v_mfma_f32_16x16x32_bf16 v[68:71], v[144:147], v[200:203], v[68:71]
	v_mfma_f32_16x16x32_bf16 v[68:71], v[148:151], v[204:207], v[68:71]
	v_mfma_f32_16x16x32_bf16 v[64:67], v[152:155], v[200:203], v[64:67]
	v_mfma_f32_16x16x32_bf16 v[64:67], v[156:159], v[204:207], v[64:67]
	s_setprio 2
	s_add_i32 s26, s56, s43
	v_lshl_add_u64 v[208:209], s[30:31], 0, v[186:187]
	s_mov_b32 m0, s26
	ds_read_b128 v[160:163], v235 offset:16384
	ds_read_b128 v[164:167], v235 offset:17408
	ds_read_b128 v[168:171], v235 offset:18432
	ds_read_b128 v[172:175], v235 offset:19456
	ds_read_b128 v[176:179], v235 offset:20480
	ds_read_b128 v[180:183], v235 offset:21504
	ds_read_b128 v[200:203], v235 offset:22528
	ds_read_b128 v[204:207], v235 offset:23552
	global_load_lds_dwordx4 v[208:209], off
	s_add_i32 m0, s26, 0x2000
	s_add_u32 s26, s30, 0xb0000
	v_lshl_add_u64 v[210:211], s[30:31], 0, v[190:191]
	s_addc_u32 s27, s31, 0
	s_add_i32 s65, s57, s43
	global_load_lds_dwordx4 v[210:211], off
	v_lshl_add_u64 v[212:213], s[26:27], 0, v[186:187]
	s_mov_b32 m0, s65
	v_lshl_add_u64 v[214:215], s[36:37], 0, v[188:189]
	global_load_lds_dwordx4 v[212:213], off
	s_add_i32 m0, s65, 0x2000
	v_lshl_add_u64 v[212:213], s[26:27], 0, v[190:191]
	global_load_lds_dwordx4 v[212:213], off
	s_mov_b32 m0, s44
	v_lshl_add_u64 v[212:213], s[36:37], 0, v[184:185]
	global_load_lds_dwordx4 v[212:213], off
	s_mov_b32 m0, s45
	s_nop 0
	global_load_lds_dwordx4 v[214:215], off
	s_waitcnt vmcnt(8) lgkmcnt(0)
	s_barrier
	s_setprio 1
	v_mfma_f32_16x16x32_bf16 v[60:63], v[120:123], v[160:163], v[60:63]
	v_mfma_f32_16x16x32_bf16 v[60:63], v[124:127], v[164:167], v[60:63]
	v_mfma_f32_16x16x32_bf16 v[56:59], v[136:139], v[160:163], v[56:59]
	v_mfma_f32_16x16x32_bf16 v[56:59], v[140:143], v[164:167], v[56:59]
	v_mfma_f32_16x16x32_bf16 v[44:47], v[120:123], v[168:171], v[44:47]
	v_mfma_f32_16x16x32_bf16 v[44:47], v[124:127], v[172:175], v[44:47]
	v_mfma_f32_16x16x32_bf16 v[40:43], v[136:139], v[168:171], v[40:43]
	v_mfma_f32_16x16x32_bf16 v[40:43], v[140:143], v[172:175], v[40:43]
	v_mfma_f32_16x16x32_bf16 v[28:31], v[120:123], v[176:179], v[28:31]
	v_mfma_f32_16x16x32_bf16 v[28:31], v[124:127], v[180:183], v[28:31]
	v_mfma_f32_16x16x32_bf16 v[24:27], v[136:139], v[176:179], v[24:27]
	v_mfma_f32_16x16x32_bf16 v[24:27], v[140:143], v[180:183], v[24:27]
	v_mfma_f32_16x16x32_bf16 v[12:15], v[120:123], v[200:203], v[12:15]
	v_mfma_f32_16x16x32_bf16 v[12:15], v[124:127], v[204:207], v[12:15]
	v_mfma_f32_16x16x32_bf16 v[8:11], v[136:139], v[200:203], v[8:11]
	v_mfma_f32_16x16x32_bf16 v[8:11], v[140:143], v[204:207], v[8:11]
	v_mfma_f32_16x16x32_bf16 v[52:55], v[144:147], v[160:163], v[52:55]
	v_mfma_f32_16x16x32_bf16 v[52:55], v[148:151], v[164:167], v[52:55]
	v_mfma_f32_16x16x32_bf16 v[48:51], v[152:155], v[160:163], v[48:51]
	v_mfma_f32_16x16x32_bf16 v[48:51], v[156:159], v[164:167], v[48:51]
	v_mfma_f32_16x16x32_bf16 v[36:39], v[144:147], v[168:171], v[36:39]
	v_mfma_f32_16x16x32_bf16 v[36:39], v[148:151], v[172:175], v[36:39]
	v_mfma_f32_16x16x32_bf16 v[32:35], v[152:155], v[168:171], v[32:35]
	v_mfma_f32_16x16x32_bf16 v[32:35], v[156:159], v[172:175], v[32:35]
	v_mfma_f32_16x16x32_bf16 v[20:23], v[144:147], v[176:179], v[20:23]
	v_mfma_f32_16x16x32_bf16 v[20:23], v[148:151], v[180:183], v[20:23]
	v_mfma_f32_16x16x32_bf16 v[16:19], v[152:155], v[176:179], v[16:19]
	v_mfma_f32_16x16x32_bf16 v[16:19], v[156:159], v[180:183], v[16:19]
	s_setprio 2
	s_barrier
	v_mfma_f32_16x16x32_bf16 v[4:7], v[144:147], v[200:203], v[4:7]
	v_mfma_f32_16x16x32_bf16 v[4:7], v[148:151], v[204:207], v[4:7]
	v_mfma_f32_16x16x32_bf16 v[0:3], v[152:155], v[200:203], v[0:3]
	v_mfma_f32_16x16x32_bf16 v[0:3], v[156:159], v[204:207], v[0:3]
	s_setprio 0
	s_add_i32 s65, 0, 0x18000
	s_add_i32 s66, 0, 0x1c000
	v_add_u32_e32 v140, s65, v232
	v_add_u32_e32 v156, s66, v232
	ds_read_b128 v[120:123], v140
	ds_read_b128 v[124:127], v140 offset:1024
	ds_read_b128 v[136:139], v140 offset:2048
	ds_read_b128 v[140:143], v140 offset:3072
	ds_read_b128 v[144:147], v156
	ds_read_b128 v[148:151], v156 offset:1024
	ds_read_b128 v[152:155], v156 offset:2048
	ds_read_b128 v[156:159], v156 offset:3072
	s_add_u32 s26, s36, 0xb0000
	s_addc_u32 s27, s37, 0
	s_mov_b32 m0, s46
	v_lshl_add_u64 v[216:217], s[26:27], 0, v[184:185]
	ds_read_b128 v[160:163], v235 offset:32768
	ds_read_b128 v[164:167], v235 offset:33792
	ds_read_b128 v[168:171], v235 offset:34816
	ds_read_b128 v[172:175], v235 offset:35840
	ds_read_b128 v[176:179], v235 offset:36864
	ds_read_b128 v[180:183], v235 offset:37888
	ds_read_b128 v[200:203], v235 offset:38912
	ds_read_b128 v[204:207], v235 offset:39936
	global_load_lds_dwordx4 v[216:217], off
	s_mov_b32 m0, s47
	v_lshl_add_u64 v[216:217], s[26:27], 0, v[188:189]
	global_load_lds_dwordx4 v[216:217], off
	s_waitcnt vmcnt(8) lgkmcnt(0)
	s_barrier
	s_setprio 1
	v_mfma_f32_16x16x32_bf16 v[132:135], v[120:123], v[160:163], v[132:135]
	v_mfma_f32_16x16x32_bf16 v[132:135], v[124:127], v[164:167], v[132:135]
	v_mfma_f32_16x16x32_bf16 v[128:131], v[136:139], v[160:163], v[128:131]
	v_mfma_f32_16x16x32_bf16 v[128:131], v[140:143], v[164:167], v[128:131]
	v_mfma_f32_16x16x32_bf16 v[108:111], v[120:123], v[168:171], v[108:111]
	v_mfma_f32_16x16x32_bf16 v[108:111], v[124:127], v[172:175], v[108:111]
	v_mfma_f32_16x16x32_bf16 v[104:107], v[136:139], v[168:171], v[104:107]
	v_mfma_f32_16x16x32_bf16 v[104:107], v[140:143], v[172:175], v[104:107]
	v_mfma_f32_16x16x32_bf16 v[92:95], v[120:123], v[176:179], v[92:95]
	v_mfma_f32_16x16x32_bf16 v[92:95], v[124:127], v[180:183], v[92:95]
	v_mfma_f32_16x16x32_bf16 v[88:91], v[136:139], v[176:179], v[88:91]
	v_mfma_f32_16x16x32_bf16 v[88:91], v[140:143], v[180:183], v[88:91]
	v_mfma_f32_16x16x32_bf16 v[76:79], v[120:123], v[200:203], v[76:79]
	v_mfma_f32_16x16x32_bf16 v[76:79], v[124:127], v[204:207], v[76:79]
	v_mfma_f32_16x16x32_bf16 v[72:75], v[136:139], v[200:203], v[72:75]
	v_mfma_f32_16x16x32_bf16 v[72:75], v[140:143], v[204:207], v[72:75]
	v_mfma_f32_16x16x32_bf16 v[116:119], v[144:147], v[160:163], v[116:119]
	v_mfma_f32_16x16x32_bf16 v[116:119], v[148:151], v[164:167], v[116:119]
	v_mfma_f32_16x16x32_bf16 v[112:115], v[152:155], v[160:163], v[112:115]
	v_mfma_f32_16x16x32_bf16 v[112:115], v[156:159], v[164:167], v[112:115]
	v_mfma_f32_16x16x32_bf16 v[100:103], v[144:147], v[168:171], v[100:103]
	v_mfma_f32_16x16x32_bf16 v[100:103], v[148:151], v[172:175], v[100:103]
	v_mfma_f32_16x16x32_bf16 v[96:99], v[152:155], v[168:171], v[96:99]
	v_mfma_f32_16x16x32_bf16 v[96:99], v[156:159], v[172:175], v[96:99]
	v_mfma_f32_16x16x32_bf16 v[84:87], v[144:147], v[176:179], v[84:87]
	v_mfma_f32_16x16x32_bf16 v[84:87], v[148:151], v[180:183], v[84:87]
	v_mfma_f32_16x16x32_bf16 v[80:83], v[152:155], v[176:179], v[80:83]
	v_mfma_f32_16x16x32_bf16 v[80:83], v[156:159], v[180:183], v[80:83]
	s_setprio 2
	s_barrier
	v_mfma_f32_16x16x32_bf16 v[68:71], v[144:147], v[200:203], v[68:71]
	v_mfma_f32_16x16x32_bf16 v[68:71], v[148:151], v[204:207], v[68:71]
	v_mfma_f32_16x16x32_bf16 v[64:67], v[152:155], v[200:203], v[64:67]
	v_mfma_f32_16x16x32_bf16 v[64:67], v[156:159], v[204:207], v[64:67]
	s_setprio 2
	s_add_i32 s26, s65, s43
	v_lshl_add_u64 v[208:209], v[208:209], 0, s[20:21]
	s_mov_b32 m0, s26
	ds_read_b128 v[160:163], v235 offset:49152
	ds_read_b128 v[164:167], v235 offset:50176
	ds_read_b128 v[168:171], v235 offset:51200
	ds_read_b128 v[172:175], v235 offset:52224
	ds_read_b128 v[176:179], v235 offset:53248
	ds_read_b128 v[180:183], v235 offset:54272
	ds_read_b128 v[200:203], v235 offset:55296
	ds_read_b128 v[204:207], v235 offset:56320
	global_load_lds_dwordx4 v[208:209], off
	s_add_i32 m0, s26, 0x2000
	s_add_u32 s26, s30, 0xb0080
	v_lshl_add_u64 v[208:209], v[210:211], 0, s[20:21]
	s_addc_u32 s27, s31, 0
	s_add_i32 s30, s66, s43
	global_load_lds_dwordx4 v[208:209], off
	s_mov_b32 m0, s30
	v_lshl_add_u64 v[208:209], s[26:27], 0, v[186:187]
	global_load_lds_dwordx4 v[208:209], off
	s_add_i32 m0, s30, 0x2000
	v_lshl_add_u64 v[208:209], s[26:27], 0, v[190:191]
	global_load_lds_dwordx4 v[208:209], off
	s_mov_b32 m0, s49
	v_lshl_add_u64 v[208:209], v[212:213], 0, s[20:21]
	global_load_lds_dwordx4 v[208:209], off
	s_mov_b32 m0, s50
	v_lshl_add_u64 v[208:209], v[214:215], 0, s[20:21]
	global_load_lds_dwordx4 v[208:209], off
	s_waitcnt vmcnt(8) lgkmcnt(0)
	s_barrier
	s_setprio 1
	v_mfma_f32_16x16x32_bf16 v[60:63], v[120:123], v[160:163], v[60:63]
	v_mfma_f32_16x16x32_bf16 v[60:63], v[124:127], v[164:167], v[60:63]
	v_mfma_f32_16x16x32_bf16 v[56:59], v[136:139], v[160:163], v[56:59]
	v_mfma_f32_16x16x32_bf16 v[56:59], v[140:143], v[164:167], v[56:59]
	v_mfma_f32_16x16x32_bf16 v[44:47], v[120:123], v[168:171], v[44:47]
	v_mfma_f32_16x16x32_bf16 v[44:47], v[124:127], v[172:175], v[44:47]
	v_mfma_f32_16x16x32_bf16 v[40:43], v[136:139], v[168:171], v[40:43]
	v_mfma_f32_16x16x32_bf16 v[40:43], v[140:143], v[172:175], v[40:43]
	v_mfma_f32_16x16x32_bf16 v[28:31], v[120:123], v[176:179], v[28:31]
	v_mfma_f32_16x16x32_bf16 v[28:31], v[124:127], v[180:183], v[28:31]
	v_mfma_f32_16x16x32_bf16 v[24:27], v[136:139], v[176:179], v[24:27]
	v_mfma_f32_16x16x32_bf16 v[24:27], v[140:143], v[180:183], v[24:27]
	v_mfma_f32_16x16x32_bf16 v[12:15], v[120:123], v[200:203], v[12:15]
	v_mfma_f32_16x16x32_bf16 v[12:15], v[124:127], v[204:207], v[12:15]
	v_mfma_f32_16x16x32_bf16 v[8:11], v[136:139], v[200:203], v[8:11]
	v_mfma_f32_16x16x32_bf16 v[8:11], v[140:143], v[204:207], v[8:11]
	v_mfma_f32_16x16x32_bf16 v[52:55], v[144:147], v[160:163], v[52:55]
	v_mfma_f32_16x16x32_bf16 v[52:55], v[148:151], v[164:167], v[52:55]
	v_mfma_f32_16x16x32_bf16 v[48:51], v[152:155], v[160:163], v[48:51]
	v_mfma_f32_16x16x32_bf16 v[48:51], v[156:159], v[164:167], v[48:51]
	v_mfma_f32_16x16x32_bf16 v[36:39], v[144:147], v[168:171], v[36:39]
	v_mfma_f32_16x16x32_bf16 v[36:39], v[148:151], v[172:175], v[36:39]
	v_mfma_f32_16x16x32_bf16 v[32:35], v[152:155], v[168:171], v[32:35]
	v_mfma_f32_16x16x32_bf16 v[32:35], v[156:159], v[172:175], v[32:35]
	v_mfma_f32_16x16x32_bf16 v[20:23], v[144:147], v[176:179], v[20:23]
	v_mfma_f32_16x16x32_bf16 v[20:23], v[148:151], v[180:183], v[20:23]
	v_mfma_f32_16x16x32_bf16 v[16:19], v[152:155], v[176:179], v[16:19]
	v_mfma_f32_16x16x32_bf16 v[16:19], v[156:159], v[180:183], v[16:19]
	s_setprio 2
	s_barrier
	v_mfma_f32_16x16x32_bf16 v[4:7], v[144:147], v[200:203], v[4:7]
	v_mfma_f32_16x16x32_bf16 v[4:7], v[148:151], v[204:207], v[4:7]
	v_mfma_f32_16x16x32_bf16 v[0:3], v[152:155], v[200:203], v[0:3]
	v_mfma_f32_16x16x32_bf16 v[0:3], v[156:159], v[204:207], v[0:3]
	s_setprio 0
	s_add_i32 s64, s64, 2
	s_add_u32 s62, s62, 0x100
	s_addc_u32 s63, s63, 0
	s_cmp_gt_u32 s64, 41
	s_mov_b64 s[26:27], s[28:29]
	s_cbranch_scc0 .LBB0_866

.LBB0_951:
	s_ashr_i32 s27, s26, 31
	s_lshl_b64 s[30:31], s[26:27], 19
	s_add_u32 s30, s47, s30
	s_addc_u32 s31, s48, s31
	s_and_b64 s[36:37], s[4:5], exec
	s_cselect_b32 s27, s31, s7
	s_cselect_b32 s39, s30, s6
	s_ashr_i32 s29, s28, 31
	s_lshl_b64 s[36:37], s[28:29], 19
	s_add_u32 s36, s49, s36
	s_addc_u32 s37, s50, s37
	s_and_b64 s[44:45], s[4:5], exec
	s_cselect_b32 s29, s37, s41
	s_cselect_b32 s43, s36, s40
	s_add_u32 s6, s6, 0x40080
	s_addc_u32 s7, s7, 0
	s_add_u32 s71, s40, 0x100
	s_addc_u32 s72, s41, 0
	s_mov_b32 s73, -2
	ds_read_b128 v[144:147], v179
	ds_read_b128 v[148:151], v179 offset:1024
	ds_read_b128 v[152:155], v179 offset:2048
	ds_read_b128 v[156:159], v179 offset:3072
	ds_read_b128 v[160:163], v180
	ds_read_b128 v[164:167], v180 offset:1024
	ds_read_b128 v[168:171], v180 offset:2048
	ds_read_b128 v[172:175], v180 offset:3072
	s_add_u32 s40, s6, 0xfffc0080
	s_addc_u32 s41, s7, -1
	s_cmp_eq_u32 s73, 12
	s_cselect_b32 s45, s27, s41
	s_cselect_b32 s44, s39, s40
	s_cselect_b32 s41, s29, s72
	s_cselect_b32 s40, s43, s71
	v_lshl_add_u64 v[176:177], s[6:7], 0, v[136:137]
	s_add_i32 m0, s54, 0xc000
	ds_read_b128 v[184:187], v181
	ds_read_b128 v[188:191], v181 offset:1024
	ds_read_b128 v[192:195], v181 offset:2048
	ds_read_b128 v[196:199], v181 offset:3072
	ds_read_b128 v[200:203], v181 offset:4096
	ds_read_b128 v[204:207], v181 offset:5120
	ds_read_b128 v[208:211], v181 offset:6144
	ds_read_b128 v[212:215], v181 offset:7168
	global_load_lds_dwordx4 v[176:177], off
	s_add_i32 m0, s54, 0xe000
	v_lshl_add_u64 v[176:177], s[6:7], 0, v[138:139]
	global_load_lds_dwordx4 v[176:177], off
	s_waitcnt vmcnt(8) lgkmcnt(0)
	s_barrier
	s_setprio 1
	v_mfma_f32_16x16x32_bf16 v[124:127], v[144:147], v[184:187], 0
	v_mfma_f32_16x16x32_bf16 v[124:127], v[148:151], v[188:191], v[124:127]
	v_mfma_f32_16x16x32_bf16 v[120:123], v[152:155], v[184:187], 0
	v_mfma_f32_16x16x32_bf16 v[120:123], v[156:159], v[188:191], v[120:123]
	v_mfma_f32_16x16x32_bf16 v[108:111], v[144:147], v[192:195], 0
	v_mfma_f32_16x16x32_bf16 v[108:111], v[148:151], v[196:199], v[108:111]
	v_mfma_f32_16x16x32_bf16 v[104:107], v[152:155], v[192:195], 0
	v_mfma_f32_16x16x32_bf16 v[104:107], v[156:159], v[196:199], v[104:107]
	v_mfma_f32_16x16x32_bf16 v[92:95], v[144:147], v[200:203], 0
	v_mfma_f32_16x16x32_bf16 v[92:95], v[148:151], v[204:207], v[92:95]
	v_mfma_f32_16x16x32_bf16 v[88:91], v[152:155], v[200:203], 0
	v_mfma_f32_16x16x32_bf16 v[88:91], v[156:159], v[204:207], v[88:91]
	v_mfma_f32_16x16x32_bf16 v[76:79], v[144:147], v[208:211], 0
	v_mfma_f32_16x16x32_bf16 v[76:79], v[148:151], v[212:215], v[76:79]
	v_mfma_f32_16x16x32_bf16 v[72:75], v[152:155], v[208:211], 0
	v_mfma_f32_16x16x32_bf16 v[72:75], v[156:159], v[212:215], v[72:75]
	v_mfma_f32_16x16x32_bf16 v[116:119], v[160:163], v[184:187], 0
	v_mfma_f32_16x16x32_bf16 v[116:119], v[164:167], v[188:191], v[116:119]
	v_mfma_f32_16x16x32_bf16 v[112:115], v[168:171], v[184:187], 0
	v_mfma_f32_16x16x32_bf16 v[112:115], v[172:175], v[188:191], v[112:115]
	v_mfma_f32_16x16x32_bf16 v[100:103], v[160:163], v[192:195], 0
	v_mfma_f32_16x16x32_bf16 v[100:103], v[164:167], v[196:199], v[100:103]
	v_mfma_f32_16x16x32_bf16 v[96:99], v[168:171], v[192:195], 0
	v_mfma_f32_16x16x32_bf16 v[96:99], v[172:175], v[196:199], v[96:99]
	v_mfma_f32_16x16x32_bf16 v[84:87], v[160:163], v[200:203], 0
	v_mfma_f32_16x16x32_bf16 v[84:87], v[164:167], v[204:207], v[84:87]
	v_mfma_f32_16x16x32_bf16 v[80:83], v[168:171], v[200:203], 0
	v_mfma_f32_16x16x32_bf16 v[80:83], v[172:175], v[204:207], v[80:83]
	s_setprio 2
	s_barrier
	v_mfma_f32_16x16x32_bf16 v[68:71], v[160:163], v[208:211], 0
	v_mfma_f32_16x16x32_bf16 v[68:71], v[164:167], v[212:215], v[68:71]
	v_mfma_f32_16x16x32_bf16 v[64:67], v[168:171], v[208:211], 0
	v_mfma_f32_16x16x32_bf16 v[64:67], v[172:175], v[212:215], v[64:67]
	s_setprio 2
	s_add_i32 s74, s69, s51
	v_lshl_add_u64 v[176:177], s[40:41], 0, v[130:131]
	s_mov_b32 m0, s74
	ds_read_b128 v[184:187], v181 offset:16384
	ds_read_b128 v[188:191], v181 offset:17408
	ds_read_b128 v[192:195], v181 offset:18432
	ds_read_b128 v[196:199], v181 offset:19456
	ds_read_b128 v[200:203], v181 offset:20480
	ds_read_b128 v[204:207], v181 offset:21504
	ds_read_b128 v[208:211], v181 offset:22528
	ds_read_b128 v[212:215], v181 offset:23552
	global_load_lds_dwordx4 v[176:177], off
	s_add_i32 m0, s74, 0x2000
	s_add_u32 s74, s40, 0x40000
	v_lshl_add_u64 v[216:217], s[40:41], 0, v[134:135]
	s_addc_u32 s75, s41, 0
	s_add_i32 s76, s70, s51
	global_load_lds_dwordx4 v[216:217], off
	v_lshl_add_u64 v[218:219], s[74:75], 0, v[130:131]
	s_mov_b32 m0, s76
	v_lshl_add_u64 v[220:221], s[44:45], 0, v[132:133]
	global_load_lds_dwordx4 v[218:219], off
	s_add_i32 m0, s76, 0x2000
	v_lshl_add_u64 v[218:219], s[74:75], 0, v[134:135]
	global_load_lds_dwordx4 v[218:219], off
	s_mov_b32 m0, s54
	v_lshl_add_u64 v[218:219], s[44:45], 0, v[128:129]
	global_load_lds_dwordx4 v[218:219], off
	s_mov_b32 m0, s55
	s_nop 0
	global_load_lds_dwordx4 v[220:221], off
	s_waitcnt vmcnt(8) lgkmcnt(0)
	s_barrier
	s_setprio 1
	v_mfma_f32_16x16x32_bf16 v[60:63], v[144:147], v[184:187], 0
	v_mfma_f32_16x16x32_bf16 v[60:63], v[148:151], v[188:191], v[60:63]
	v_mfma_f32_16x16x32_bf16 v[56:59], v[152:155], v[184:187], 0
	v_mfma_f32_16x16x32_bf16 v[56:59], v[156:159], v[188:191], v[56:59]
	v_mfma_f32_16x16x32_bf16 v[44:47], v[144:147], v[192:195], 0
	v_mfma_f32_16x16x32_bf16 v[44:47], v[148:151], v[196:199], v[44:47]
	v_mfma_f32_16x16x32_bf16 v[40:43], v[152:155], v[192:195], 0
	v_mfma_f32_16x16x32_bf16 v[40:43], v[156:159], v[196:199], v[40:43]
	v_mfma_f32_16x16x32_bf16 v[28:31], v[144:147], v[200:203], 0
	v_mfma_f32_16x16x32_bf16 v[28:31], v[148:151], v[204:207], v[28:31]
	v_mfma_f32_16x16x32_bf16 v[24:27], v[152:155], v[200:203], 0
	v_mfma_f32_16x16x32_bf16 v[24:27], v[156:159], v[204:207], v[24:27]
	v_mfma_f32_16x16x32_bf16 v[12:15], v[144:147], v[208:211], 0
	v_mfma_f32_16x16x32_bf16 v[12:15], v[148:151], v[212:215], v[12:15]
	v_mfma_f32_16x16x32_bf16 v[8:11], v[152:155], v[208:211], 0
	v_mfma_f32_16x16x32_bf16 v[8:11], v[156:159], v[212:215], v[8:11]
	v_mfma_f32_16x16x32_bf16 v[52:55], v[160:163], v[184:187], 0
	v_mfma_f32_16x16x32_bf16 v[52:55], v[164:167], v[188:191], v[52:55]
	v_mfma_f32_16x16x32_bf16 v[48:51], v[168:171], v[184:187], 0
	v_mfma_f32_16x16x32_bf16 v[48:51], v[172:175], v[188:191], v[48:51]
	v_mfma_f32_16x16x32_bf16 v[36:39], v[160:163], v[192:195], 0
	v_mfma_f32_16x16x32_bf16 v[36:39], v[164:167], v[196:199], v[36:39]
	v_mfma_f32_16x16x32_bf16 v[32:35], v[168:171], v[192:195], 0
	v_mfma_f32_16x16x32_bf16 v[32:35], v[172:175], v[196:199], v[32:35]
	v_mfma_f32_16x16x32_bf16 v[20:23], v[160:163], v[200:203], 0
	v_mfma_f32_16x16x32_bf16 v[20:23], v[164:167], v[204:207], v[20:23]
	v_mfma_f32_16x16x32_bf16 v[16:19], v[168:171], v[200:203], 0
	v_mfma_f32_16x16x32_bf16 v[16:19], v[172:175], v[204:207], v[16:19]
	s_setprio 2
	s_barrier
	v_mfma_f32_16x16x32_bf16 v[4:7], v[160:163], v[208:211], 0
	v_mfma_f32_16x16x32_bf16 v[4:7], v[164:167], v[212:215], v[4:7]
	v_mfma_f32_16x16x32_bf16 v[0:3], v[168:171], v[208:211], 0
	v_mfma_f32_16x16x32_bf16 v[0:3], v[172:175], v[212:215], v[0:3]
	s_setprio 0
	s_add_i32 s74, 0, 0x18000
	s_add_i32 s75, 0, 0x1c000
	v_add_u32_e32 v156, s74, v178
	v_add_u32_e32 v172, s75, v178
	ds_read_b128 v[144:147], v156
	ds_read_b128 v[148:151], v156 offset:1024
	ds_read_b128 v[152:155], v156 offset:2048
	ds_read_b128 v[156:159], v156 offset:3072
	ds_read_b128 v[160:163], v172
	ds_read_b128 v[164:167], v172 offset:1024
	ds_read_b128 v[168:171], v172 offset:2048
	ds_read_b128 v[172:175], v172 offset:3072
	s_add_u32 s44, s44, 0x40000
	s_addc_u32 s45, s45, 0
	s_mov_b32 m0, s56
	v_lshl_add_u64 v[222:223], s[44:45], 0, v[128:129]
	ds_read_b128 v[184:187], v181 offset:32768
	ds_read_b128 v[188:191], v181 offset:33792
	ds_read_b128 v[192:195], v181 offset:34816
	ds_read_b128 v[196:199], v181 offset:35840
	ds_read_b128 v[200:203], v181 offset:36864
	ds_read_b128 v[204:207], v181 offset:37888
	ds_read_b128 v[208:211], v181 offset:38912
	ds_read_b128 v[212:215], v181 offset:39936
	global_load_lds_dwordx4 v[222:223], off
	s_mov_b32 m0, s57
	v_lshl_add_u64 v[222:223], s[44:45], 0, v[132:133]
	global_load_lds_dwordx4 v[222:223], off
	s_waitcnt vmcnt(8) lgkmcnt(0)
	s_barrier
	s_setprio 1
	v_mfma_f32_16x16x32_bf16 v[124:127], v[144:147], v[184:187], v[124:127]
	v_mfma_f32_16x16x32_bf16 v[124:127], v[148:151], v[188:191], v[124:127]
	v_mfma_f32_16x16x32_bf16 v[120:123], v[152:155], v[184:187], v[120:123]
	v_mfma_f32_16x16x32_bf16 v[120:123], v[156:159], v[188:191], v[120:123]
	v_mfma_f32_16x16x32_bf16 v[108:111], v[144:147], v[192:195], v[108:111]
	v_mfma_f32_16x16x32_bf16 v[108:111], v[148:151], v[196:199], v[108:111]
	v_mfma_f32_16x16x32_bf16 v[104:107], v[152:155], v[192:195], v[104:107]
	v_mfma_f32_16x16x32_bf16 v[104:107], v[156:159], v[196:199], v[104:107]
	v_mfma_f32_16x16x32_bf16 v[92:95], v[144:147], v[200:203], v[92:95]
	v_mfma_f32_16x16x32_bf16 v[92:95], v[148:151], v[204:207], v[92:95]
	v_mfma_f32_16x16x32_bf16 v[88:91], v[152:155], v[200:203], v[88:91]
	v_mfma_f32_16x16x32_bf16 v[88:91], v[156:159], v[204:207], v[88:91]
	v_mfma_f32_16x16x32_bf16 v[76:79], v[144:147], v[208:211], v[76:79]
	v_mfma_f32_16x16x32_bf16 v[76:79], v[148:151], v[212:215], v[76:79]
	v_mfma_f32_16x16x32_bf16 v[72:75], v[152:155], v[208:211], v[72:75]
	v_mfma_f32_16x16x32_bf16 v[72:75], v[156:159], v[212:215], v[72:75]
	v_mfma_f32_16x16x32_bf16 v[116:119], v[160:163], v[184:187], v[116:119]
	v_mfma_f32_16x16x32_bf16 v[116:119], v[164:167], v[188:191], v[116:119]
	v_mfma_f32_16x16x32_bf16 v[112:115], v[168:171], v[184:187], v[112:115]
	v_mfma_f32_16x16x32_bf16 v[112:115], v[172:175], v[188:191], v[112:115]
	v_mfma_f32_16x16x32_bf16 v[100:103], v[160:163], v[192:195], v[100:103]
	v_mfma_f32_16x16x32_bf16 v[100:103], v[164:167], v[196:199], v[100:103]
	v_mfma_f32_16x16x32_bf16 v[96:99], v[168:171], v[192:195], v[96:99]
	v_mfma_f32_16x16x32_bf16 v[96:99], v[172:175], v[196:199], v[96:99]
	v_mfma_f32_16x16x32_bf16 v[84:87], v[160:163], v[200:203], v[84:87]
	v_mfma_f32_16x16x32_bf16 v[84:87], v[164:167], v[204:207], v[84:87]
	v_mfma_f32_16x16x32_bf16 v[80:83], v[168:171], v[200:203], v[80:83]
	v_mfma_f32_16x16x32_bf16 v[80:83], v[172:175], v[204:207], v[80:83]
	s_setprio 2
	s_barrier
	v_mfma_f32_16x16x32_bf16 v[68:71], v[160:163], v[208:211], v[68:71]
	v_mfma_f32_16x16x32_bf16 v[68:71], v[164:167], v[212:215], v[68:71]
	v_mfma_f32_16x16x32_bf16 v[64:67], v[168:171], v[208:211], v[64:67]
	v_mfma_f32_16x16x32_bf16 v[64:67], v[172:175], v[212:215], v[64:67]
	s_setprio 2
	s_add_i32 s44, s74, s51
	v_lshl_add_u64 v[176:177], v[176:177], 0, s[22:23]
	s_mov_b32 m0, s44
	ds_read_b128 v[184:187], v181 offset:49152
	ds_read_b128 v[188:191], v181 offset:50176
	ds_read_b128 v[192:195], v181 offset:51200
	ds_read_b128 v[196:199], v181 offset:52224
	ds_read_b128 v[200:203], v181 offset:53248
	ds_read_b128 v[204:207], v181 offset:54272
	ds_read_b128 v[208:211], v181 offset:55296
	ds_read_b128 v[212:215], v181 offset:56320
	global_load_lds_dwordx4 v[176:177], off
	s_add_i32 m0, s44, 0x2000
	s_add_u32 s40, s40, 0x40080
	v_lshl_add_u64 v[176:177], v[216:217], 0, s[22:23]
	s_addc_u32 s41, s41, 0
	s_add_i32 s44, s75, s51
	global_load_lds_dwordx4 v[176:177], off
	s_mov_b32 m0, s44
	v_lshl_add_u64 v[176:177], s[40:41], 0, v[130:131]
	global_load_lds_dwordx4 v[176:177], off
	s_add_i32 m0, s44, 0x2000
	v_lshl_add_u64 v[176:177], s[40:41], 0, v[134:135]
	global_load_lds_dwordx4 v[176:177], off
	s_mov_b32 m0, s64
	v_lshl_add_u64 v[176:177], v[218:219], 0, s[22:23]
	global_load_lds_dwordx4 v[176:177], off
	s_mov_b32 m0, s65
	v_lshl_add_u64 v[176:177], v[220:221], 0, s[22:23]
	global_load_lds_dwordx4 v[176:177], off
	s_waitcnt vmcnt(8) lgkmcnt(0)
	s_barrier
	s_setprio 1
	v_mfma_f32_16x16x32_bf16 v[60:63], v[144:147], v[184:187], v[60:63]
	v_mfma_f32_16x16x32_bf16 v[60:63], v[148:151], v[188:191], v[60:63]
	v_mfma_f32_16x16x32_bf16 v[56:59], v[152:155], v[184:187], v[56:59]
	v_mfma_f32_16x16x32_bf16 v[56:59], v[156:159], v[188:191], v[56:59]
	v_mfma_f32_16x16x32_bf16 v[44:47], v[144:147], v[192:195], v[44:47]
	v_mfma_f32_16x16x32_bf16 v[44:47], v[148:151], v[196:199], v[44:47]
	v_mfma_f32_16x16x32_bf16 v[40:43], v[152:155], v[192:195], v[40:43]
	v_mfma_f32_16x16x32_bf16 v[40:43], v[156:159], v[196:199], v[40:43]
	v_mfma_f32_16x16x32_bf16 v[28:31], v[144:147], v[200:203], v[28:31]
	v_mfma_f32_16x16x32_bf16 v[28:31], v[148:151], v[204:207], v[28:31]
	v_mfma_f32_16x16x32_bf16 v[24:27], v[152:155], v[200:203], v[24:27]
	v_mfma_f32_16x16x32_bf16 v[24:27], v[156:159], v[204:207], v[24:27]
	v_mfma_f32_16x16x32_bf16 v[12:15], v[144:147], v[208:211], v[12:15]
	v_mfma_f32_16x16x32_bf16 v[12:15], v[148:151], v[212:215], v[12:15]
	v_mfma_f32_16x16x32_bf16 v[8:11], v[152:155], v[208:211], v[8:11]
	v_mfma_f32_16x16x32_bf16 v[8:11], v[156:159], v[212:215], v[8:11]
	v_mfma_f32_16x16x32_bf16 v[52:55], v[160:163], v[184:187], v[52:55]
	v_mfma_f32_16x16x32_bf16 v[52:55], v[164:167], v[188:191], v[52:55]
	v_mfma_f32_16x16x32_bf16 v[48:51], v[168:171], v[184:187], v[48:51]
	v_mfma_f32_16x16x32_bf16 v[48:51], v[172:175], v[188:191], v[48:51]
	v_mfma_f32_16x16x32_bf16 v[36:39], v[160:163], v[192:195], v[36:39]
	v_mfma_f32_16x16x32_bf16 v[36:39], v[164:167], v[196:199], v[36:39]
	v_mfma_f32_16x16x32_bf16 v[32:35], v[168:171], v[192:195], v[32:35]
	v_mfma_f32_16x16x32_bf16 v[32:35], v[172:175], v[196:199], v[32:35]
	v_mfma_f32_16x16x32_bf16 v[20:23], v[160:163], v[200:203], v[20:23]
	v_mfma_f32_16x16x32_bf16 v[20:23], v[164:167], v[204:207], v[20:23]
	v_mfma_f32_16x16x32_bf16 v[16:19], v[168:171], v[200:203], v[16:19]
	v_mfma_f32_16x16x32_bf16 v[16:19], v[172:175], v[204:207], v[16:19]
	s_setprio 2
	s_barrier
	v_mfma_f32_16x16x32_bf16 v[4:7], v[160:163], v[208:211], v[4:7]
	v_mfma_f32_16x16x32_bf16 v[4:7], v[164:167], v[212:215], v[4:7]
	v_mfma_f32_16x16x32_bf16 v[0:3], v[168:171], v[208:211], v[0:3]
	v_mfma_f32_16x16x32_bf16 v[0:3], v[172:175], v[212:215], v[0:3]
	s_setprio 0
	s_add_i32 s73, s73, 2
	s_add_u32 s6, s6, 0x100
	s_addc_u32 s7, s7, 0
	s_add_u32 s71, s71, 0x100
	s_addc_u32 s72, s72, 0
	s_cmp_gt_u32 s73, 13
.LBB0_952:
	ds_read_b128 v[144:147], v179
	ds_read_b128 v[148:151], v179 offset:1024
	ds_read_b128 v[152:155], v179 offset:2048
	ds_read_b128 v[156:159], v179 offset:3072
	ds_read_b128 v[160:163], v180
	ds_read_b128 v[164:167], v180 offset:1024
	ds_read_b128 v[168:171], v180 offset:2048
	ds_read_b128 v[172:175], v180 offset:3072
	s_add_u32 s40, s6, 0xfffc0080
	s_addc_u32 s41, s7, -1
	s_cmp_eq_u32 s73, 12
	s_cselect_b32 s45, s27, s41
	s_cselect_b32 s44, s39, s40
	s_cselect_b32 s41, s29, s72
	s_cselect_b32 s40, s43, s71
	v_lshl_add_u64 v[176:177], s[6:7], 0, v[136:137]
	s_add_i32 m0, s54, 0xc000
	ds_read_b128 v[184:187], v181
	ds_read_b128 v[188:191], v181 offset:1024
	ds_read_b128 v[192:195], v181 offset:2048
	ds_read_b128 v[196:199], v181 offset:3072
	ds_read_b128 v[200:203], v181 offset:4096
	ds_read_b128 v[204:207], v181 offset:5120
	ds_read_b128 v[208:211], v181 offset:6144
	ds_read_b128 v[212:215], v181 offset:7168
	global_load_lds_dwordx4 v[176:177], off
	s_add_i32 m0, s54, 0xe000
	v_lshl_add_u64 v[176:177], s[6:7], 0, v[138:139]
	global_load_lds_dwordx4 v[176:177], off
	s_waitcnt vmcnt(8) lgkmcnt(0)
	s_barrier
	s_setprio 1
	v_mfma_f32_16x16x32_bf16 v[124:127], v[144:147], v[184:187], v[124:127]
	v_mfma_f32_16x16x32_bf16 v[124:127], v[148:151], v[188:191], v[124:127]
	v_mfma_f32_16x16x32_bf16 v[120:123], v[152:155], v[184:187], v[120:123]
	v_mfma_f32_16x16x32_bf16 v[120:123], v[156:159], v[188:191], v[120:123]
	v_mfma_f32_16x16x32_bf16 v[108:111], v[144:147], v[192:195], v[108:111]
	v_mfma_f32_16x16x32_bf16 v[108:111], v[148:151], v[196:199], v[108:111]
	v_mfma_f32_16x16x32_bf16 v[104:107], v[152:155], v[192:195], v[104:107]
	v_mfma_f32_16x16x32_bf16 v[104:107], v[156:159], v[196:199], v[104:107]
	v_mfma_f32_16x16x32_bf16 v[92:95], v[144:147], v[200:203], v[92:95]
	v_mfma_f32_16x16x32_bf16 v[92:95], v[148:151], v[204:207], v[92:95]
	v_mfma_f32_16x16x32_bf16 v[88:91], v[152:155], v[200:203], v[88:91]
	v_mfma_f32_16x16x32_bf16 v[88:91], v[156:159], v[204:207], v[88:91]
	v_mfma_f32_16x16x32_bf16 v[76:79], v[144:147], v[208:211], v[76:79]
	v_mfma_f32_16x16x32_bf16 v[76:79], v[148:151], v[212:215], v[76:79]
	v_mfma_f32_16x16x32_bf16 v[72:75], v[152:155], v[208:211], v[72:75]
	v_mfma_f32_16x16x32_bf16 v[72:75], v[156:159], v[212:215], v[72:75]
	v_mfma_f32_16x16x32_bf16 v[116:119], v[160:163], v[184:187], v[116:119]
	v_mfma_f32_16x16x32_bf16 v[116:119], v[164:167], v[188:191], v[116:119]
	v_mfma_f32_16x16x32_bf16 v[112:115], v[168:171], v[184:187], v[112:115]
	v_mfma_f32_16x16x32_bf16 v[112:115], v[172:175], v[188:191], v[112:115]
	v_mfma_f32_16x16x32_bf16 v[100:103], v[160:163], v[192:195], v[100:103]
	v_mfma_f32_16x16x32_bf16 v[100:103], v[164:167], v[196:199], v[100:103]
	v_mfma_f32_16x16x32_bf16 v[96:99], v[168:171], v[192:195], v[96:99]
	v_mfma_f32_16x16x32_bf16 v[96:99], v[172:175], v[196:199], v[96:99]
	v_mfma_f32_16x16x32_bf16 v[84:87], v[160:163], v[200:203], v[84:87]
	v_mfma_f32_16x16x32_bf16 v[84:87], v[164:167], v[204:207], v[84:87]
	v_mfma_f32_16x16x32_bf16 v[80:83], v[168:171], v[200:203], v[80:83]
	v_mfma_f32_16x16x32_bf16 v[80:83], v[172:175], v[204:207], v[80:83]
	s_setprio 2
	s_barrier
	v_mfma_f32_16x16x32_bf16 v[68:71], v[160:163], v[208:211], v[68:71]
	v_mfma_f32_16x16x32_bf16 v[68:71], v[164:167], v[212:215], v[68:71]
	v_mfma_f32_16x16x32_bf16 v[64:67], v[168:171], v[208:211], v[64:67]
	v_mfma_f32_16x16x32_bf16 v[64:67], v[172:175], v[212:215], v[64:67]
	s_setprio 2
	s_add_i32 s74, s69, s51
	v_lshl_add_u64 v[176:177], s[40:41], 0, v[130:131]
	s_mov_b32 m0, s74
	ds_read_b128 v[184:187], v181 offset:16384
	ds_read_b128 v[188:191], v181 offset:17408
	ds_read_b128 v[192:195], v181 offset:18432
	ds_read_b128 v[196:199], v181 offset:19456
	ds_read_b128 v[200:203], v181 offset:20480
	ds_read_b128 v[204:207], v181 offset:21504
	ds_read_b128 v[208:211], v181 offset:22528
	ds_read_b128 v[212:215], v181 offset:23552
	global_load_lds_dwordx4 v[176:177], off
	s_add_i32 m0, s74, 0x2000
	s_add_u32 s74, s40, 0x40000
	v_lshl_add_u64 v[216:217], s[40:41], 0, v[134:135]
	s_addc_u32 s75, s41, 0
	s_add_i32 s76, s70, s51
	global_load_lds_dwordx4 v[216:217], off
	v_lshl_add_u64 v[218:219], s[74:75], 0, v[130:131]
	s_mov_b32 m0, s76
	v_lshl_add_u64 v[220:221], s[44:45], 0, v[132:133]
	global_load_lds_dwordx4 v[218:219], off
	s_add_i32 m0, s76, 0x2000
	v_lshl_add_u64 v[218:219], s[74:75], 0, v[134:135]
	global_load_lds_dwordx4 v[218:219], off
	s_mov_b32 m0, s54
	v_lshl_add_u64 v[218:219], s[44:45], 0, v[128:129]
	global_load_lds_dwordx4 v[218:219], off
	s_mov_b32 m0, s55
	s_nop 0
	global_load_lds_dwordx4 v[220:221], off
	s_waitcnt vmcnt(8) lgkmcnt(0)
	s_barrier
	s_setprio 1
	v_mfma_f32_16x16x32_bf16 v[60:63], v[144:147], v[184:187], v[60:63]
	v_mfma_f32_16x16x32_bf16 v[60:63], v[148:151], v[188:191], v[60:63]
	v_mfma_f32_16x16x32_bf16 v[56:59], v[152:155], v[184:187], v[56:59]
	v_mfma_f32_16x16x32_bf16 v[56:59], v[156:159], v[188:191], v[56:59]
	v_mfma_f32_16x16x32_bf16 v[44:47], v[144:147], v[192:195], v[44:47]
	v_mfma_f32_16x16x32_bf16 v[44:47], v[148:151], v[196:199], v[44:47]
	v_mfma_f32_16x16x32_bf16 v[40:43], v[152:155], v[192:195], v[40:43]
	v_mfma_f32_16x16x32_bf16 v[40:43], v[156:159], v[196:199], v[40:43]
	v_mfma_f32_16x16x32_bf16 v[28:31], v[144:147], v[200:203], v[28:31]
	v_mfma_f32_16x16x32_bf16 v[28:31], v[148:151], v[204:207], v[28:31]
	v_mfma_f32_16x16x32_bf16 v[24:27], v[152:155], v[200:203], v[24:27]
	v_mfma_f32_16x16x32_bf16 v[24:27], v[156:159], v[204:207], v[24:27]
	v_mfma_f32_16x16x32_bf16 v[12:15], v[144:147], v[208:211], v[12:15]
	v_mfma_f32_16x16x32_bf16 v[12:15], v[148:151], v[212:215], v[12:15]
	v_mfma_f32_16x16x32_bf16 v[8:11], v[152:155], v[208:211], v[8:11]
	v_mfma_f32_16x16x32_bf16 v[8:11], v[156:159], v[212:215], v[8:11]
	v_mfma_f32_16x16x32_bf16 v[52:55], v[160:163], v[184:187], v[52:55]
	v_mfma_f32_16x16x32_bf16 v[52:55], v[164:167], v[188:191], v[52:55]
	v_mfma_f32_16x16x32_bf16 v[48:51], v[168:171], v[184:187], v[48:51]
	v_mfma_f32_16x16x32_bf16 v[48:51], v[172:175], v[188:191], v[48:51]
	v_mfma_f32_16x16x32_bf16 v[36:39], v[160:163], v[192:195], v[36:39]
	v_mfma_f32_16x16x32_bf16 v[36:39], v[164:167], v[196:199], v[36:39]
	v_mfma_f32_16x16x32_bf16 v[32:35], v[168:171], v[192:195], v[32:35]
	v_mfma_f32_16x16x32_bf16 v[32:35], v[172:175], v[196:199], v[32:35]
	v_mfma_f32_16x16x32_bf16 v[20:23], v[160:163], v[200:203], v[20:23]
	v_mfma_f32_16x16x32_bf16 v[20:23], v[164:167], v[204:207], v[20:23]
	v_mfma_f32_16x16x32_bf16 v[16:19], v[168:171], v[200:203], v[16:19]
	v_mfma_f32_16x16x32_bf16 v[16:19], v[172:175], v[204:207], v[16:19]
	s_setprio 2
	s_barrier
	v_mfma_f32_16x16x32_bf16 v[4:7], v[160:163], v[208:211], v[4:7]
	v_mfma_f32_16x16x32_bf16 v[4:7], v[164:167], v[212:215], v[4:7]
	v_mfma_f32_16x16x32_bf16 v[0:3], v[168:171], v[208:211], v[0:3]
	v_mfma_f32_16x16x32_bf16 v[0:3], v[172:175], v[212:215], v[0:3]
	s_setprio 0
	s_add_i32 s74, 0, 0x18000
	s_add_i32 s75, 0, 0x1c000
	v_add_u32_e32 v156, s74, v178
	v_add_u32_e32 v172, s75, v178
	ds_read_b128 v[144:147], v156
	ds_read_b128 v[148:151], v156 offset:1024
	ds_read_b128 v[152:155], v156 offset:2048
	ds_read_b128 v[156:159], v156 offset:3072
	ds_read_b128 v[160:163], v172
	ds_read_b128 v[164:167], v172 offset:1024
	ds_read_b128 v[168:171], v172 offset:2048
	ds_read_b128 v[172:175], v172 offset:3072
	s_add_u32 s44, s44, 0x40000
	s_addc_u32 s45, s45, 0
	s_mov_b32 m0, s56
	v_lshl_add_u64 v[222:223], s[44:45], 0, v[128:129]
	ds_read_b128 v[184:187], v181 offset:32768
	ds_read_b128 v[188:191], v181 offset:33792
	ds_read_b128 v[192:195], v181 offset:34816
	ds_read_b128 v[196:199], v181 offset:35840
	ds_read_b128 v[200:203], v181 offset:36864
	ds_read_b128 v[204:207], v181 offset:37888
	ds_read_b128 v[208:211], v181 offset:38912
	ds_read_b128 v[212:215], v181 offset:39936
	global_load_lds_dwordx4 v[222:223], off
	s_mov_b32 m0, s57
	v_lshl_add_u64 v[222:223], s[44:45], 0, v[132:133]
	global_load_lds_dwordx4 v[222:223], off
	s_waitcnt vmcnt(8) lgkmcnt(0)
	s_barrier
	s_setprio 1
	v_mfma_f32_16x16x32_bf16 v[124:127], v[144:147], v[184:187], v[124:127]
	v_mfma_f32_16x16x32_bf16 v[124:127], v[148:151], v[188:191], v[124:127]
	v_mfma_f32_16x16x32_bf16 v[120:123], v[152:155], v[184:187], v[120:123]
	v_mfma_f32_16x16x32_bf16 v[120:123], v[156:159], v[188:191], v[120:123]
	v_mfma_f32_16x16x32_bf16 v[108:111], v[144:147], v[192:195], v[108:111]
	v_mfma_f32_16x16x32_bf16 v[108:111], v[148:151], v[196:199], v[108:111]
	v_mfma_f32_16x16x32_bf16 v[104:107], v[152:155], v[192:195], v[104:107]
	v_mfma_f32_16x16x32_bf16 v[104:107], v[156:159], v[196:199], v[104:107]
	v_mfma_f32_16x16x32_bf16 v[92:95], v[144:147], v[200:203], v[92:95]
	v_mfma_f32_16x16x32_bf16 v[92:95], v[148:151], v[204:207], v[92:95]
	v_mfma_f32_16x16x32_bf16 v[88:91], v[152:155], v[200:203], v[88:91]
	v_mfma_f32_16x16x32_bf16 v[88:91], v[156:159], v[204:207], v[88:91]
	v_mfma_f32_16x16x32_bf16 v[76:79], v[144:147], v[208:211], v[76:79]
	v_mfma_f32_16x16x32_bf16 v[76:79], v[148:151], v[212:215], v[76:79]
	v_mfma_f32_16x16x32_bf16 v[72:75], v[152:155], v[208:211], v[72:75]
	v_mfma_f32_16x16x32_bf16 v[72:75], v[156:159], v[212:215], v[72:75]
	v_mfma_f32_16x16x32_bf16 v[116:119], v[160:163], v[184:187], v[116:119]
	v_mfma_f32_16x16x32_bf16 v[116:119], v[164:167], v[188:191], v[116:119]
	v_mfma_f32_16x16x32_bf16 v[112:115], v[168:171], v[184:187], v[112:115]
	v_mfma_f32_16x16x32_bf16 v[112:115], v[172:175], v[188:191], v[112:115]
	v_mfma_f32_16x16x32_bf16 v[100:103], v[160:163], v[192:195], v[100:103]
	v_mfma_f32_16x16x32_bf16 v[100:103], v[164:167], v[196:199], v[100:103]
	v_mfma_f32_16x16x32_bf16 v[96:99], v[168:171], v[192:195], v[96:99]
	v_mfma_f32_16x16x32_bf16 v[96:99], v[172:175], v[196:199], v[96:99]
	v_mfma_f32_16x16x32_bf16 v[84:87], v[160:163], v[200:203], v[84:87]
	v_mfma_f32_16x16x32_bf16 v[84:87], v[164:167], v[204:207], v[84:87]
	v_mfma_f32_16x16x32_bf16 v[80:83], v[168:171], v[200:203], v[80:83]
	v_mfma_f32_16x16x32_bf16 v[80:83], v[172:175], v[204:207], v[80:83]
	s_setprio 2
	s_barrier
	v_mfma_f32_16x16x32_bf16 v[68:71], v[160:163], v[208:211], v[68:71]
	v_mfma_f32_16x16x32_bf16 v[68:71], v[164:167], v[212:215], v[68:71]
	v_mfma_f32_16x16x32_bf16 v[64:67], v[168:171], v[208:211], v[64:67]
	v_mfma_f32_16x16x32_bf16 v[64:67], v[172:175], v[212:215], v[64:67]
	s_setprio 2
	s_add_i32 s44, s74, s51
	v_lshl_add_u64 v[176:177], v[176:177], 0, s[22:23]
	s_mov_b32 m0, s44
	ds_read_b128 v[184:187], v181 offset:49152
	ds_read_b128 v[188:191], v181 offset:50176
	ds_read_b128 v[192:195], v181 offset:51200
	ds_read_b128 v[196:199], v181 offset:52224
	ds_read_b128 v[200:203], v181 offset:53248
	ds_read_b128 v[204:207], v181 offset:54272
	ds_read_b128 v[208:211], v181 offset:55296
	ds_read_b128 v[212:215], v181 offset:56320
	global_load_lds_dwordx4 v[176:177], off
	s_add_i32 m0, s44, 0x2000
	s_add_u32 s40, s40, 0x40080
	v_lshl_add_u64 v[176:177], v[216:217], 0, s[22:23]
	s_addc_u32 s41, s41, 0
	s_add_i32 s44, s75, s51
	global_load_lds_dwordx4 v[176:177], off
	s_mov_b32 m0, s44
	v_lshl_add_u64 v[176:177], s[40:41], 0, v[130:131]
	global_load_lds_dwordx4 v[176:177], off
	s_add_i32 m0, s44, 0x2000
	v_lshl_add_u64 v[176:177], s[40:41], 0, v[134:135]
	global_load_lds_dwordx4 v[176:177], off
	s_mov_b32 m0, s64
	v_lshl_add_u64 v[176:177], v[218:219], 0, s[22:23]
	global_load_lds_dwordx4 v[176:177], off
	s_mov_b32 m0, s65
	v_lshl_add_u64 v[176:177], v[220:221], 0, s[22:23]
	global_load_lds_dwordx4 v[176:177], off
	s_waitcnt vmcnt(8) lgkmcnt(0)
	s_barrier
	s_setprio 1
	v_mfma_f32_16x16x32_bf16 v[60:63], v[144:147], v[184:187], v[60:63]
	v_mfma_f32_16x16x32_bf16 v[60:63], v[148:151], v[188:191], v[60:63]
	v_mfma_f32_16x16x32_bf16 v[56:59], v[152:155], v[184:187], v[56:59]
	v_mfma_f32_16x16x32_bf16 v[56:59], v[156:159], v[188:191], v[56:59]
	v_mfma_f32_16x16x32_bf16 v[44:47], v[144:147], v[192:195], v[44:47]
	v_mfma_f32_16x16x32_bf16 v[44:47], v[148:151], v[196:199], v[44:47]
	v_mfma_f32_16x16x32_bf16 v[40:43], v[152:155], v[192:195], v[40:43]
	v_mfma_f32_16x16x32_bf16 v[40:43], v[156:159], v[196:199], v[40:43]
	v_mfma_f32_16x16x32_bf16 v[28:31], v[144:147], v[200:203], v[28:31]
	v_mfma_f32_16x16x32_bf16 v[28:31], v[148:151], v[204:207], v[28:31]
	v_mfma_f32_16x16x32_bf16 v[24:27], v[152:155], v[200:203], v[24:27]
	v_mfma_f32_16x16x32_bf16 v[24:27], v[156:159], v[204:207], v[24:27]
	v_mfma_f32_16x16x32_bf16 v[12:15], v[144:147], v[208:211], v[12:15]
	v_mfma_f32_16x16x32_bf16 v[12:15], v[148:151], v[212:215], v[12:15]
	v_mfma_f32_16x16x32_bf16 v[8:11], v[152:155], v[208:211], v[8:11]
	v_mfma_f32_16x16x32_bf16 v[8:11], v[156:159], v[212:215], v[8:11]
	v_mfma_f32_16x16x32_bf16 v[52:55], v[160:163], v[184:187], v[52:55]
	v_mfma_f32_16x16x32_bf16 v[52:55], v[164:167], v[188:191], v[52:55]
	v_mfma_f32_16x16x32_bf16 v[48:51], v[168:171], v[184:187], v[48:51]
	v_mfma_f32_16x16x32_bf16 v[48:51], v[172:175], v[188:191], v[48:51]
	v_mfma_f32_16x16x32_bf16 v[36:39], v[160:163], v[192:195], v[36:39]
	v_mfma_f32_16x16x32_bf16 v[36:39], v[164:167], v[196:199], v[36:39]
	v_mfma_f32_16x16x32_bf16 v[32:35], v[168:171], v[192:195], v[32:35]
	v_mfma_f32_16x16x32_bf16 v[32:35], v[172:175], v[196:199], v[32:35]
	v_mfma_f32_16x16x32_bf16 v[20:23], v[160:163], v[200:203], v[20:23]
	v_mfma_f32_16x16x32_bf16 v[20:23], v[164:167], v[204:207], v[20:23]
	v_mfma_f32_16x16x32_bf16 v[16:19], v[168:171], v[200:203], v[16:19]
	v_mfma_f32_16x16x32_bf16 v[16:19], v[172:175], v[204:207], v[16:19]
	s_setprio 2
	s_barrier
	v_mfma_f32_16x16x32_bf16 v[4:7], v[160:163], v[208:211], v[4:7]
	v_mfma_f32_16x16x32_bf16 v[4:7], v[164:167], v[212:215], v[4:7]
	v_mfma_f32_16x16x32_bf16 v[0:3], v[168:171], v[208:211], v[0:3]
	v_mfma_f32_16x16x32_bf16 v[0:3], v[172:175], v[212:215], v[0:3]
	s_setprio 0
	s_add_i32 s73, s73, 2
	s_add_u32 s6, s6, 0x100
	s_addc_u32 s7, s7, 0
	s_add_u32 s71, s71, 0x100
	s_addc_u32 s72, s72, 0
	s_cmp_gt_u32 s73, 13
	s_cbranch_scc0 .LBB0_952

.LBB0_1145:
	s_ashr_i32 s23, s22, 31
	s_lshl_b64 s[26:27], s[22:23], 19
	s_add_u32 s26, s45, s26
	s_addc_u32 s27, s46, s27
	s_and_b64 s[28:29], s[4:5], exec
	s_cselect_b32 s23, s27, s39
	s_cselect_b32 s31, s26, s38
	s_ashr_i32 s25, s24, 31
	s_lshl_b64 s[28:29], s[24:25], 19
	s_add_u32 s28, s47, s28
	s_addc_u32 s29, s48, s29
	s_and_b64 s[42:43], s[4:5], exec
	s_cselect_b32 s25, s29, s41
	s_cselect_b32 s37, s28, s40
	s_add_u32 s38, s38, 0x40080
	s_addc_u32 s39, s39, 0
	s_add_u32 s64, s40, 0x100
	s_addc_u32 s65, s41, 0
	s_mov_b32 s66, -2
	ds_read_b128 v[120:123], v233
	ds_read_b128 v[132:135], v233 offset:1024
	ds_read_b128 v[136:139], v233 offset:2048
	ds_read_b128 v[140:143], v233 offset:3072
	ds_read_b128 v[144:147], v234
	ds_read_b128 v[148:151], v234 offset:1024
	ds_read_b128 v[152:155], v234 offset:2048
	ds_read_b128 v[156:159], v234 offset:3072
	s_add_u32 s40, s38, 0xfffc0080
	s_addc_u32 s41, s39, -1
	s_cmp_eq_u32 s66, 12
	s_cselect_b32 s43, s23, s41
	s_cselect_b32 s42, s31, s40
	s_cselect_b32 s41, s25, s65
	s_cselect_b32 s40, s37, s64
	v_lshl_add_u64 v[208:209], s[38:39], 0, v[192:193]
	s_add_i32 m0, s50, 0xc000
	ds_read_b128 v[160:163], v235
	ds_read_b128 v[164:167], v235 offset:1024
	ds_read_b128 v[168:171], v235 offset:2048
	ds_read_b128 v[172:175], v235 offset:3072
	ds_read_b128 v[176:179], v235 offset:4096
	ds_read_b128 v[180:183], v235 offset:5120
	ds_read_b128 v[200:203], v235 offset:6144
	ds_read_b128 v[204:207], v235 offset:7168
	global_load_lds_dwordx4 v[208:209], off
	s_add_i32 m0, s50, 0xe000
	v_lshl_add_u64 v[208:209], s[38:39], 0, v[194:195]
	global_load_lds_dwordx4 v[208:209], off
	s_waitcnt vmcnt(8) lgkmcnt(0)
	s_barrier
	s_setprio 1
	v_mfma_f32_16x16x32_bf16 v[128:131], v[120:123], v[160:163], 0
	v_mfma_f32_16x16x32_bf16 v[128:131], v[132:135], v[164:167], v[128:131]
	v_mfma_f32_16x16x32_bf16 v[124:127], v[136:139], v[160:163], 0
	v_mfma_f32_16x16x32_bf16 v[124:127], v[140:143], v[164:167], v[124:127]
	v_mfma_f32_16x16x32_bf16 v[108:111], v[120:123], v[168:171], 0
	v_mfma_f32_16x16x32_bf16 v[108:111], v[132:135], v[172:175], v[108:111]
	v_mfma_f32_16x16x32_bf16 v[104:107], v[136:139], v[168:171], 0
	v_mfma_f32_16x16x32_bf16 v[104:107], v[140:143], v[172:175], v[104:107]
	v_mfma_f32_16x16x32_bf16 v[92:95], v[120:123], v[176:179], 0
	v_mfma_f32_16x16x32_bf16 v[92:95], v[132:135], v[180:183], v[92:95]
	v_mfma_f32_16x16x32_bf16 v[88:91], v[136:139], v[176:179], 0
	v_mfma_f32_16x16x32_bf16 v[88:91], v[140:143], v[180:183], v[88:91]
	v_mfma_f32_16x16x32_bf16 v[76:79], v[120:123], v[200:203], 0
	v_mfma_f32_16x16x32_bf16 v[76:79], v[132:135], v[204:207], v[76:79]
	v_mfma_f32_16x16x32_bf16 v[72:75], v[136:139], v[200:203], 0
	v_mfma_f32_16x16x32_bf16 v[72:75], v[140:143], v[204:207], v[72:75]
	v_mfma_f32_16x16x32_bf16 v[116:119], v[144:147], v[160:163], 0
	v_mfma_f32_16x16x32_bf16 v[116:119], v[148:151], v[164:167], v[116:119]
	v_mfma_f32_16x16x32_bf16 v[112:115], v[152:155], v[160:163], 0
	v_mfma_f32_16x16x32_bf16 v[112:115], v[156:159], v[164:167], v[112:115]
	v_mfma_f32_16x16x32_bf16 v[100:103], v[144:147], v[168:171], 0
	v_mfma_f32_16x16x32_bf16 v[100:103], v[148:151], v[172:175], v[100:103]
	v_mfma_f32_16x16x32_bf16 v[96:99], v[152:155], v[168:171], 0
	v_mfma_f32_16x16x32_bf16 v[96:99], v[156:159], v[172:175], v[96:99]
	v_mfma_f32_16x16x32_bf16 v[84:87], v[144:147], v[176:179], 0
	v_mfma_f32_16x16x32_bf16 v[84:87], v[148:151], v[180:183], v[84:87]
	v_mfma_f32_16x16x32_bf16 v[80:83], v[152:155], v[176:179], 0
	v_mfma_f32_16x16x32_bf16 v[80:83], v[156:159], v[180:183], v[80:83]
	s_setprio 2
	s_barrier
	v_mfma_f32_16x16x32_bf16 v[68:71], v[144:147], v[200:203], 0
	v_mfma_f32_16x16x32_bf16 v[68:71], v[148:151], v[204:207], v[68:71]
	v_mfma_f32_16x16x32_bf16 v[64:67], v[152:155], v[200:203], 0
	v_mfma_f32_16x16x32_bf16 v[64:67], v[156:159], v[204:207], v[64:67]
	s_setprio 2
	s_add_i32 s67, s62, s49
	v_lshl_add_u64 v[208:209], s[40:41], 0, v[186:187]
	s_mov_b32 m0, s67
	ds_read_b128 v[160:163], v235 offset:16384
	ds_read_b128 v[164:167], v235 offset:17408
	ds_read_b128 v[168:171], v235 offset:18432
	ds_read_b128 v[172:175], v235 offset:19456
	ds_read_b128 v[176:179], v235 offset:20480
	ds_read_b128 v[180:183], v235 offset:21504
	ds_read_b128 v[200:203], v235 offset:22528
	ds_read_b128 v[204:207], v235 offset:23552
	global_load_lds_dwordx4 v[208:209], off
	s_add_i32 m0, s67, 0x2000
	s_add_u32 s68, s40, 0x40000
	v_lshl_add_u64 v[210:211], s[40:41], 0, v[190:191]
	s_addc_u32 s69, s41, 0
	s_add_i32 s67, s63, s49
	global_load_lds_dwordx4 v[210:211], off
	v_lshl_add_u64 v[212:213], s[68:69], 0, v[186:187]
	s_mov_b32 m0, s67
	v_lshl_add_u64 v[214:215], s[42:43], 0, v[188:189]
	global_load_lds_dwordx4 v[212:213], off
	s_add_i32 m0, s67, 0x2000
	v_lshl_add_u64 v[212:213], s[68:69], 0, v[190:191]
	global_load_lds_dwordx4 v[212:213], off
	s_mov_b32 m0, s50
	v_lshl_add_u64 v[212:213], s[42:43], 0, v[184:185]
	global_load_lds_dwordx4 v[212:213], off
	s_mov_b32 m0, s51
	s_nop 0
	global_load_lds_dwordx4 v[214:215], off
	s_waitcnt vmcnt(8) lgkmcnt(0)
	s_barrier
	s_setprio 1
	v_mfma_f32_16x16x32_bf16 v[60:63], v[120:123], v[160:163], 0
	v_mfma_f32_16x16x32_bf16 v[60:63], v[132:135], v[164:167], v[60:63]
	v_mfma_f32_16x16x32_bf16 v[56:59], v[136:139], v[160:163], 0
	v_mfma_f32_16x16x32_bf16 v[56:59], v[140:143], v[164:167], v[56:59]
	v_mfma_f32_16x16x32_bf16 v[44:47], v[120:123], v[168:171], 0
	v_mfma_f32_16x16x32_bf16 v[44:47], v[132:135], v[172:175], v[44:47]
	v_mfma_f32_16x16x32_bf16 v[40:43], v[136:139], v[168:171], 0
	v_mfma_f32_16x16x32_bf16 v[40:43], v[140:143], v[172:175], v[40:43]
	v_mfma_f32_16x16x32_bf16 v[28:31], v[120:123], v[176:179], 0
	v_mfma_f32_16x16x32_bf16 v[28:31], v[132:135], v[180:183], v[28:31]
	v_mfma_f32_16x16x32_bf16 v[24:27], v[136:139], v[176:179], 0
	v_mfma_f32_16x16x32_bf16 v[24:27], v[140:143], v[180:183], v[24:27]
	v_mfma_f32_16x16x32_bf16 v[12:15], v[120:123], v[200:203], 0
	v_mfma_f32_16x16x32_bf16 v[12:15], v[132:135], v[204:207], v[12:15]
	v_mfma_f32_16x16x32_bf16 v[8:11], v[136:139], v[200:203], 0
	v_mfma_f32_16x16x32_bf16 v[8:11], v[140:143], v[204:207], v[8:11]
	v_mfma_f32_16x16x32_bf16 v[52:55], v[144:147], v[160:163], 0
	v_mfma_f32_16x16x32_bf16 v[52:55], v[148:151], v[164:167], v[52:55]
	v_mfma_f32_16x16x32_bf16 v[48:51], v[152:155], v[160:163], 0
	v_mfma_f32_16x16x32_bf16 v[48:51], v[156:159], v[164:167], v[48:51]
	v_mfma_f32_16x16x32_bf16 v[36:39], v[144:147], v[168:171], 0
	v_mfma_f32_16x16x32_bf16 v[36:39], v[148:151], v[172:175], v[36:39]
	v_mfma_f32_16x16x32_bf16 v[32:35], v[152:155], v[168:171], 0
	v_mfma_f32_16x16x32_bf16 v[32:35], v[156:159], v[172:175], v[32:35]
	v_mfma_f32_16x16x32_bf16 v[20:23], v[144:147], v[176:179], 0
	v_mfma_f32_16x16x32_bf16 v[20:23], v[148:151], v[180:183], v[20:23]
	v_mfma_f32_16x16x32_bf16 v[16:19], v[152:155], v[176:179], 0
	v_mfma_f32_16x16x32_bf16 v[16:19], v[156:159], v[180:183], v[16:19]
	s_setprio 2
	s_barrier
	v_mfma_f32_16x16x32_bf16 v[4:7], v[144:147], v[200:203], 0
	v_mfma_f32_16x16x32_bf16 v[4:7], v[148:151], v[204:207], v[4:7]
	v_mfma_f32_16x16x32_bf16 v[0:3], v[152:155], v[200:203], 0
	v_mfma_f32_16x16x32_bf16 v[0:3], v[156:159], v[204:207], v[0:3]
	s_setprio 0
	s_add_i32 s67, 0, 0x18000
	s_add_i32 s68, 0, 0x1c000
	v_add_u32_e32 v140, s67, v232
	v_add_u32_e32 v156, s68, v232
	ds_read_b128 v[120:123], v140
	ds_read_b128 v[132:135], v140 offset:1024
	ds_read_b128 v[136:139], v140 offset:2048
	ds_read_b128 v[140:143], v140 offset:3072
	ds_read_b128 v[144:147], v156
	ds_read_b128 v[148:151], v156 offset:1024
	ds_read_b128 v[152:155], v156 offset:2048
	ds_read_b128 v[156:159], v156 offset:3072
	s_add_u32 s42, s42, 0x40000
	s_addc_u32 s43, s43, 0
	s_mov_b32 m0, s54
	v_lshl_add_u64 v[216:217], s[42:43], 0, v[184:185]
	ds_read_b128 v[160:163], v235 offset:32768
	ds_read_b128 v[164:167], v235 offset:33792
	ds_read_b128 v[168:171], v235 offset:34816
	ds_read_b128 v[172:175], v235 offset:35840
	ds_read_b128 v[176:179], v235 offset:36864
	ds_read_b128 v[180:183], v235 offset:37888
	ds_read_b128 v[200:203], v235 offset:38912
	ds_read_b128 v[204:207], v235 offset:39936
	global_load_lds_dwordx4 v[216:217], off
	s_mov_b32 m0, s55
	v_lshl_add_u64 v[216:217], s[42:43], 0, v[188:189]
	global_load_lds_dwordx4 v[216:217], off
	s_waitcnt vmcnt(8) lgkmcnt(0)
	s_barrier
	s_setprio 1
	v_mfma_f32_16x16x32_bf16 v[128:131], v[120:123], v[160:163], v[128:131]
	v_mfma_f32_16x16x32_bf16 v[128:131], v[132:135], v[164:167], v[128:131]
	v_mfma_f32_16x16x32_bf16 v[124:127], v[136:139], v[160:163], v[124:127]
	v_mfma_f32_16x16x32_bf16 v[124:127], v[140:143], v[164:167], v[124:127]
	v_mfma_f32_16x16x32_bf16 v[108:111], v[120:123], v[168:171], v[108:111]
	v_mfma_f32_16x16x32_bf16 v[108:111], v[132:135], v[172:175], v[108:111]
	v_mfma_f32_16x16x32_bf16 v[104:107], v[136:139], v[168:171], v[104:107]
	v_mfma_f32_16x16x32_bf16 v[104:107], v[140:143], v[172:175], v[104:107]
	v_mfma_f32_16x16x32_bf16 v[92:95], v[120:123], v[176:179], v[92:95]
	v_mfma_f32_16x16x32_bf16 v[92:95], v[132:135], v[180:183], v[92:95]
	v_mfma_f32_16x16x32_bf16 v[88:91], v[136:139], v[176:179], v[88:91]
	v_mfma_f32_16x16x32_bf16 v[88:91], v[140:143], v[180:183], v[88:91]
	v_mfma_f32_16x16x32_bf16 v[76:79], v[120:123], v[200:203], v[76:79]
	v_mfma_f32_16x16x32_bf16 v[76:79], v[132:135], v[204:207], v[76:79]
	v_mfma_f32_16x16x32_bf16 v[72:75], v[136:139], v[200:203], v[72:75]
	v_mfma_f32_16x16x32_bf16 v[72:75], v[140:143], v[204:207], v[72:75]
	v_mfma_f32_16x16x32_bf16 v[116:119], v[144:147], v[160:163], v[116:119]
	v_mfma_f32_16x16x32_bf16 v[116:119], v[148:151], v[164:167], v[116:119]
	v_mfma_f32_16x16x32_bf16 v[112:115], v[152:155], v[160:163], v[112:115]
	v_mfma_f32_16x16x32_bf16 v[112:115], v[156:159], v[164:167], v[112:115]
	v_mfma_f32_16x16x32_bf16 v[100:103], v[144:147], v[168:171], v[100:103]
	v_mfma_f32_16x16x32_bf16 v[100:103], v[148:151], v[172:175], v[100:103]
	v_mfma_f32_16x16x32_bf16 v[96:99], v[152:155], v[168:171], v[96:99]
	v_mfma_f32_16x16x32_bf16 v[96:99], v[156:159], v[172:175], v[96:99]
	v_mfma_f32_16x16x32_bf16 v[84:87], v[144:147], v[176:179], v[84:87]
	v_mfma_f32_16x16x32_bf16 v[84:87], v[148:151], v[180:183], v[84:87]
	v_mfma_f32_16x16x32_bf16 v[80:83], v[152:155], v[176:179], v[80:83]
	v_mfma_f32_16x16x32_bf16 v[80:83], v[156:159], v[180:183], v[80:83]
	s_setprio 2
	s_barrier
	v_mfma_f32_16x16x32_bf16 v[68:71], v[144:147], v[200:203], v[68:71]
	v_mfma_f32_16x16x32_bf16 v[68:71], v[148:151], v[204:207], v[68:71]
	v_mfma_f32_16x16x32_bf16 v[64:67], v[152:155], v[200:203], v[64:67]
	v_mfma_f32_16x16x32_bf16 v[64:67], v[156:159], v[204:207], v[64:67]
	s_setprio 2
	s_add_i32 s42, s67, s49
	v_lshl_add_u64 v[208:209], v[208:209], 0, s[18:19]
	s_mov_b32 m0, s42
	ds_read_b128 v[160:163], v235 offset:49152
	ds_read_b128 v[164:167], v235 offset:50176
	ds_read_b128 v[168:171], v235 offset:51200
	ds_read_b128 v[172:175], v235 offset:52224
	ds_read_b128 v[176:179], v235 offset:53248
	ds_read_b128 v[180:183], v235 offset:54272
	ds_read_b128 v[200:203], v235 offset:55296
	ds_read_b128 v[204:207], v235 offset:56320
	global_load_lds_dwordx4 v[208:209], off
	s_add_i32 m0, s42, 0x2000
	s_add_u32 s40, s40, 0x40080
	v_lshl_add_u64 v[208:209], v[210:211], 0, s[18:19]
	s_addc_u32 s41, s41, 0
	s_add_i32 s42, s68, s49
	global_load_lds_dwordx4 v[208:209], off
	s_mov_b32 m0, s42
	v_lshl_add_u64 v[208:209], s[40:41], 0, v[186:187]
	global_load_lds_dwordx4 v[208:209], off
	s_add_i32 m0, s42, 0x2000
	v_lshl_add_u64 v[208:209], s[40:41], 0, v[190:191]
	global_load_lds_dwordx4 v[208:209], off
	s_mov_b32 m0, s57
	v_lshl_add_u64 v[208:209], v[212:213], 0, s[18:19]
	global_load_lds_dwordx4 v[208:209], off
	s_mov_b32 m0, s58
	v_lshl_add_u64 v[208:209], v[214:215], 0, s[18:19]
	global_load_lds_dwordx4 v[208:209], off
	s_waitcnt vmcnt(8) lgkmcnt(0)
	s_barrier
	s_setprio 1
	v_mfma_f32_16x16x32_bf16 v[60:63], v[120:123], v[160:163], v[60:63]
	v_mfma_f32_16x16x32_bf16 v[60:63], v[132:135], v[164:167], v[60:63]
	v_mfma_f32_16x16x32_bf16 v[56:59], v[136:139], v[160:163], v[56:59]
	v_mfma_f32_16x16x32_bf16 v[56:59], v[140:143], v[164:167], v[56:59]
	v_mfma_f32_16x16x32_bf16 v[44:47], v[120:123], v[168:171], v[44:47]
	v_mfma_f32_16x16x32_bf16 v[44:47], v[132:135], v[172:175], v[44:47]
	v_mfma_f32_16x16x32_bf16 v[40:43], v[136:139], v[168:171], v[40:43]
	v_mfma_f32_16x16x32_bf16 v[40:43], v[140:143], v[172:175], v[40:43]
	v_mfma_f32_16x16x32_bf16 v[28:31], v[120:123], v[176:179], v[28:31]
	v_mfma_f32_16x16x32_bf16 v[28:31], v[132:135], v[180:183], v[28:31]
	v_mfma_f32_16x16x32_bf16 v[24:27], v[136:139], v[176:179], v[24:27]
	v_mfma_f32_16x16x32_bf16 v[24:27], v[140:143], v[180:183], v[24:27]
	v_mfma_f32_16x16x32_bf16 v[12:15], v[120:123], v[200:203], v[12:15]
	v_mfma_f32_16x16x32_bf16 v[12:15], v[132:135], v[204:207], v[12:15]
	v_mfma_f32_16x16x32_bf16 v[8:11], v[136:139], v[200:203], v[8:11]
	v_mfma_f32_16x16x32_bf16 v[8:11], v[140:143], v[204:207], v[8:11]
	v_mfma_f32_16x16x32_bf16 v[52:55], v[144:147], v[160:163], v[52:55]
	v_mfma_f32_16x16x32_bf16 v[52:55], v[148:151], v[164:167], v[52:55]
	v_mfma_f32_16x16x32_bf16 v[48:51], v[152:155], v[160:163], v[48:51]
	v_mfma_f32_16x16x32_bf16 v[48:51], v[156:159], v[164:167], v[48:51]
	v_mfma_f32_16x16x32_bf16 v[36:39], v[144:147], v[168:171], v[36:39]
	v_mfma_f32_16x16x32_bf16 v[36:39], v[148:151], v[172:175], v[36:39]
	v_mfma_f32_16x16x32_bf16 v[32:35], v[152:155], v[168:171], v[32:35]
	v_mfma_f32_16x16x32_bf16 v[32:35], v[156:159], v[172:175], v[32:35]
	v_mfma_f32_16x16x32_bf16 v[20:23], v[144:147], v[176:179], v[20:23]
	v_mfma_f32_16x16x32_bf16 v[20:23], v[148:151], v[180:183], v[20:23]
	v_mfma_f32_16x16x32_bf16 v[16:19], v[152:155], v[176:179], v[16:19]
	v_mfma_f32_16x16x32_bf16 v[16:19], v[156:159], v[180:183], v[16:19]
	s_setprio 2
	s_barrier
	v_mfma_f32_16x16x32_bf16 v[4:7], v[144:147], v[200:203], v[4:7]
	v_mfma_f32_16x16x32_bf16 v[4:7], v[148:151], v[204:207], v[4:7]
	v_mfma_f32_16x16x32_bf16 v[0:3], v[152:155], v[200:203], v[0:3]
	v_mfma_f32_16x16x32_bf16 v[0:3], v[156:159], v[204:207], v[0:3]
	s_setprio 0
	s_add_i32 s66, s66, 2
	s_add_u32 s38, s38, 0x100
	s_addc_u32 s39, s39, 0
	s_add_u32 s64, s64, 0x100
	s_addc_u32 s65, s65, 0
	s_cmp_gt_u32 s66, 13
.LBB0_1146:
	ds_read_b128 v[120:123], v233
	ds_read_b128 v[132:135], v233 offset:1024
	ds_read_b128 v[136:139], v233 offset:2048
	ds_read_b128 v[140:143], v233 offset:3072
	ds_read_b128 v[144:147], v234
	ds_read_b128 v[148:151], v234 offset:1024
	ds_read_b128 v[152:155], v234 offset:2048
	ds_read_b128 v[156:159], v234 offset:3072
	s_add_u32 s40, s38, 0xfffc0080
	s_addc_u32 s41, s39, -1
	s_cmp_eq_u32 s66, 12
	s_cselect_b32 s43, s23, s41
	s_cselect_b32 s42, s31, s40
	s_cselect_b32 s41, s25, s65
	s_cselect_b32 s40, s37, s64
	v_lshl_add_u64 v[208:209], s[38:39], 0, v[192:193]
	s_add_i32 m0, s50, 0xc000
	ds_read_b128 v[160:163], v235
	ds_read_b128 v[164:167], v235 offset:1024
	ds_read_b128 v[168:171], v235 offset:2048
	ds_read_b128 v[172:175], v235 offset:3072
	ds_read_b128 v[176:179], v235 offset:4096
	ds_read_b128 v[180:183], v235 offset:5120
	ds_read_b128 v[200:203], v235 offset:6144
	ds_read_b128 v[204:207], v235 offset:7168
	global_load_lds_dwordx4 v[208:209], off
	s_add_i32 m0, s50, 0xe000
	v_lshl_add_u64 v[208:209], s[38:39], 0, v[194:195]
	global_load_lds_dwordx4 v[208:209], off
	s_waitcnt vmcnt(8) lgkmcnt(0)
	s_barrier
	s_setprio 1
	v_mfma_f32_16x16x32_bf16 v[128:131], v[120:123], v[160:163], v[128:131]
	v_mfma_f32_16x16x32_bf16 v[128:131], v[132:135], v[164:167], v[128:131]
	v_mfma_f32_16x16x32_bf16 v[124:127], v[136:139], v[160:163], v[124:127]
	v_mfma_f32_16x16x32_bf16 v[124:127], v[140:143], v[164:167], v[124:127]
	v_mfma_f32_16x16x32_bf16 v[108:111], v[120:123], v[168:171], v[108:111]
	v_mfma_f32_16x16x32_bf16 v[108:111], v[132:135], v[172:175], v[108:111]
	v_mfma_f32_16x16x32_bf16 v[104:107], v[136:139], v[168:171], v[104:107]
	v_mfma_f32_16x16x32_bf16 v[104:107], v[140:143], v[172:175], v[104:107]
	v_mfma_f32_16x16x32_bf16 v[92:95], v[120:123], v[176:179], v[92:95]
	v_mfma_f32_16x16x32_bf16 v[92:95], v[132:135], v[180:183], v[92:95]
	v_mfma_f32_16x16x32_bf16 v[88:91], v[136:139], v[176:179], v[88:91]
	v_mfma_f32_16x16x32_bf16 v[88:91], v[140:143], v[180:183], v[88:91]
	v_mfma_f32_16x16x32_bf16 v[76:79], v[120:123], v[200:203], v[76:79]
	v_mfma_f32_16x16x32_bf16 v[76:79], v[132:135], v[204:207], v[76:79]
	v_mfma_f32_16x16x32_bf16 v[72:75], v[136:139], v[200:203], v[72:75]
	v_mfma_f32_16x16x32_bf16 v[72:75], v[140:143], v[204:207], v[72:75]
	v_mfma_f32_16x16x32_bf16 v[116:119], v[144:147], v[160:163], v[116:119]
	v_mfma_f32_16x16x32_bf16 v[116:119], v[148:151], v[164:167], v[116:119]
	v_mfma_f32_16x16x32_bf16 v[112:115], v[152:155], v[160:163], v[112:115]
	v_mfma_f32_16x16x32_bf16 v[112:115], v[156:159], v[164:167], v[112:115]
	v_mfma_f32_16x16x32_bf16 v[100:103], v[144:147], v[168:171], v[100:103]
	v_mfma_f32_16x16x32_bf16 v[100:103], v[148:151], v[172:175], v[100:103]
	v_mfma_f32_16x16x32_bf16 v[96:99], v[152:155], v[168:171], v[96:99]
	v_mfma_f32_16x16x32_bf16 v[96:99], v[156:159], v[172:175], v[96:99]
	v_mfma_f32_16x16x32_bf16 v[84:87], v[144:147], v[176:179], v[84:87]
	v_mfma_f32_16x16x32_bf16 v[84:87], v[148:151], v[180:183], v[84:87]
	v_mfma_f32_16x16x32_bf16 v[80:83], v[152:155], v[176:179], v[80:83]
	v_mfma_f32_16x16x32_bf16 v[80:83], v[156:159], v[180:183], v[80:83]
	s_setprio 2
	s_barrier
	v_mfma_f32_16x16x32_bf16 v[68:71], v[144:147], v[200:203], v[68:71]
	v_mfma_f32_16x16x32_bf16 v[68:71], v[148:151], v[204:207], v[68:71]
	v_mfma_f32_16x16x32_bf16 v[64:67], v[152:155], v[200:203], v[64:67]
	v_mfma_f32_16x16x32_bf16 v[64:67], v[156:159], v[204:207], v[64:67]
	s_setprio 2
	s_add_i32 s67, s62, s49
	v_lshl_add_u64 v[208:209], s[40:41], 0, v[186:187]
	s_mov_b32 m0, s67
	ds_read_b128 v[160:163], v235 offset:16384
	ds_read_b128 v[164:167], v235 offset:17408
	ds_read_b128 v[168:171], v235 offset:18432
	ds_read_b128 v[172:175], v235 offset:19456
	ds_read_b128 v[176:179], v235 offset:20480
	ds_read_b128 v[180:183], v235 offset:21504
	ds_read_b128 v[200:203], v235 offset:22528
	ds_read_b128 v[204:207], v235 offset:23552
	global_load_lds_dwordx4 v[208:209], off
	s_add_i32 m0, s67, 0x2000
	s_add_u32 s68, s40, 0x40000
	v_lshl_add_u64 v[210:211], s[40:41], 0, v[190:191]
	s_addc_u32 s69, s41, 0
	s_add_i32 s67, s63, s49
	global_load_lds_dwordx4 v[210:211], off
	v_lshl_add_u64 v[212:213], s[68:69], 0, v[186:187]
	s_mov_b32 m0, s67
	v_lshl_add_u64 v[214:215], s[42:43], 0, v[188:189]
	global_load_lds_dwordx4 v[212:213], off
	s_add_i32 m0, s67, 0x2000
	v_lshl_add_u64 v[212:213], s[68:69], 0, v[190:191]
	global_load_lds_dwordx4 v[212:213], off
	s_mov_b32 m0, s50
	v_lshl_add_u64 v[212:213], s[42:43], 0, v[184:185]
	global_load_lds_dwordx4 v[212:213], off
	s_mov_b32 m0, s51
	s_nop 0
	global_load_lds_dwordx4 v[214:215], off
	s_waitcnt vmcnt(8) lgkmcnt(0)
	s_barrier
	s_setprio 1
	v_mfma_f32_16x16x32_bf16 v[60:63], v[120:123], v[160:163], v[60:63]
	v_mfma_f32_16x16x32_bf16 v[60:63], v[132:135], v[164:167], v[60:63]
	v_mfma_f32_16x16x32_bf16 v[56:59], v[136:139], v[160:163], v[56:59]
	v_mfma_f32_16x16x32_bf16 v[56:59], v[140:143], v[164:167], v[56:59]
	v_mfma_f32_16x16x32_bf16 v[44:47], v[120:123], v[168:171], v[44:47]
	v_mfma_f32_16x16x32_bf16 v[44:47], v[132:135], v[172:175], v[44:47]
	v_mfma_f32_16x16x32_bf16 v[40:43], v[136:139], v[168:171], v[40:43]
	v_mfma_f32_16x16x32_bf16 v[40:43], v[140:143], v[172:175], v[40:43]
	v_mfma_f32_16x16x32_bf16 v[28:31], v[120:123], v[176:179], v[28:31]
	v_mfma_f32_16x16x32_bf16 v[28:31], v[132:135], v[180:183], v[28:31]
	v_mfma_f32_16x16x32_bf16 v[24:27], v[136:139], v[176:179], v[24:27]
	v_mfma_f32_16x16x32_bf16 v[24:27], v[140:143], v[180:183], v[24:27]
	v_mfma_f32_16x16x32_bf16 v[12:15], v[120:123], v[200:203], v[12:15]
	v_mfma_f32_16x16x32_bf16 v[12:15], v[132:135], v[204:207], v[12:15]
	v_mfma_f32_16x16x32_bf16 v[8:11], v[136:139], v[200:203], v[8:11]
	v_mfma_f32_16x16x32_bf16 v[8:11], v[140:143], v[204:207], v[8:11]
	v_mfma_f32_16x16x32_bf16 v[52:55], v[144:147], v[160:163], v[52:55]
	v_mfma_f32_16x16x32_bf16 v[52:55], v[148:151], v[164:167], v[52:55]
	v_mfma_f32_16x16x32_bf16 v[48:51], v[152:155], v[160:163], v[48:51]
	v_mfma_f32_16x16x32_bf16 v[48:51], v[156:159], v[164:167], v[48:51]
	v_mfma_f32_16x16x32_bf16 v[36:39], v[144:147], v[168:171], v[36:39]
	v_mfma_f32_16x16x32_bf16 v[36:39], v[148:151], v[172:175], v[36:39]
	v_mfma_f32_16x16x32_bf16 v[32:35], v[152:155], v[168:171], v[32:35]
	v_mfma_f32_16x16x32_bf16 v[32:35], v[156:159], v[172:175], v[32:35]
	v_mfma_f32_16x16x32_bf16 v[20:23], v[144:147], v[176:179], v[20:23]
	v_mfma_f32_16x16x32_bf16 v[20:23], v[148:151], v[180:183], v[20:23]
	v_mfma_f32_16x16x32_bf16 v[16:19], v[152:155], v[176:179], v[16:19]
	v_mfma_f32_16x16x32_bf16 v[16:19], v[156:159], v[180:183], v[16:19]
	s_setprio 2
	s_barrier
	v_mfma_f32_16x16x32_bf16 v[4:7], v[144:147], v[200:203], v[4:7]
	v_mfma_f32_16x16x32_bf16 v[4:7], v[148:151], v[204:207], v[4:7]
	v_mfma_f32_16x16x32_bf16 v[0:3], v[152:155], v[200:203], v[0:3]
	v_mfma_f32_16x16x32_bf16 v[0:3], v[156:159], v[204:207], v[0:3]
	s_setprio 0
	s_add_i32 s67, 0, 0x18000
	s_add_i32 s68, 0, 0x1c000
	v_add_u32_e32 v140, s67, v232
	v_add_u32_e32 v156, s68, v232
	ds_read_b128 v[120:123], v140
	ds_read_b128 v[132:135], v140 offset:1024
	ds_read_b128 v[136:139], v140 offset:2048
	ds_read_b128 v[140:143], v140 offset:3072
	ds_read_b128 v[144:147], v156
	ds_read_b128 v[148:151], v156 offset:1024
	ds_read_b128 v[152:155], v156 offset:2048
	ds_read_b128 v[156:159], v156 offset:3072
	s_add_u32 s42, s42, 0x40000
	s_addc_u32 s43, s43, 0
	s_mov_b32 m0, s54
	v_lshl_add_u64 v[216:217], s[42:43], 0, v[184:185]
	ds_read_b128 v[160:163], v235 offset:32768
	ds_read_b128 v[164:167], v235 offset:33792
	ds_read_b128 v[168:171], v235 offset:34816
	ds_read_b128 v[172:175], v235 offset:35840
	ds_read_b128 v[176:179], v235 offset:36864
	ds_read_b128 v[180:183], v235 offset:37888
	ds_read_b128 v[200:203], v235 offset:38912
	ds_read_b128 v[204:207], v235 offset:39936
	global_load_lds_dwordx4 v[216:217], off
	s_mov_b32 m0, s55
	v_lshl_add_u64 v[216:217], s[42:43], 0, v[188:189]
	global_load_lds_dwordx4 v[216:217], off
	s_waitcnt vmcnt(8) lgkmcnt(0)
	s_barrier
	s_setprio 1
	v_mfma_f32_16x16x32_bf16 v[128:131], v[120:123], v[160:163], v[128:131]
	v_mfma_f32_16x16x32_bf16 v[128:131], v[132:135], v[164:167], v[128:131]
	v_mfma_f32_16x16x32_bf16 v[124:127], v[136:139], v[160:163], v[124:127]
	v_mfma_f32_16x16x32_bf16 v[124:127], v[140:143], v[164:167], v[124:127]
	v_mfma_f32_16x16x32_bf16 v[108:111], v[120:123], v[168:171], v[108:111]
	v_mfma_f32_16x16x32_bf16 v[108:111], v[132:135], v[172:175], v[108:111]
	v_mfma_f32_16x16x32_bf16 v[104:107], v[136:139], v[168:171], v[104:107]
	v_mfma_f32_16x16x32_bf16 v[104:107], v[140:143], v[172:175], v[104:107]
	v_mfma_f32_16x16x32_bf16 v[92:95], v[120:123], v[176:179], v[92:95]
	v_mfma_f32_16x16x32_bf16 v[92:95], v[132:135], v[180:183], v[92:95]
	v_mfma_f32_16x16x32_bf16 v[88:91], v[136:139], v[176:179], v[88:91]
	v_mfma_f32_16x16x32_bf16 v[88:91], v[140:143], v[180:183], v[88:91]
	v_mfma_f32_16x16x32_bf16 v[76:79], v[120:123], v[200:203], v[76:79]
	v_mfma_f32_16x16x32_bf16 v[76:79], v[132:135], v[204:207], v[76:79]
	v_mfma_f32_16x16x32_bf16 v[72:75], v[136:139], v[200:203], v[72:75]
	v_mfma_f32_16x16x32_bf16 v[72:75], v[140:143], v[204:207], v[72:75]
	v_mfma_f32_16x16x32_bf16 v[116:119], v[144:147], v[160:163], v[116:119]
	v_mfma_f32_16x16x32_bf16 v[116:119], v[148:151], v[164:167], v[116:119]
	v_mfma_f32_16x16x32_bf16 v[112:115], v[152:155], v[160:163], v[112:115]
	v_mfma_f32_16x16x32_bf16 v[112:115], v[156:159], v[164:167], v[112:115]
	v_mfma_f32_16x16x32_bf16 v[100:103], v[144:147], v[168:171], v[100:103]
	v_mfma_f32_16x16x32_bf16 v[100:103], v[148:151], v[172:175], v[100:103]
	v_mfma_f32_16x16x32_bf16 v[96:99], v[152:155], v[168:171], v[96:99]
	v_mfma_f32_16x16x32_bf16 v[96:99], v[156:159], v[172:175], v[96:99]
	v_mfma_f32_16x16x32_bf16 v[84:87], v[144:147], v[176:179], v[84:87]
	v_mfma_f32_16x16x32_bf16 v[84:87], v[148:151], v[180:183], v[84:87]
	v_mfma_f32_16x16x32_bf16 v[80:83], v[152:155], v[176:179], v[80:83]
	v_mfma_f32_16x16x32_bf16 v[80:83], v[156:159], v[180:183], v[80:83]
	s_setprio 2
	s_barrier
	v_mfma_f32_16x16x32_bf16 v[68:71], v[144:147], v[200:203], v[68:71]
	v_mfma_f32_16x16x32_bf16 v[68:71], v[148:151], v[204:207], v[68:71]
	v_mfma_f32_16x16x32_bf16 v[64:67], v[152:155], v[200:203], v[64:67]
	v_mfma_f32_16x16x32_bf16 v[64:67], v[156:159], v[204:207], v[64:67]
	s_setprio 2
	s_add_i32 s42, s67, s49
	v_lshl_add_u64 v[208:209], v[208:209], 0, s[18:19]
	s_mov_b32 m0, s42
	ds_read_b128 v[160:163], v235 offset:49152
	ds_read_b128 v[164:167], v235 offset:50176
	ds_read_b128 v[168:171], v235 offset:51200
	ds_read_b128 v[172:175], v235 offset:52224
	ds_read_b128 v[176:179], v235 offset:53248
	ds_read_b128 v[180:183], v235 offset:54272
	ds_read_b128 v[200:203], v235 offset:55296
	ds_read_b128 v[204:207], v235 offset:56320
	global_load_lds_dwordx4 v[208:209], off
	s_add_i32 m0, s42, 0x2000
	s_add_u32 s40, s40, 0x40080
	v_lshl_add_u64 v[208:209], v[210:211], 0, s[18:19]
	s_addc_u32 s41, s41, 0
	s_add_i32 s42, s68, s49
	global_load_lds_dwordx4 v[208:209], off
	s_mov_b32 m0, s42
	v_lshl_add_u64 v[208:209], s[40:41], 0, v[186:187]
	global_load_lds_dwordx4 v[208:209], off
	s_add_i32 m0, s42, 0x2000
	v_lshl_add_u64 v[208:209], s[40:41], 0, v[190:191]
	global_load_lds_dwordx4 v[208:209], off
	s_mov_b32 m0, s57
	v_lshl_add_u64 v[208:209], v[212:213], 0, s[18:19]
	global_load_lds_dwordx4 v[208:209], off
	s_mov_b32 m0, s58
	v_lshl_add_u64 v[208:209], v[214:215], 0, s[18:19]
	global_load_lds_dwordx4 v[208:209], off
	s_waitcnt vmcnt(8) lgkmcnt(0)
	s_barrier
	s_setprio 1
	v_mfma_f32_16x16x32_bf16 v[60:63], v[120:123], v[160:163], v[60:63]
	v_mfma_f32_16x16x32_bf16 v[60:63], v[132:135], v[164:167], v[60:63]
	v_mfma_f32_16x16x32_bf16 v[56:59], v[136:139], v[160:163], v[56:59]
	v_mfma_f32_16x16x32_bf16 v[56:59], v[140:143], v[164:167], v[56:59]
	v_mfma_f32_16x16x32_bf16 v[44:47], v[120:123], v[168:171], v[44:47]
	v_mfma_f32_16x16x32_bf16 v[44:47], v[132:135], v[172:175], v[44:47]
	v_mfma_f32_16x16x32_bf16 v[40:43], v[136:139], v[168:171], v[40:43]
	v_mfma_f32_16x16x32_bf16 v[40:43], v[140:143], v[172:175], v[40:43]
	v_mfma_f32_16x16x32_bf16 v[28:31], v[120:123], v[176:179], v[28:31]
	v_mfma_f32_16x16x32_bf16 v[28:31], v[132:135], v[180:183], v[28:31]
	v_mfma_f32_16x16x32_bf16 v[24:27], v[136:139], v[176:179], v[24:27]
	v_mfma_f32_16x16x32_bf16 v[24:27], v[140:143], v[180:183], v[24:27]
	v_mfma_f32_16x16x32_bf16 v[12:15], v[120:123], v[200:203], v[12:15]
	v_mfma_f32_16x16x32_bf16 v[12:15], v[132:135], v[204:207], v[12:15]
	v_mfma_f32_16x16x32_bf16 v[8:11], v[136:139], v[200:203], v[8:11]
	v_mfma_f32_16x16x32_bf16 v[8:11], v[140:143], v[204:207], v[8:11]
	v_mfma_f32_16x16x32_bf16 v[52:55], v[144:147], v[160:163], v[52:55]
	v_mfma_f32_16x16x32_bf16 v[52:55], v[148:151], v[164:167], v[52:55]
	v_mfma_f32_16x16x32_bf16 v[48:51], v[152:155], v[160:163], v[48:51]
	v_mfma_f32_16x16x32_bf16 v[48:51], v[156:159], v[164:167], v[48:51]
	v_mfma_f32_16x16x32_bf16 v[36:39], v[144:147], v[168:171], v[36:39]
	v_mfma_f32_16x16x32_bf16 v[36:39], v[148:151], v[172:175], v[36:39]
	v_mfma_f32_16x16x32_bf16 v[32:35], v[152:155], v[168:171], v[32:35]
	v_mfma_f32_16x16x32_bf16 v[32:35], v[156:159], v[172:175], v[32:35]
	v_mfma_f32_16x16x32_bf16 v[20:23], v[144:147], v[176:179], v[20:23]
	v_mfma_f32_16x16x32_bf16 v[20:23], v[148:151], v[180:183], v[20:23]
	v_mfma_f32_16x16x32_bf16 v[16:19], v[152:155], v[176:179], v[16:19]
	v_mfma_f32_16x16x32_bf16 v[16:19], v[156:159], v[180:183], v[16:19]
	s_setprio 2
	s_barrier
	v_mfma_f32_16x16x32_bf16 v[4:7], v[144:147], v[200:203], v[4:7]
	v_mfma_f32_16x16x32_bf16 v[4:7], v[148:151], v[204:207], v[4:7]
	v_mfma_f32_16x16x32_bf16 v[0:3], v[152:155], v[200:203], v[0:3]
	v_mfma_f32_16x16x32_bf16 v[0:3], v[156:159], v[204:207], v[0:3]
	s_setprio 0
	s_add_i32 s66, s66, 2
	s_add_u32 s38, s38, 0x100
	s_addc_u32 s39, s39, 0
	s_add_u32 s64, s64, 0x100
	s_addc_u32 s65, s65, 0
	s_cmp_gt_u32 s66, 13
	s_cbranch_scc0 .LBB0_1146

.LBB0_1309:
	s_add_u32 s51, s26, 0x100
	s_addc_u32 s52, s27, 0
	s_mov_b32 s53, -2
	ds_read_b128 v[128:131], v197
	ds_read_b128 v[132:135], v197 offset:1024
	ds_read_b128 v[136:139], v197 offset:2048
	ds_read_b128 v[140:143], v197 offset:3072
	ds_read_b128 v[144:147], v198
	ds_read_b128 v[148:151], v198 offset:1024
	ds_read_b128 v[152:155], v198 offset:2048
	ds_read_b128 v[156:159], v198 offset:3072
	s_add_u32 s4, s24, 0x100
	s_addc_u32 s5, s25, 0
	s_cmp_eq_u32 s53, 40
	s_cselect_b32 s29, s21, s5
	s_cselect_b32 s28, s20, s4
	s_cselect_b32 s27, s23, s52
	s_cselect_b32 s26, s22, s51
	v_lshl_add_u64 v[212:213], s[24:25], 0, v[172:173]
	s_add_i32 m0, s36, 0xc000
	ds_read_b128 v[160:163], v199
	ds_read_b128 v[180:183], v199 offset:1024
	ds_read_b128 v[184:187], v199 offset:2048
	ds_read_b128 v[188:191], v199 offset:3072
	ds_read_b128 v[192:195], v199 offset:4096
	ds_read_b128 v[200:203], v199 offset:5120
	ds_read_b128 v[204:207], v199 offset:6144
	ds_read_b128 v[208:211], v199 offset:7168
	global_load_lds_dwordx4 v[212:213], off
	s_add_i32 m0, s36, 0xe000
	v_lshl_add_u64 v[212:213], s[24:25], 0, v[174:175]
	global_load_lds_dwordx4 v[212:213], off
	s_waitcnt vmcnt(8) lgkmcnt(0)
	s_barrier
	s_setprio 1
	v_mfma_f32_16x16x32_bf16 v[124:127], v[128:131], v[160:163], 0
	v_mfma_f32_16x16x32_bf16 v[124:127], v[132:135], v[180:183], v[124:127]
	v_mfma_f32_16x16x32_bf16 v[120:123], v[136:139], v[160:163], 0
	v_mfma_f32_16x16x32_bf16 v[120:123], v[140:143], v[180:183], v[120:123]
	v_mfma_f32_16x16x32_bf16 v[116:119], v[128:131], v[184:187], 0
	v_mfma_f32_16x16x32_bf16 v[116:119], v[132:135], v[188:191], v[116:119]
	v_mfma_f32_16x16x32_bf16 v[108:111], v[136:139], v[184:187], 0
	v_mfma_f32_16x16x32_bf16 v[108:111], v[140:143], v[188:191], v[108:111]
	v_mfma_f32_16x16x32_bf16 v[88:91], v[128:131], v[192:195], 0
	v_mfma_f32_16x16x32_bf16 v[88:91], v[132:135], v[200:203], v[88:91]
	v_mfma_f32_16x16x32_bf16 v[100:103], v[136:139], v[192:195], 0
	v_mfma_f32_16x16x32_bf16 v[100:103], v[140:143], v[200:203], v[100:103]
	v_mfma_f32_16x16x32_bf16 v[72:75], v[128:131], v[204:207], 0
	v_mfma_f32_16x16x32_bf16 v[72:75], v[132:135], v[208:211], v[72:75]
	v_mfma_f32_16x16x32_bf16 v[76:79], v[136:139], v[204:207], 0
	v_mfma_f32_16x16x32_bf16 v[76:79], v[140:143], v[208:211], v[76:79]
	v_mfma_f32_16x16x32_bf16 v[112:115], v[144:147], v[160:163], 0
	v_mfma_f32_16x16x32_bf16 v[112:115], v[148:151], v[180:183], v[112:115]
	v_mfma_f32_16x16x32_bf16 v[104:107], v[152:155], v[160:163], 0
	v_mfma_f32_16x16x32_bf16 v[104:107], v[156:159], v[180:183], v[104:107]
	v_mfma_f32_16x16x32_bf16 v[96:99], v[144:147], v[184:187], 0
	v_mfma_f32_16x16x32_bf16 v[96:99], v[148:151], v[188:191], v[96:99]
	v_mfma_f32_16x16x32_bf16 v[92:95], v[152:155], v[184:187], 0
	v_mfma_f32_16x16x32_bf16 v[92:95], v[156:159], v[188:191], v[92:95]
	v_mfma_f32_16x16x32_bf16 v[80:83], v[144:147], v[192:195], 0
	v_mfma_f32_16x16x32_bf16 v[80:83], v[148:151], v[200:203], v[80:83]
	v_mfma_f32_16x16x32_bf16 v[84:87], v[152:155], v[192:195], 0
	v_mfma_f32_16x16x32_bf16 v[84:87], v[156:159], v[200:203], v[84:87]
	s_setprio 2
	s_barrier
	v_mfma_f32_16x16x32_bf16 v[64:67], v[144:147], v[204:207], 0
	v_mfma_f32_16x16x32_bf16 v[64:67], v[148:151], v[208:211], v[64:67]
	v_mfma_f32_16x16x32_bf16 v[68:71], v[152:155], v[204:207], 0
	v_mfma_f32_16x16x32_bf16 v[68:71], v[156:159], v[208:211], v[68:71]
	s_setprio 2
	s_add_i32 s24, s45, s35
	v_lshl_add_u64 v[212:213], s[26:27], 0, v[166:167]
	s_mov_b32 m0, s24
	ds_read_b128 v[160:163], v199 offset:16384
	ds_read_b128 v[180:183], v199 offset:17408
	ds_read_b128 v[184:187], v199 offset:18432
	ds_read_b128 v[188:191], v199 offset:19456
	ds_read_b128 v[192:195], v199 offset:20480
	ds_read_b128 v[200:203], v199 offset:21504
	ds_read_b128 v[204:207], v199 offset:22528
	ds_read_b128 v[208:211], v199 offset:23552
	global_load_lds_dwordx4 v[212:213], off
	s_add_i32 m0, s24, 0x2000
	s_add_u32 s24, s26, 0xb0000
	v_lshl_add_u64 v[214:215], s[26:27], 0, v[170:171]
	s_addc_u32 s25, s27, 0
	s_add_i32 s54, s46, s35
	global_load_lds_dwordx4 v[214:215], off
	v_lshl_add_u64 v[216:217], s[24:25], 0, v[166:167]
	s_mov_b32 m0, s54
	v_lshl_add_u64 v[218:219], s[28:29], 0, v[168:169]
	global_load_lds_dwordx4 v[216:217], off
	s_add_i32 m0, s54, 0x2000
	v_lshl_add_u64 v[216:217], s[24:25], 0, v[170:171]
	global_load_lds_dwordx4 v[216:217], off
	s_mov_b32 m0, s36
	v_lshl_add_u64 v[216:217], s[28:29], 0, v[164:165]
	global_load_lds_dwordx4 v[216:217], off
	s_mov_b32 m0, s37
	s_nop 0
	global_load_lds_dwordx4 v[218:219], off
	s_waitcnt vmcnt(8) lgkmcnt(0)
	s_barrier
	s_setprio 1
	v_mfma_f32_16x16x32_bf16 v[56:59], v[128:131], v[160:163], 0
	v_mfma_f32_16x16x32_bf16 v[56:59], v[132:135], v[180:183], v[56:59]
	v_mfma_f32_16x16x32_bf16 v[60:63], v[136:139], v[160:163], 0
	v_mfma_f32_16x16x32_bf16 v[60:63], v[140:143], v[180:183], v[60:63]
	v_mfma_f32_16x16x32_bf16 v[40:43], v[128:131], v[184:187], 0
	v_mfma_f32_16x16x32_bf16 v[40:43], v[132:135], v[188:191], v[40:43]
	v_mfma_f32_16x16x32_bf16 v[44:47], v[136:139], v[184:187], 0
	v_mfma_f32_16x16x32_bf16 v[44:47], v[140:143], v[188:191], v[44:47]
	v_mfma_f32_16x16x32_bf16 v[24:27], v[128:131], v[192:195], 0
	v_mfma_f32_16x16x32_bf16 v[24:27], v[132:135], v[200:203], v[24:27]
	v_mfma_f32_16x16x32_bf16 v[28:31], v[136:139], v[192:195], 0
	v_mfma_f32_16x16x32_bf16 v[28:31], v[140:143], v[200:203], v[28:31]
	v_mfma_f32_16x16x32_bf16 v[8:11], v[128:131], v[204:207], 0
	v_mfma_f32_16x16x32_bf16 v[8:11], v[132:135], v[208:211], v[8:11]
	v_mfma_f32_16x16x32_bf16 v[12:15], v[136:139], v[204:207], 0
	v_mfma_f32_16x16x32_bf16 v[12:15], v[140:143], v[208:211], v[12:15]
	v_mfma_f32_16x16x32_bf16 v[48:51], v[144:147], v[160:163], 0
	v_mfma_f32_16x16x32_bf16 v[48:51], v[148:151], v[180:183], v[48:51]
	v_mfma_f32_16x16x32_bf16 v[52:55], v[152:155], v[160:163], 0
	v_mfma_f32_16x16x32_bf16 v[52:55], v[156:159], v[180:183], v[52:55]
	v_mfma_f32_16x16x32_bf16 v[32:35], v[144:147], v[184:187], 0
	v_mfma_f32_16x16x32_bf16 v[32:35], v[148:151], v[188:191], v[32:35]
	v_mfma_f32_16x16x32_bf16 v[36:39], v[152:155], v[184:187], 0
	v_mfma_f32_16x16x32_bf16 v[36:39], v[156:159], v[188:191], v[36:39]
	v_mfma_f32_16x16x32_bf16 v[16:19], v[144:147], v[192:195], 0
	v_mfma_f32_16x16x32_bf16 v[16:19], v[148:151], v[200:203], v[16:19]
	v_mfma_f32_16x16x32_bf16 v[20:23], v[152:155], v[192:195], 0
	v_mfma_f32_16x16x32_bf16 v[20:23], v[156:159], v[200:203], v[20:23]
	s_setprio 2
	s_barrier
	v_mfma_f32_16x16x32_bf16 v[0:3], v[144:147], v[204:207], 0
	v_mfma_f32_16x16x32_bf16 v[0:3], v[148:151], v[208:211], v[0:3]
	v_mfma_f32_16x16x32_bf16 v[4:7], v[152:155], v[204:207], 0
	v_mfma_f32_16x16x32_bf16 v[4:7], v[156:159], v[208:211], v[4:7]
	s_setprio 0
	s_add_i32 s54, 0, 0x18000
	s_add_i32 s55, 0, 0x1c000
	v_add_u32_e32 v140, s54, v196
	v_add_u32_e32 v156, s55, v196
	ds_read_b128 v[128:131], v140
	ds_read_b128 v[132:135], v140 offset:1024
	ds_read_b128 v[136:139], v140 offset:2048
	ds_read_b128 v[140:143], v140 offset:3072
	ds_read_b128 v[144:147], v156
	ds_read_b128 v[148:151], v156 offset:1024
	ds_read_b128 v[152:155], v156 offset:2048
	ds_read_b128 v[156:159], v156 offset:3072
	s_add_u32 s24, s28, 0xb0000
	s_addc_u32 s25, s29, 0
	s_mov_b32 m0, s38
	v_lshl_add_u64 v[220:221], s[24:25], 0, v[164:165]
	ds_read_b128 v[160:163], v199 offset:32768
	ds_read_b128 v[180:183], v199 offset:33792
	ds_read_b128 v[184:187], v199 offset:34816
	ds_read_b128 v[188:191], v199 offset:35840
	ds_read_b128 v[192:195], v199 offset:36864
	ds_read_b128 v[200:203], v199 offset:37888
	ds_read_b128 v[204:207], v199 offset:38912
	ds_read_b128 v[208:211], v199 offset:39936
	global_load_lds_dwordx4 v[220:221], off
	s_mov_b32 m0, s39
	v_lshl_add_u64 v[220:221], s[24:25], 0, v[168:169]
	global_load_lds_dwordx4 v[220:221], off
	s_waitcnt vmcnt(8) lgkmcnt(0)
	s_barrier
	s_setprio 1
	v_mfma_f32_16x16x32_bf16 v[124:127], v[128:131], v[160:163], v[124:127]
	v_mfma_f32_16x16x32_bf16 v[124:127], v[132:135], v[180:183], v[124:127]
	v_mfma_f32_16x16x32_bf16 v[120:123], v[136:139], v[160:163], v[120:123]
	v_mfma_f32_16x16x32_bf16 v[120:123], v[140:143], v[180:183], v[120:123]
	v_mfma_f32_16x16x32_bf16 v[116:119], v[128:131], v[184:187], v[116:119]
	v_mfma_f32_16x16x32_bf16 v[116:119], v[132:135], v[188:191], v[116:119]
	v_mfma_f32_16x16x32_bf16 v[108:111], v[136:139], v[184:187], v[108:111]
	v_mfma_f32_16x16x32_bf16 v[108:111], v[140:143], v[188:191], v[108:111]
	v_mfma_f32_16x16x32_bf16 v[88:91], v[128:131], v[192:195], v[88:91]
	v_mfma_f32_16x16x32_bf16 v[88:91], v[132:135], v[200:203], v[88:91]
	v_mfma_f32_16x16x32_bf16 v[100:103], v[136:139], v[192:195], v[100:103]
	v_mfma_f32_16x16x32_bf16 v[100:103], v[140:143], v[200:203], v[100:103]
	v_mfma_f32_16x16x32_bf16 v[72:75], v[128:131], v[204:207], v[72:75]
	v_mfma_f32_16x16x32_bf16 v[72:75], v[132:135], v[208:211], v[72:75]
	v_mfma_f32_16x16x32_bf16 v[76:79], v[136:139], v[204:207], v[76:79]
	v_mfma_f32_16x16x32_bf16 v[76:79], v[140:143], v[208:211], v[76:79]
	v_mfma_f32_16x16x32_bf16 v[112:115], v[144:147], v[160:163], v[112:115]
	v_mfma_f32_16x16x32_bf16 v[112:115], v[148:151], v[180:183], v[112:115]
	v_mfma_f32_16x16x32_bf16 v[104:107], v[152:155], v[160:163], v[104:107]
	v_mfma_f32_16x16x32_bf16 v[104:107], v[156:159], v[180:183], v[104:107]
	v_mfma_f32_16x16x32_bf16 v[96:99], v[144:147], v[184:187], v[96:99]
	v_mfma_f32_16x16x32_bf16 v[96:99], v[148:151], v[188:191], v[96:99]
	v_mfma_f32_16x16x32_bf16 v[92:95], v[152:155], v[184:187], v[92:95]
	v_mfma_f32_16x16x32_bf16 v[92:95], v[156:159], v[188:191], v[92:95]
	v_mfma_f32_16x16x32_bf16 v[80:83], v[144:147], v[192:195], v[80:83]
	v_mfma_f32_16x16x32_bf16 v[80:83], v[148:151], v[200:203], v[80:83]
	v_mfma_f32_16x16x32_bf16 v[84:87], v[152:155], v[192:195], v[84:87]
	v_mfma_f32_16x16x32_bf16 v[84:87], v[156:159], v[200:203], v[84:87]
	s_setprio 2
	s_barrier
	v_mfma_f32_16x16x32_bf16 v[64:67], v[144:147], v[204:207], v[64:67]
	v_mfma_f32_16x16x32_bf16 v[64:67], v[148:151], v[208:211], v[64:67]
	v_mfma_f32_16x16x32_bf16 v[68:71], v[152:155], v[204:207], v[68:71]
	v_mfma_f32_16x16x32_bf16 v[68:71], v[156:159], v[208:211], v[68:71]
	s_setprio 2
	s_add_i32 s24, s54, s35
	v_lshl_add_u64 v[212:213], v[212:213], 0, s[16:17]
	s_mov_b32 m0, s24
	ds_read_b128 v[160:163], v199 offset:49152
	ds_read_b128 v[180:183], v199 offset:50176
	ds_read_b128 v[184:187], v199 offset:51200
	ds_read_b128 v[188:191], v199 offset:52224
	ds_read_b128 v[192:195], v199 offset:53248
	ds_read_b128 v[200:203], v199 offset:54272
	ds_read_b128 v[204:207], v199 offset:55296
	ds_read_b128 v[208:211], v199 offset:56320
	global_load_lds_dwordx4 v[212:213], off
	s_add_i32 m0, s24, 0x2000
	s_add_u32 s24, s26, 0xb0080
	v_lshl_add_u64 v[212:213], v[214:215], 0, s[16:17]
	s_addc_u32 s25, s27, 0
	s_add_i32 s26, s55, s35
	global_load_lds_dwordx4 v[212:213], off
	s_mov_b32 m0, s26
	v_lshl_add_u64 v[212:213], s[24:25], 0, v[166:167]
	global_load_lds_dwordx4 v[212:213], off
	s_add_i32 m0, s26, 0x2000
	v_lshl_add_u64 v[212:213], s[24:25], 0, v[170:171]
	global_load_lds_dwordx4 v[212:213], off
	s_mov_b32 m0, s41
	v_lshl_add_u64 v[212:213], v[216:217], 0, s[16:17]
	global_load_lds_dwordx4 v[212:213], off
	s_mov_b32 m0, s42
	v_lshl_add_u64 v[212:213], v[218:219], 0, s[16:17]
	global_load_lds_dwordx4 v[212:213], off
	s_waitcnt vmcnt(8) lgkmcnt(0)
	s_barrier
	s_setprio 1
	v_mfma_f32_16x16x32_bf16 v[56:59], v[128:131], v[160:163], v[56:59]
	v_mfma_f32_16x16x32_bf16 v[56:59], v[132:135], v[180:183], v[56:59]
	v_mfma_f32_16x16x32_bf16 v[60:63], v[136:139], v[160:163], v[60:63]
	v_mfma_f32_16x16x32_bf16 v[60:63], v[140:143], v[180:183], v[60:63]
	v_mfma_f32_16x16x32_bf16 v[40:43], v[128:131], v[184:187], v[40:43]
	v_mfma_f32_16x16x32_bf16 v[40:43], v[132:135], v[188:191], v[40:43]
	v_mfma_f32_16x16x32_bf16 v[44:47], v[136:139], v[184:187], v[44:47]
	v_mfma_f32_16x16x32_bf16 v[44:47], v[140:143], v[188:191], v[44:47]
	v_mfma_f32_16x16x32_bf16 v[24:27], v[128:131], v[192:195], v[24:27]
	v_mfma_f32_16x16x32_bf16 v[24:27], v[132:135], v[200:203], v[24:27]
	v_mfma_f32_16x16x32_bf16 v[28:31], v[136:139], v[192:195], v[28:31]
	v_mfma_f32_16x16x32_bf16 v[28:31], v[140:143], v[200:203], v[28:31]
	v_mfma_f32_16x16x32_bf16 v[8:11], v[128:131], v[204:207], v[8:11]
	v_mfma_f32_16x16x32_bf16 v[8:11], v[132:135], v[208:211], v[8:11]
	v_mfma_f32_16x16x32_bf16 v[12:15], v[136:139], v[204:207], v[12:15]
	v_mfma_f32_16x16x32_bf16 v[12:15], v[140:143], v[208:211], v[12:15]
	v_mfma_f32_16x16x32_bf16 v[48:51], v[144:147], v[160:163], v[48:51]
	v_mfma_f32_16x16x32_bf16 v[48:51], v[148:151], v[180:183], v[48:51]
	v_mfma_f32_16x16x32_bf16 v[52:55], v[152:155], v[160:163], v[52:55]
	v_mfma_f32_16x16x32_bf16 v[52:55], v[156:159], v[180:183], v[52:55]
	v_mfma_f32_16x16x32_bf16 v[32:35], v[144:147], v[184:187], v[32:35]
	v_mfma_f32_16x16x32_bf16 v[32:35], v[148:151], v[188:191], v[32:35]
	v_mfma_f32_16x16x32_bf16 v[36:39], v[152:155], v[184:187], v[36:39]
	v_mfma_f32_16x16x32_bf16 v[36:39], v[156:159], v[188:191], v[36:39]
	v_mfma_f32_16x16x32_bf16 v[16:19], v[144:147], v[192:195], v[16:19]
	v_mfma_f32_16x16x32_bf16 v[16:19], v[148:151], v[200:203], v[16:19]
	v_mfma_f32_16x16x32_bf16 v[20:23], v[152:155], v[192:195], v[20:23]
	v_mfma_f32_16x16x32_bf16 v[20:23], v[156:159], v[200:203], v[20:23]
	s_setprio 2
	s_barrier
	v_mfma_f32_16x16x32_bf16 v[0:3], v[144:147], v[204:207], v[0:3]
	v_mfma_f32_16x16x32_bf16 v[0:3], v[148:151], v[208:211], v[0:3]
	v_mfma_f32_16x16x32_bf16 v[4:7], v[152:155], v[204:207], v[4:7]
	v_mfma_f32_16x16x32_bf16 v[4:7], v[156:159], v[208:211], v[4:7]
	s_setprio 0
	s_add_i32 s53, s53, 2
	s_add_u32 s51, s51, 0x100
	s_addc_u32 s52, s52, 0
	s_cmp_gt_u32 s53, 41
	s_mov_b64 s[24:25], s[4:5]
.LBB0_1310:
	ds_read_b128 v[128:131], v197
	ds_read_b128 v[132:135], v197 offset:1024
	ds_read_b128 v[136:139], v197 offset:2048
	ds_read_b128 v[140:143], v197 offset:3072
	ds_read_b128 v[144:147], v198
	ds_read_b128 v[148:151], v198 offset:1024
	ds_read_b128 v[152:155], v198 offset:2048
	ds_read_b128 v[156:159], v198 offset:3072
	s_add_u32 s4, s24, 0x100
	s_addc_u32 s5, s25, 0
	s_cmp_eq_u32 s53, 40
	s_cselect_b32 s29, s21, s5
	s_cselect_b32 s28, s20, s4
	s_cselect_b32 s27, s23, s52
	s_cselect_b32 s26, s22, s51
	v_lshl_add_u64 v[212:213], s[24:25], 0, v[172:173]
	s_add_i32 m0, s36, 0xc000
	ds_read_b128 v[160:163], v199
	ds_read_b128 v[180:183], v199 offset:1024
	ds_read_b128 v[184:187], v199 offset:2048
	ds_read_b128 v[188:191], v199 offset:3072
	ds_read_b128 v[192:195], v199 offset:4096
	ds_read_b128 v[200:203], v199 offset:5120
	ds_read_b128 v[204:207], v199 offset:6144
	ds_read_b128 v[208:211], v199 offset:7168
	global_load_lds_dwordx4 v[212:213], off
	s_add_i32 m0, s36, 0xe000
	v_lshl_add_u64 v[212:213], s[24:25], 0, v[174:175]
	global_load_lds_dwordx4 v[212:213], off
	s_waitcnt vmcnt(8) lgkmcnt(0)
	s_barrier
	s_setprio 1
	v_mfma_f32_16x16x32_bf16 v[124:127], v[128:131], v[160:163], v[124:127]
	v_mfma_f32_16x16x32_bf16 v[124:127], v[132:135], v[180:183], v[124:127]
	v_mfma_f32_16x16x32_bf16 v[120:123], v[136:139], v[160:163], v[120:123]
	v_mfma_f32_16x16x32_bf16 v[120:123], v[140:143], v[180:183], v[120:123]
	v_mfma_f32_16x16x32_bf16 v[116:119], v[128:131], v[184:187], v[116:119]
	v_mfma_f32_16x16x32_bf16 v[116:119], v[132:135], v[188:191], v[116:119]
	v_mfma_f32_16x16x32_bf16 v[108:111], v[136:139], v[184:187], v[108:111]
	v_mfma_f32_16x16x32_bf16 v[108:111], v[140:143], v[188:191], v[108:111]
	v_mfma_f32_16x16x32_bf16 v[88:91], v[128:131], v[192:195], v[88:91]
	v_mfma_f32_16x16x32_bf16 v[88:91], v[132:135], v[200:203], v[88:91]
	v_mfma_f32_16x16x32_bf16 v[100:103], v[136:139], v[192:195], v[100:103]
	v_mfma_f32_16x16x32_bf16 v[100:103], v[140:143], v[200:203], v[100:103]
	v_mfma_f32_16x16x32_bf16 v[72:75], v[128:131], v[204:207], v[72:75]
	v_mfma_f32_16x16x32_bf16 v[72:75], v[132:135], v[208:211], v[72:75]
	v_mfma_f32_16x16x32_bf16 v[76:79], v[136:139], v[204:207], v[76:79]
	v_mfma_f32_16x16x32_bf16 v[76:79], v[140:143], v[208:211], v[76:79]
	v_mfma_f32_16x16x32_bf16 v[112:115], v[144:147], v[160:163], v[112:115]
	v_mfma_f32_16x16x32_bf16 v[112:115], v[148:151], v[180:183], v[112:115]
	v_mfma_f32_16x16x32_bf16 v[104:107], v[152:155], v[160:163], v[104:107]
	v_mfma_f32_16x16x32_bf16 v[104:107], v[156:159], v[180:183], v[104:107]
	v_mfma_f32_16x16x32_bf16 v[96:99], v[144:147], v[184:187], v[96:99]
	v_mfma_f32_16x16x32_bf16 v[96:99], v[148:151], v[188:191], v[96:99]
	v_mfma_f32_16x16x32_bf16 v[92:95], v[152:155], v[184:187], v[92:95]
	v_mfma_f32_16x16x32_bf16 v[92:95], v[156:159], v[188:191], v[92:95]
	v_mfma_f32_16x16x32_bf16 v[80:83], v[144:147], v[192:195], v[80:83]
	v_mfma_f32_16x16x32_bf16 v[80:83], v[148:151], v[200:203], v[80:83]
	v_mfma_f32_16x16x32_bf16 v[84:87], v[152:155], v[192:195], v[84:87]
	v_mfma_f32_16x16x32_bf16 v[84:87], v[156:159], v[200:203], v[84:87]
	s_setprio 2
	s_barrier
	v_mfma_f32_16x16x32_bf16 v[64:67], v[144:147], v[204:207], v[64:67]
	v_mfma_f32_16x16x32_bf16 v[64:67], v[148:151], v[208:211], v[64:67]
	v_mfma_f32_16x16x32_bf16 v[68:71], v[152:155], v[204:207], v[68:71]
	v_mfma_f32_16x16x32_bf16 v[68:71], v[156:159], v[208:211], v[68:71]
	s_setprio 2
	s_add_i32 s24, s45, s35
	v_lshl_add_u64 v[212:213], s[26:27], 0, v[166:167]
	s_mov_b32 m0, s24
	ds_read_b128 v[160:163], v199 offset:16384
	ds_read_b128 v[180:183], v199 offset:17408
	ds_read_b128 v[184:187], v199 offset:18432
	ds_read_b128 v[188:191], v199 offset:19456
	ds_read_b128 v[192:195], v199 offset:20480
	ds_read_b128 v[200:203], v199 offset:21504
	ds_read_b128 v[204:207], v199 offset:22528
	ds_read_b128 v[208:211], v199 offset:23552
	global_load_lds_dwordx4 v[212:213], off
	s_add_i32 m0, s24, 0x2000
	s_add_u32 s24, s26, 0xb0000
	v_lshl_add_u64 v[214:215], s[26:27], 0, v[170:171]
	s_addc_u32 s25, s27, 0
	s_add_i32 s54, s46, s35
	global_load_lds_dwordx4 v[214:215], off
	v_lshl_add_u64 v[216:217], s[24:25], 0, v[166:167]
	s_mov_b32 m0, s54
	v_lshl_add_u64 v[218:219], s[28:29], 0, v[168:169]
	global_load_lds_dwordx4 v[216:217], off
	s_add_i32 m0, s54, 0x2000
	v_lshl_add_u64 v[216:217], s[24:25], 0, v[170:171]
	global_load_lds_dwordx4 v[216:217], off
	s_mov_b32 m0, s36
	v_lshl_add_u64 v[216:217], s[28:29], 0, v[164:165]
	global_load_lds_dwordx4 v[216:217], off
	s_mov_b32 m0, s37
	s_nop 0
	global_load_lds_dwordx4 v[218:219], off
	s_waitcnt vmcnt(8) lgkmcnt(0)
	s_barrier
	s_setprio 1
	v_mfma_f32_16x16x32_bf16 v[56:59], v[128:131], v[160:163], v[56:59]
	v_mfma_f32_16x16x32_bf16 v[56:59], v[132:135], v[180:183], v[56:59]
	v_mfma_f32_16x16x32_bf16 v[60:63], v[136:139], v[160:163], v[60:63]
	v_mfma_f32_16x16x32_bf16 v[60:63], v[140:143], v[180:183], v[60:63]
	v_mfma_f32_16x16x32_bf16 v[40:43], v[128:131], v[184:187], v[40:43]
	v_mfma_f32_16x16x32_bf16 v[40:43], v[132:135], v[188:191], v[40:43]
	v_mfma_f32_16x16x32_bf16 v[44:47], v[136:139], v[184:187], v[44:47]
	v_mfma_f32_16x16x32_bf16 v[44:47], v[140:143], v[188:191], v[44:47]
	v_mfma_f32_16x16x32_bf16 v[24:27], v[128:131], v[192:195], v[24:27]
	v_mfma_f32_16x16x32_bf16 v[24:27], v[132:135], v[200:203], v[24:27]
	v_mfma_f32_16x16x32_bf16 v[28:31], v[136:139], v[192:195], v[28:31]
	v_mfma_f32_16x16x32_bf16 v[28:31], v[140:143], v[200:203], v[28:31]
	v_mfma_f32_16x16x32_bf16 v[8:11], v[128:131], v[204:207], v[8:11]
	v_mfma_f32_16x16x32_bf16 v[8:11], v[132:135], v[208:211], v[8:11]
	v_mfma_f32_16x16x32_bf16 v[12:15], v[136:139], v[204:207], v[12:15]
	v_mfma_f32_16x16x32_bf16 v[12:15], v[140:143], v[208:211], v[12:15]
	v_mfma_f32_16x16x32_bf16 v[48:51], v[144:147], v[160:163], v[48:51]
	v_mfma_f32_16x16x32_bf16 v[48:51], v[148:151], v[180:183], v[48:51]
	v_mfma_f32_16x16x32_bf16 v[52:55], v[152:155], v[160:163], v[52:55]
	v_mfma_f32_16x16x32_bf16 v[52:55], v[156:159], v[180:183], v[52:55]
	v_mfma_f32_16x16x32_bf16 v[32:35], v[144:147], v[184:187], v[32:35]
	v_mfma_f32_16x16x32_bf16 v[32:35], v[148:151], v[188:191], v[32:35]
	v_mfma_f32_16x16x32_bf16 v[36:39], v[152:155], v[184:187], v[36:39]
	v_mfma_f32_16x16x32_bf16 v[36:39], v[156:159], v[188:191], v[36:39]
	v_mfma_f32_16x16x32_bf16 v[16:19], v[144:147], v[192:195], v[16:19]
	v_mfma_f32_16x16x32_bf16 v[16:19], v[148:151], v[200:203], v[16:19]
	v_mfma_f32_16x16x32_bf16 v[20:23], v[152:155], v[192:195], v[20:23]
	v_mfma_f32_16x16x32_bf16 v[20:23], v[156:159], v[200:203], v[20:23]
	s_setprio 2
	s_barrier
	v_mfma_f32_16x16x32_bf16 v[0:3], v[144:147], v[204:207], v[0:3]
	v_mfma_f32_16x16x32_bf16 v[0:3], v[148:151], v[208:211], v[0:3]
	v_mfma_f32_16x16x32_bf16 v[4:7], v[152:155], v[204:207], v[4:7]
	v_mfma_f32_16x16x32_bf16 v[4:7], v[156:159], v[208:211], v[4:7]
	s_setprio 0
	s_add_i32 s54, 0, 0x18000
	s_add_i32 s55, 0, 0x1c000
	v_add_u32_e32 v140, s54, v196
	v_add_u32_e32 v156, s55, v196
	ds_read_b128 v[128:131], v140
	ds_read_b128 v[132:135], v140 offset:1024
	ds_read_b128 v[136:139], v140 offset:2048
	ds_read_b128 v[140:143], v140 offset:3072
	ds_read_b128 v[144:147], v156
	ds_read_b128 v[148:151], v156 offset:1024
	ds_read_b128 v[152:155], v156 offset:2048
	ds_read_b128 v[156:159], v156 offset:3072
	s_add_u32 s24, s28, 0xb0000
	s_addc_u32 s25, s29, 0
	s_mov_b32 m0, s38
	v_lshl_add_u64 v[220:221], s[24:25], 0, v[164:165]
	ds_read_b128 v[160:163], v199 offset:32768
	ds_read_b128 v[180:183], v199 offset:33792
	ds_read_b128 v[184:187], v199 offset:34816
	ds_read_b128 v[188:191], v199 offset:35840
	ds_read_b128 v[192:195], v199 offset:36864
	ds_read_b128 v[200:203], v199 offset:37888
	ds_read_b128 v[204:207], v199 offset:38912
	ds_read_b128 v[208:211], v199 offset:39936
	global_load_lds_dwordx4 v[220:221], off
	s_mov_b32 m0, s39
	v_lshl_add_u64 v[220:221], s[24:25], 0, v[168:169]
	global_load_lds_dwordx4 v[220:221], off
	s_waitcnt vmcnt(8) lgkmcnt(0)
	s_barrier
	s_setprio 1
	v_mfma_f32_16x16x32_bf16 v[124:127], v[128:131], v[160:163], v[124:127]
	v_mfma_f32_16x16x32_bf16 v[124:127], v[132:135], v[180:183], v[124:127]
	v_mfma_f32_16x16x32_bf16 v[120:123], v[136:139], v[160:163], v[120:123]
	v_mfma_f32_16x16x32_bf16 v[120:123], v[140:143], v[180:183], v[120:123]
	v_mfma_f32_16x16x32_bf16 v[116:119], v[128:131], v[184:187], v[116:119]
	v_mfma_f32_16x16x32_bf16 v[116:119], v[132:135], v[188:191], v[116:119]
	v_mfma_f32_16x16x32_bf16 v[108:111], v[136:139], v[184:187], v[108:111]
	v_mfma_f32_16x16x32_bf16 v[108:111], v[140:143], v[188:191], v[108:111]
	v_mfma_f32_16x16x32_bf16 v[88:91], v[128:131], v[192:195], v[88:91]
	v_mfma_f32_16x16x32_bf16 v[88:91], v[132:135], v[200:203], v[88:91]
	v_mfma_f32_16x16x32_bf16 v[100:103], v[136:139], v[192:195], v[100:103]
	v_mfma_f32_16x16x32_bf16 v[100:103], v[140:143], v[200:203], v[100:103]
	v_mfma_f32_16x16x32_bf16 v[72:75], v[128:131], v[204:207], v[72:75]
	v_mfma_f32_16x16x32_bf16 v[72:75], v[132:135], v[208:211], v[72:75]
	v_mfma_f32_16x16x32_bf16 v[76:79], v[136:139], v[204:207], v[76:79]
	v_mfma_f32_16x16x32_bf16 v[76:79], v[140:143], v[208:211], v[76:79]
	v_mfma_f32_16x16x32_bf16 v[112:115], v[144:147], v[160:163], v[112:115]
	v_mfma_f32_16x16x32_bf16 v[112:115], v[148:151], v[180:183], v[112:115]
	v_mfma_f32_16x16x32_bf16 v[104:107], v[152:155], v[160:163], v[104:107]
	v_mfma_f32_16x16x32_bf16 v[104:107], v[156:159], v[180:183], v[104:107]
	v_mfma_f32_16x16x32_bf16 v[96:99], v[144:147], v[184:187], v[96:99]
	v_mfma_f32_16x16x32_bf16 v[96:99], v[148:151], v[188:191], v[96:99]
	v_mfma_f32_16x16x32_bf16 v[92:95], v[152:155], v[184:187], v[92:95]
	v_mfma_f32_16x16x32_bf16 v[92:95], v[156:159], v[188:191], v[92:95]
	v_mfma_f32_16x16x32_bf16 v[80:83], v[144:147], v[192:195], v[80:83]
	v_mfma_f32_16x16x32_bf16 v[80:83], v[148:151], v[200:203], v[80:83]
	v_mfma_f32_16x16x32_bf16 v[84:87], v[152:155], v[192:195], v[84:87]
	v_mfma_f32_16x16x32_bf16 v[84:87], v[156:159], v[200:203], v[84:87]
	s_setprio 2
	s_barrier
	v_mfma_f32_16x16x32_bf16 v[64:67], v[144:147], v[204:207], v[64:67]
	v_mfma_f32_16x16x32_bf16 v[64:67], v[148:151], v[208:211], v[64:67]
	v_mfma_f32_16x16x32_bf16 v[68:71], v[152:155], v[204:207], v[68:71]
	v_mfma_f32_16x16x32_bf16 v[68:71], v[156:159], v[208:211], v[68:71]
	s_setprio 2
	s_add_i32 s24, s54, s35
	v_lshl_add_u64 v[212:213], v[212:213], 0, s[16:17]
	s_mov_b32 m0, s24
	ds_read_b128 v[160:163], v199 offset:49152
	ds_read_b128 v[180:183], v199 offset:50176
	ds_read_b128 v[184:187], v199 offset:51200
	ds_read_b128 v[188:191], v199 offset:52224
	ds_read_b128 v[192:195], v199 offset:53248
	ds_read_b128 v[200:203], v199 offset:54272
	ds_read_b128 v[204:207], v199 offset:55296
	ds_read_b128 v[208:211], v199 offset:56320
	global_load_lds_dwordx4 v[212:213], off
	s_add_i32 m0, s24, 0x2000
	s_add_u32 s24, s26, 0xb0080
	v_lshl_add_u64 v[212:213], v[214:215], 0, s[16:17]
	s_addc_u32 s25, s27, 0
	s_add_i32 s26, s55, s35
	global_load_lds_dwordx4 v[212:213], off
	s_mov_b32 m0, s26
	v_lshl_add_u64 v[212:213], s[24:25], 0, v[166:167]
	global_load_lds_dwordx4 v[212:213], off
	s_add_i32 m0, s26, 0x2000
	v_lshl_add_u64 v[212:213], s[24:25], 0, v[170:171]
	global_load_lds_dwordx4 v[212:213], off
	s_mov_b32 m0, s41
	v_lshl_add_u64 v[212:213], v[216:217], 0, s[16:17]
	global_load_lds_dwordx4 v[212:213], off
	s_mov_b32 m0, s42
	v_lshl_add_u64 v[212:213], v[218:219], 0, s[16:17]
	global_load_lds_dwordx4 v[212:213], off
	s_waitcnt vmcnt(8) lgkmcnt(0)
	s_barrier
	s_setprio 1
	v_mfma_f32_16x16x32_bf16 v[56:59], v[128:131], v[160:163], v[56:59]
	v_mfma_f32_16x16x32_bf16 v[56:59], v[132:135], v[180:183], v[56:59]
	v_mfma_f32_16x16x32_bf16 v[60:63], v[136:139], v[160:163], v[60:63]
	v_mfma_f32_16x16x32_bf16 v[60:63], v[140:143], v[180:183], v[60:63]
	v_mfma_f32_16x16x32_bf16 v[40:43], v[128:131], v[184:187], v[40:43]
	v_mfma_f32_16x16x32_bf16 v[40:43], v[132:135], v[188:191], v[40:43]
	v_mfma_f32_16x16x32_bf16 v[44:47], v[136:139], v[184:187], v[44:47]
	v_mfma_f32_16x16x32_bf16 v[44:47], v[140:143], v[188:191], v[44:47]
	v_mfma_f32_16x16x32_bf16 v[24:27], v[128:131], v[192:195], v[24:27]
	v_mfma_f32_16x16x32_bf16 v[24:27], v[132:135], v[200:203], v[24:27]
	v_mfma_f32_16x16x32_bf16 v[28:31], v[136:139], v[192:195], v[28:31]
	v_mfma_f32_16x16x32_bf16 v[28:31], v[140:143], v[200:203], v[28:31]
	v_mfma_f32_16x16x32_bf16 v[8:11], v[128:131], v[204:207], v[8:11]
	v_mfma_f32_16x16x32_bf16 v[8:11], v[132:135], v[208:211], v[8:11]
	v_mfma_f32_16x16x32_bf16 v[12:15], v[136:139], v[204:207], v[12:15]
	v_mfma_f32_16x16x32_bf16 v[12:15], v[140:143], v[208:211], v[12:15]
	v_mfma_f32_16x16x32_bf16 v[48:51], v[144:147], v[160:163], v[48:51]
	v_mfma_f32_16x16x32_bf16 v[48:51], v[148:151], v[180:183], v[48:51]
	v_mfma_f32_16x16x32_bf16 v[52:55], v[152:155], v[160:163], v[52:55]
	v_mfma_f32_16x16x32_bf16 v[52:55], v[156:159], v[180:183], v[52:55]
	v_mfma_f32_16x16x32_bf16 v[32:35], v[144:147], v[184:187], v[32:35]
	v_mfma_f32_16x16x32_bf16 v[32:35], v[148:151], v[188:191], v[32:35]
	v_mfma_f32_16x16x32_bf16 v[36:39], v[152:155], v[184:187], v[36:39]
	v_mfma_f32_16x16x32_bf16 v[36:39], v[156:159], v[188:191], v[36:39]
	v_mfma_f32_16x16x32_bf16 v[16:19], v[144:147], v[192:195], v[16:19]
	v_mfma_f32_16x16x32_bf16 v[16:19], v[148:151], v[200:203], v[16:19]
	v_mfma_f32_16x16x32_bf16 v[20:23], v[152:155], v[192:195], v[20:23]
	v_mfma_f32_16x16x32_bf16 v[20:23], v[156:159], v[200:203], v[20:23]
	s_setprio 2
	s_barrier
	v_mfma_f32_16x16x32_bf16 v[0:3], v[144:147], v[204:207], v[0:3]
	v_mfma_f32_16x16x32_bf16 v[0:3], v[148:151], v[208:211], v[0:3]
	v_mfma_f32_16x16x32_bf16 v[4:7], v[152:155], v[204:207], v[4:7]
	v_mfma_f32_16x16x32_bf16 v[4:7], v[156:159], v[208:211], v[4:7]
	s_setprio 0
	s_add_i32 s53, s53, 2
	s_add_u32 s51, s51, 0x100
	s_addc_u32 s52, s52, 0
	s_cmp_gt_u32 s53, 41
	s_mov_b64 s[24:25], s[4:5]
	s_cbranch_scc0 .LBB0_1310
